# group barriers (blockIdx%8 slices) at 3 seams, fewer redundant invalidates, nt hint on prologue weight streams
# speedup vs baseline: 1.0195x; 1.0195x over previous
; #define LAS __attribute__((address_space(3)))
; __device__ __forceinline__ int opaque_tid(int wv) { unsigned z = 0u; asm volatile("" : "+v"(z)); return (wv << 6) | (int)__builtin_amdgcn_mbcnt_hi(~0u, __builtin_amdgcn_mbcnt_lo(~0u, z)); }
; __device__ __forceinline__ unsigned xb_add(unsigned* p, unsigned v) { return __hip_atomic_fetch_add(p, v, __ATOMIC_RELAXED, __HIP_MEMORY_SCOPE_AGENT); }
; __device__ __forceinline__ unsigned xb_xcc_id() { return (unsigned)__builtin_amdgcn_s_getreg((3 << 11) | 20) & 0xFu; }
; __global__ void __launch_bounds__(512) fwd_megakernel(Args A) {
;     ...
;     const int G = gridDim.x, bx = blockIdx.x;
;     const int wv = __builtin_amdgcn_readfirstlane((int)threadIdx.x >> 6);
;     unsigned char* ws = A.ws;
;     const int lo = A.ph_lo, hi = A.ph_hi;
;     ...
;     cg::grid_group grid = cg::this_grid();
;     unsigned* xbar = (unsigned*)(ws + WS_CTL) + 1024;
;     volatile LAS unsigned* xst = (volatile LAS unsigned*)(lds + MISC_OFF + 64);
;     { const int t0_ = opaque_tid(wv); if (t0_ == 0) { xst[0] = 0u; xst[1] = 0u; (void)xb_add(&xbar[XB_XCNT(xb_xcc_id())], 1u); } }
;     ...
;     if (EN(0) && IN(0)) {
;         prologue_phase(A, lds, G, wv);
.LBB0_3:
	s_or_b64 exec, exec, s[2:3]
	s_cmp_lg_u32 s94, 0
	s_cbranch_scc1 .Lxm_skip
	s_mov_b64 s[2:3], exec
	s_mov_b64 exec, 1
	s_getreg_b32 s4, hwreg(HW_REG_XCC_ID, 0, 4)
	s_and_b32 s4, s4, 15
	s_lshl_b32 s5, 1, s4
	s_and_b32 s6, s86, 7
	s_lshl_b32 s6, s6, 8
	s_add_u32 s6, s6, 0x6000
	s_add_u32 s8, s60, s6
	s_addc_u32 s9, s61, 0
	v_mov_b32_e32 v2, s5
	v_mov_b32_e32 v3, 0
	global_atomic_or v3, v2, s[8:9]
	s_mov_b64 exec, s[2:3]
.Lxm_skip:
	s_load_dwordx16 s[4:19], s[0:1], 0x40
	s_add_u32 s0, s60, 0x200000
	s_addc_u32 s1, s61, 0
	s_cmp_lt_i32 s62, 1
	s_waitcnt lgkmcnt(0)
	v_writelane_b32 v251, s4, 5
	s_nop 1
	v_writelane_b32 v251, s5, 6
	v_writelane_b32 v251, s6, 7
	v_writelane_b32 v251, s7, 8
	v_writelane_b32 v251, s8, 9
	v_writelane_b32 v251, s9, 10
	v_writelane_b32 v251, s10, 11
	v_writelane_b32 v251, s11, 12
	v_writelane_b32 v251, s12, 13
	v_writelane_b32 v251, s13, 14
	v_writelane_b32 v251, s14, 15
	v_writelane_b32 v251, s15, 16
	v_writelane_b32 v251, s16, 17
	v_writelane_b32 v251, s17, 18
	v_writelane_b32 v251, s18, 19
	v_writelane_b32 v251, s19, 20
	v_writelane_b32 v251, s0, 21
	s_nop 1
	v_writelane_b32 v251, s1, 22
	s_cselect_b64 s[0:1], -1, 0
	s_cmp_gt_i32 s63, 0
	s_cselect_b64 s[2:3], -1, 0
	s_and_b64 s[0:1], s[0:1], s[2:3]
	s_andn2_b64 vcc, exec, s[0:1]
	s_mov_b32 s1, 0
	v_writelane_b32 v251, s0, 23
	s_nop 1
	v_writelane_b32 v251, s1, 24
	v_writelane_b32 v251, s40, 25
	s_nop 1
	v_writelane_b32 v251, s41, 26
	v_writelane_b32 v251, s42, 27
	v_writelane_b32 v251, s43, 28
	v_writelane_b32 v251, s44, 29
	v_writelane_b32 v251, s45, 30
	v_writelane_b32 v251, s46, 31
	v_writelane_b32 v251, s47, 32
	v_writelane_b32 v251, s48, 33
	v_writelane_b32 v251, s49, 34
	v_writelane_b32 v251, s50, 35
	v_writelane_b32 v251, s51, 36
	v_writelane_b32 v251, s52, 37
	v_writelane_b32 v251, s53, 38
	v_writelane_b32 v251, s54, 39
	v_writelane_b32 v251, s55, 40
	v_writelane_b32 v251, s56, 41
	s_nop 1
	v_writelane_b32 v251, s57, 42
	v_writelane_b32 v251, s58, 43
	v_writelane_b32 v251, s59, 44
	v_writelane_b32 v251, s60, 45
	v_writelane_b32 v251, s61, 46
	v_writelane_b32 v251, s62, 47
	v_writelane_b32 v251, s63, 48
	v_writelane_b32 v251, s94, 49
	s_cbranch_vccnz .LBB0_182
	v_mov_b32_e32 v2, 0
	s_movk_i32 s0, 0x2000
	v_mbcnt_lo_u32_b32 v2, -1, v2
	v_mbcnt_hi_u32_b32 v17, -1, v2
	v_or_b32_e32 v2, s94, v17
	v_ashrrev_i32_e32 v18, 6, v2
	v_cmp_gt_i32_e32 vcc, s0, v2
	v_readfirstlane_b32 s23, v18
	s_and_saveexec_b64 s[2:3], vcc
	s_cbranch_execz .LBB0_16
	v_max_i32_e32 v3, 0x1e00, v2
	v_sub_u32_e32 v3, v3, v2
	s_movk_i32 s0, 0x1ff
	v_add_u32_e32 v3, 0x1ff, v3
	v_cmp_lt_u32_e32 vcc, s0, v3
	s_mov_b64 s[0:1], -1
	v_mov_b32_e32 v4, v2
	s_and_saveexec_b64 s[8:9], vcc
	s_cbranch_execz .LBB0_13
	v_lshrrev_b32_e32 v6, 9, v3
	v_add_u32_e32 v3, 0x200, v2
	v_add_u32_e32 v7, -1, v6
	v_cmp_lt_u32_e32 vcc, 1, v7
	v_mov_b64_e32 v[4:5], v[2:3]
	s_and_saveexec_b64 s[10:11], vcc
	s_cbranch_execz .LBB0_10
	v_lshrrev_b32_e32 v4, 1, v7
	v_add_u32_e32 v4, 1, v4
	v_and_b32_e32 v8, -2, v4
	s_mov_b64 s[12:13], 0
	s_mov_b32 s14, 0xbfb8aa3b
	s_mov_b32 s15, 0x42ce8ed0
	s_mov_b32 s16, 0xc2b17218
	v_mov_b32_e32 v9, 0x7f800000
	s_add_i32 s17, 0, 0x11000
	v_mov_b64_e32 v[4:5], v[2:3]

; #define LAS __attribute__((address_space(3)))
; __device__ __forceinline__ void prologue_phase(const Args& A, LAS unsigned char* lds, int G, const int wv) {
;     ...
;     for (int t = blockIdx.x; t < 384; t += G) {
;         const int l = t / 192, n0 = (t % 192) * 64;
;         const float* Wp = A.w_ada + (size_t)l * DM * ADAW + (size_t)(256 * wave) * ADAW + n0 + lane;
;         float a0 = 0.f, a1 = 0.f, a2 = 0.f, a3 = 0.f;
; #pragma unroll 16
;         for (int k = 0; k < 256; ++k) { const float wv = Wp[(size_t)k * ADAW]; const f32x4 ca = *(const LAS f32x4*)(cact + (256 * wave + k) * 4); a0 += ca[0] * wv; a1 += ca[1] * wv; a2 += ca[2] * wv; a3 += ca[3] * wv; }
;         red[(wave * 4 + 0) * 64 + lane] = a0; red[(wave * 4 + 1) * 64 + lane] = a1; red[(wave * 4 + 2) * 64 + lane] = a2; red[(wave * 4 + 3) * 64 + lane] = a3;
.LBB0_20:
	v_add_co_u32_e64 v22, s[6:7], s10, v10
	v_add_co_u32_e32 v20, vcc, 0xfffa0000, v10
	s_nop 0
	v_addc_co_u32_e64 v23, s[6:7], 0, v11, s[6:7]
	v_add_co_u32_e64 v24, s[6:7], s13, v10
	v_addc_co_u32_e32 v21, vcc, -1, v11, vcc
	s_nop 0
	v_addc_co_u32_e64 v25, s[6:7], 0, v11, s[6:7]
	v_add_co_u32_e32 v36, vcc, 0xfffac000, v10
	v_add_co_u32_e64 v26, s[6:7], s14, v10
	s_nop 0
	v_addc_co_u32_e32 v37, vcc, -1, v11, vcc
	global_load_dword v16, v[10:11], off nt
	v_addc_co_u32_e64 v27, s[6:7], 0, v11, s[6:7]
	global_load_dword v84, v[22:23], off nt
	global_load_dword v86, v[24:25], off nt
	global_load_dword v88, v[26:27], off nt
	global_load_dword v90, v[20:21], off nt
	v_add_co_u32_e32 v20, vcc, 0xfffb8000, v10
	global_load_dword v92, v[36:37], off nt
	s_nop 0
	v_addc_co_u32_e32 v21, vcc, -1, v11, vcc
	v_add_co_u32_e32 v22, vcc, 0xfffc4000, v10
	global_load_dword v94, v[20:21], off nt
	s_nop 0
	v_addc_co_u32_e32 v23, vcc, -1, v11, vcc
	global_load_dword v96, v[22:23], off nt
	v_add_co_u32_e32 v20, vcc, 0xfffd0000, v10
	v_add_co_u32_e64 v28, s[6:7], s15, v10
	s_nop 0
	v_addc_co_u32_e32 v21, vcc, -1, v11, vcc
	v_add_co_u32_e32 v22, vcc, 0xfffdc000, v10
	global_load_dword v98, v[20:21], off nt
	s_nop 0
	v_addc_co_u32_e32 v23, vcc, -1, v11, vcc
	global_load_dword v100, v[22:23], off nt
	v_add_co_u32_e32 v20, vcc, 0xfffe8000, v10
	v_addc_co_u32_e64 v29, s[6:7], 0, v11, s[6:7]
	s_nop 0
	v_addc_co_u32_e32 v21, vcc, -1, v11, vcc
	global_load_dword v102, v[20:21], off nt
	v_add_co_u32_e64 v30, s[6:7], s16, v10
	v_add_co_u32_e32 v22, vcc, 0xffff4000, v10
	s_nop 0
	v_addc_co_u32_e64 v31, s[6:7], 0, v11, s[6:7]
	v_add_co_u32_e64 v32, s[6:7], s17, v10
	v_addc_co_u32_e32 v23, vcc, -1, v11, vcc
	s_nop 0
	v_addc_co_u32_e64 v33, s[6:7], 0, v11, s[6:7]
	global_load_dword v104, v[22:23], off nt
	global_load_dword v106, v[28:29], off nt
	global_load_dword v108, v[30:31], off nt
	global_load_dword v110, v[32:33], off nt
	v_add_co_u32_e64 v34, s[6:7], s18, v10
	s_add_i32 s24, s12, s21
	s_nop 0
	v_addc_co_u32_e64 v35, s[6:7], 0, v11, s[6:7]
	global_load_dword v112, v[34:35], off nt
	s_add_i32 s6, s24, 0x12000
	s_add_i32 s7, s24, 0x12010
	s_add_i32 s25, s24, 0x12020
	s_add_i32 s26, s24, 0x12030
	s_add_i32 s27, s24, 0x12040
	s_add_i32 s28, s24, 0x12050
	s_add_i32 s29, s24, 0x12060
	s_add_i32 s30, s24, 0x12070
	s_add_i32 s31, s24, 0x12080
	s_add_i32 s33, s24, 0x12090
	s_add_i32 s34, s24, 0x120a0
	s_add_i32 s35, s24, 0x120b0
	s_add_i32 s36, s24, 0x120c0
	s_add_i32 s37, s24, 0x120d0
	s_add_i32 s38, s24, 0x120e0
	s_add_i32 s24, s24, 0x120f0
	v_mov_b32_e32 v19, s6
	v_mov_b32_e32 v24, s7
	v_mov_b32_e32 v28, s25
	v_mov_b32_e32 v32, s26
	v_mov_b32_e32 v36, s27
	v_mov_b32_e32 v40, s28
	v_mov_b32_e32 v44, s29
	v_mov_b32_e32 v48, s30
	v_mov_b32_e32 v52, s31
	v_mov_b32_e32 v56, s33
	v_mov_b32_e32 v60, s34
	v_mov_b32_e32 v64, s35
	v_mov_b32_e32 v68, s36
	v_mov_b32_e32 v72, s37
	v_mov_b32_e32 v76, s38
	v_mov_b32_e32 v80, s24
	ds_read_b128 v[20:23], v19
	ds_read_b128 v[24:27], v24
	ds_read_b128 v[28:31], v28
	ds_read_b128 v[32:35], v32
	ds_read_b128 v[36:39], v36
	ds_read_b128 v[40:43], v40
	ds_read_b128 v[44:47], v44
	ds_read_b128 v[48:51], v48
	ds_read_b128 v[52:55], v52
	ds_read_b128 v[56:59], v56
	ds_read_b128 v[60:63], v60
	ds_read_b128 v[64:67], v64
	ds_read_b128 v[68:71], v68
	ds_read_b128 v[72:75], v72
	ds_read_b128 v[76:79], v76
	ds_read_b128 v[80:83], v80
	s_waitcnt vmcnt(11) lgkmcnt(14)
	v_pk_fma_f32 v[12:13], v[90:91], v[20:21], v[12:13] op_sel_hi:[0,1,1]
	v_pk_fma_f32 v[14:15], v[90:91], v[22:23], v[14:15] op_sel_hi:[0,1,1]
	s_waitcnt vmcnt(10)
	v_pk_fma_f32 v[12:13], v[92:93], v[24:25], v[12:13] op_sel_hi:[0,1,1]
	v_pk_fma_f32 v[14:15], v[92:93], v[26:27], v[14:15] op_sel_hi:[0,1,1]
	s_addk_i32 s21, 0x100
	s_waitcnt vmcnt(9) lgkmcnt(13)
	v_pk_fma_f32 v[12:13], v[94:95], v[28:29], v[12:13] op_sel_hi:[0,1,1]
	v_pk_fma_f32 v[14:15], v[94:95], v[30:31], v[14:15] op_sel_hi:[0,1,1]
	s_cmp_eq_u32 s21, 0
	s_waitcnt vmcnt(8) lgkmcnt(12)
	v_pk_fma_f32 v[12:13], v[96:97], v[32:33], v[12:13] op_sel_hi:[0,1,1]
	v_pk_fma_f32 v[14:15], v[96:97], v[34:35], v[14:15] op_sel_hi:[0,1,1]
	v_lshl_add_u64 v[10:11], v[10:11], 0, s[2:3]
	s_waitcnt vmcnt(7) lgkmcnt(11)
	v_pk_fma_f32 v[12:13], v[98:99], v[36:37], v[12:13] op_sel_hi:[0,1,1]
	v_pk_fma_f32 v[14:15], v[98:99], v[38:39], v[14:15] op_sel_hi:[0,1,1]
	s_waitcnt vmcnt(6) lgkmcnt(10)
	v_pk_fma_f32 v[12:13], v[100:101], v[40:41], v[12:13] op_sel_hi:[0,1,1]
	v_pk_fma_f32 v[14:15], v[100:101], v[42:43], v[14:15] op_sel_hi:[0,1,1]
	s_waitcnt vmcnt(5) lgkmcnt(9)
	v_pk_fma_f32 v[12:13], v[102:103], v[44:45], v[12:13] op_sel_hi:[0,1,1]
	v_pk_fma_f32 v[14:15], v[102:103], v[46:47], v[14:15] op_sel_hi:[0,1,1]
	s_waitcnt vmcnt(4) lgkmcnt(8)
	v_pk_fma_f32 v[12:13], v[104:105], v[48:49], v[12:13] op_sel_hi:[0,1,1]
	v_pk_fma_f32 v[14:15], v[104:105], v[50:51], v[14:15] op_sel_hi:[0,1,1]
	s_waitcnt lgkmcnt(7)
	v_pk_fma_f32 v[12:13], v[16:17], v[52:53], v[12:13] op_sel_hi:[0,1,1]
	v_pk_fma_f32 v[14:15], v[16:17], v[54:55], v[14:15] op_sel_hi:[0,1,1]
	s_waitcnt lgkmcnt(6)
	v_pk_fma_f32 v[12:13], v[84:85], v[56:57], v[12:13] op_sel_hi:[0,1,1]
	v_pk_fma_f32 v[14:15], v[84:85], v[58:59], v[14:15] op_sel_hi:[0,1,1]
	s_waitcnt lgkmcnt(5)
	v_pk_fma_f32 v[12:13], v[86:87], v[60:61], v[12:13] op_sel_hi:[0,1,1]
	v_pk_fma_f32 v[14:15], v[86:87], v[62:63], v[14:15] op_sel_hi:[0,1,1]
	s_waitcnt lgkmcnt(4)
	v_pk_fma_f32 v[12:13], v[88:89], v[64:65], v[12:13] op_sel_hi:[0,1,1]
	v_pk_fma_f32 v[14:15], v[88:89], v[66:67], v[14:15] op_sel_hi:[0,1,1]
	s_waitcnt vmcnt(3) lgkmcnt(3)
	v_pk_fma_f32 v[12:13], v[106:107], v[68:69], v[12:13] op_sel_hi:[0,1,1]
	v_pk_fma_f32 v[14:15], v[106:107], v[70:71], v[14:15] op_sel_hi:[0,1,1]
	s_waitcnt vmcnt(2) lgkmcnt(2)
	v_pk_fma_f32 v[12:13], v[108:109], v[72:73], v[12:13] op_sel_hi:[0,1,1]
	v_pk_fma_f32 v[14:15], v[108:109], v[74:75], v[14:15] op_sel_hi:[0,1,1]
	s_waitcnt vmcnt(1) lgkmcnt(1)
	v_pk_fma_f32 v[12:13], v[110:111], v[76:77], v[12:13] op_sel_hi:[0,1,1]
	v_pk_fma_f32 v[14:15], v[110:111], v[78:79], v[14:15] op_sel_hi:[0,1,1]
	s_waitcnt vmcnt(0) lgkmcnt(0)
	v_pk_fma_f32 v[12:13], v[112:113], v[80:81], v[12:13] op_sel_hi:[0,1,1]
	v_pk_fma_f32 v[14:15], v[112:113], v[82:83], v[14:15] op_sel_hi:[0,1,1]
	s_cbranch_scc0 .LBB0_20
; __device__ __forceinline__ void prologue_phase(const Args& A, LAS unsigned char* lds, int G, const int wv) {
;     ...
;         red[(wave * 4 + 0) * 64 + lane] = a0; red[(wave * 4 + 1) * 64 + lane] = a1; red[(wave * 4 + 2) * 64 + lane] = a2; red[(wave * 4 + 3) * 64 + lane] = a3;
;         __syncthreads();
;         if (tid < 256) { const int bb = tid >> 6; float s = 0.f;
; #pragma unroll
;             for (int w = 0; w < 8; ++w) s += red[(w * 4 + bb) * 64 + lane];
;             mod[(size_t)(l * 4 + bb) * ADAW + n0 + lane] = s + A.b_ada[l * ADAW + n0 + lane]; }
	v_add_u32_e32 v10, s11, v3
	ds_write2st64_b32 v10, v12, v13 offset1:1
	ds_write2st64_b32 v10, v14, v15 offset0:2 offset1:3
	s_waitcnt lgkmcnt(0)
	s_barrier
	s_and_saveexec_b64 s[6:7], s[0:1]
	s_cbranch_execz .LBB0_23
	s_mul_i32 s21, s20, 0x3000
	s_add_i32 s21, s21, s8
	v_or_b32_e32 v10, s21, v4
	v_ashrrev_i32_e32 v11, 31, v10
	v_lshl_add_u64 v[10:11], v[10:11], 2, s[46:47]
	global_load_dword v16, v[10:11], off nt
	ds_read2st64_b32 v[10:11], v5 offset1:4
	ds_read2st64_b32 v[12:13], v5 offset0:8 offset1:12
	ds_read2st64_b32 v[14:15], v5 offset0:16 offset1:20
	ds_read2st64_b32 v[20:21], v5 offset0:24 offset1:28
	v_lshl_add_u32 v19, s20, 2, v18
	s_waitcnt lgkmcnt(3)
	v_add_f32_e32 v10, 0, v10
	v_add_f32_e32 v10, v10, v11
	s_waitcnt lgkmcnt(2)
	v_add_f32_e32 v10, v10, v12
	v_readlane_b32 s20, v251, 21
	v_add_f32_e32 v10, v10, v13
	v_readlane_b32 s21, v251, 22
	s_waitcnt lgkmcnt(1)
	v_add_f32_e32 v10, v10, v14
	v_add_f32_e32 v10, v10, v15
	v_mov_b64_e32 v[22:23], s[20:21]
	v_mad_i64_i32 v[22:23], s[20:21], v19, s10, v[22:23]
	s_waitcnt lgkmcnt(0)
	v_add_f32_e32 v10, v10, v20
	v_lshl_add_u64 v[22:23], s[8:9], 2, v[22:23]
	v_add_f32_e32 v10, v10, v21
	s_waitcnt vmcnt(0)
	v_add_f32_e32 v12, v10, v16
	v_lshl_add_u64 v[10:11], v[22:23], 0, v[6:7]
	global_store_dword v[10:11], v12, off

; #define LAS __attribute__((address_space(3)))
; __device__ __forceinline__ void transpose_item(const float* __restrict__ W, int K, int N, bf16_t* __restrict__ WT, int id, const float* __restrict__ gk, LAS float* scr, int item, int nblk, int lane) {
;     const int kb = item / nblk, nb = item % nblk, k0 = 64 * kb, n0 = 32 * nb;
;     const int sc = srccol(id, n0 + (lane & 31));
;     const float* src = W + (size_t)(k0 + (lane >> 5)) * N + (sc < 0 ? 0 : sc);
;     float v[32];
; #pragma unroll
;     for (int i = 0; i < 32; ++i) v[i] = src[(size_t)(2 * i) * N];
; __device__ __forceinline__ void prologue_phase(const Args& A, LAS unsigned char* lds, int G, const int wv) {
;     ...
;         const int l = it / PER_L; int r = it % PER_L;
;     ...
;         if (r < I_KVK) { transpose_item(A.w_ukv + (size_t)l * 256 * 2048, 256, 2048, (bf16_t*)(ws + WS_WUKVK) + (size_t)l * 1024 * 256, 3, A.kv_norm + l * 256, scr, r, 32, lane); continue; } r -= I_KVK;
;         transpose_item(A.w_ukv + (size_t)l * 256 * 2048, 256, 2048, (bf16_t*)(ws + WS_WUKVV) + (size_t)l * 1024 * 256, 4, A.kv_norm + l * 256, scr, r, 32, lane);
.LBB0_40:
	s_mul_hi_i32 s0, s14, 0x2d4279a3
	s_lshr_b32 s1, s0, 31
	s_ashr_i32 s0, s0, 12
	s_add_i32 s10, s0, s1
	s_mul_i32 s0, s10, 0xffffa580
	s_add_i32 s17, s14, s0
	s_cmpk_gt_i32 s17, 0x1fff
	s_mov_b64 s[0:1], -1
	s_cbranch_scc0 .LBB0_95
	s_cmpk_gt_u32 s17, 0x3fff
	s_cbranch_scc0 .LBB0_92
	s_cmpk_gt_u32 s17, 0x4bff
	s_cbranch_scc0 .LBB0_67
	s_cmpk_gt_u32 s17, 0x53ff
	s_cbranch_scc0 .LBB0_64
	s_cmpk_gt_u32 s17, 0x57ff
	s_cbranch_scc0 .LBB0_61
	s_cmpk_gt_u32 s17, 0x597f
	s_cbranch_scc0 .LBB0_54
	s_ashr_i32 s11, s10, 31
	v_readlane_b32 s72, v251, 5
	s_lshl_b64 s[0:1], s[10:11], 21
	v_readlane_b32 s74, v251, 7
	v_readlane_b32 s75, v251, 8
	s_add_u32 s6, s74, s0
	s_addc_u32 s7, s75, s1
	s_lshl_b64 s[4:5], s[10:11], 19
	s_cmpk_gt_u32 s17, 0x59ff
	s_mov_b64 s[12:13], -1
	v_cmp_ne_u32_e64 s[0:1], 1, v46
	v_readlane_b32 s73, v251, 6
	v_readlane_b32 s76, v251, 9
	v_readlane_b32 s77, v251, 10
	v_readlane_b32 s78, v251, 11
	v_readlane_b32 s79, v251, 12
	v_readlane_b32 s80, v251, 13
	v_readlane_b32 s81, v251, 14
	v_readlane_b32 s82, v251, 15
	v_readlane_b32 s83, v251, 16
	v_readlane_b32 s84, v251, 17
	v_readlane_b32 s85, v251, 18
	v_readlane_b32 s86, v251, 19
	v_readlane_b32 s87, v251, 20
	s_cbranch_scc0 .LBB0_50
	s_lshl_b32 s12, s10, 8
	s_mov_b32 s91, s25
	s_mov_b32 s25, s24
	s_mov_b32 s24, s8
	s_mov_b32 s8, s23
	s_mov_b32 s23, s21
	s_mov_b32 s21, s18
	s_sub_i32 s11, s35, s12
	s_lshl_b32 s18, s17, 5
	s_lshl_b32 s13, s17, 6
	s_and_b32 s11, s11, 0x1c0
	s_and_b32 s13, s13, 0x700
	s_and_b32 vcc_lo, s18, 0x60
	s_or_b32 s13, vcc_lo, s13
	v_or_b32_e32 v48, s11, v3
	v_or_b32_e32 v8, s13, v38
	v_lshlrev_b32_e32 v4, 13, v48
	v_lshl_add_u64 v[6:7], s[6:7], 0, v[4:5]
	v_lshlrev_b32_e32 v4, 2, v8
	v_lshl_add_u64 v[30:31], v[6:7], 0, v[4:5]
	v_add_co_u32_e32 v8, vcc, s39, v30
	s_nop 1
	v_addc_co_u32_e32 v9, vcc, 0, v31, vcc
	v_add_co_u32_e32 v10, vcc, s40, v30
	s_nop 1
	v_addc_co_u32_e32 v11, vcc, 0, v31, vcc
	v_add_co_u32_e32 v12, vcc, s41, v30
	s_nop 1
	v_addc_co_u32_e32 v13, vcc, 0, v31, vcc
	v_add_co_u32_e32 v14, vcc, s42, v30
	s_nop 1
	v_addc_co_u32_e32 v15, vcc, 0, v31, vcc
	v_add_co_u32_e32 v16, vcc, s43, v30
	s_nop 1
	v_addc_co_u32_e32 v17, vcc, 0, v31, vcc
	v_add_co_u32_e32 v18, vcc, s44, v30
	s_nop 1
	v_addc_co_u32_e32 v19, vcc, 0, v31, vcc
	v_add_co_u32_e32 v20, vcc, s45, v30
	s_nop 1
	v_addc_co_u32_e32 v21, vcc, 0, v31, vcc
	global_load_dword v6, v[30:31], off offset:512 nt
	global_load_dword v7, v[8:9], off offset:512 nt
	s_nop 0
	global_load_dword v10, v[10:11], off offset:512 nt
	s_nop 0
	global_load_dword v11, v[12:13], off offset:512 nt
	global_load_dword v8, v[14:15], off offset:512 nt
	global_load_dword v9, v[16:17], off offset:512 nt
	s_nop 0
	global_load_dword v12, v[18:19], off offset:512 nt
	global_load_dword v13, v[20:21], off offset:512 nt
	v_add_co_u32_e32 v14, vcc, s46, v30
	s_nop 1
	v_addc_co_u32_e32 v15, vcc, 0, v31, vcc
	v_add_co_u32_e32 v16, vcc, s47, v30
	s_nop 1
	v_addc_co_u32_e32 v17, vcc, 0, v31, vcc
	v_add_co_u32_e32 v18, vcc, s48, v30
	s_nop 1
	v_addc_co_u32_e32 v19, vcc, 0, v31, vcc
	v_add_co_u32_e32 v20, vcc, s49, v30
	s_nop 1
	v_addc_co_u32_e32 v21, vcc, 0, v31, vcc
	v_add_co_u32_e32 v22, vcc, s50, v30
	s_nop 1
	v_addc_co_u32_e32 v23, vcc, 0, v31, vcc
	v_add_co_u32_e32 v24, vcc, s51, v30
	s_nop 1
	v_addc_co_u32_e32 v25, vcc, 0, v31, vcc
	v_add_co_u32_e32 v26, vcc, s52, v30
	s_nop 1
	v_addc_co_u32_e32 v27, vcc, 0, v31, vcc
	v_add_co_u32_e32 v28, vcc, s53, v30
	s_nop 1
	v_addc_co_u32_e32 v29, vcc, 0, v31, vcc
	global_load_dword v14, v[14:15], off offset:512 nt
	s_nop 0
	global_load_dword v15, v[16:17], off offset:512 nt
	s_nop 0
	global_load_dword v18, v[18:19], off offset:512 nt
	s_nop 0
	global_load_dword v19, v[20:21], off offset:512 nt
	global_load_dword v16, v[22:23], off offset:512 nt
	global_load_dword v17, v[24:25], off offset:512 nt
	s_nop 0
	global_load_dword v20, v[26:27], off offset:512 nt
	global_load_dword v21, v[28:29], off offset:512 nt
	v_add_co_u32_e32 v22, vcc, s54, v30
	s_nop 1
	v_addc_co_u32_e32 v23, vcc, 0, v31, vcc
	v_add_co_u32_e32 v24, vcc, s55, v30
	s_nop 1
	v_addc_co_u32_e32 v25, vcc, 0, v31, vcc
	v_add_co_u32_e32 v26, vcc, s56, v30
	s_nop 1
	v_addc_co_u32_e32 v27, vcc, 0, v31, vcc
	v_add_co_u32_e32 v28, vcc, s57, v30
	s_nop 1
	v_addc_co_u32_e32 v29, vcc, 0, v31, vcc
	v_add_co_u32_e32 v32, vcc, s58, v30
	s_nop 1
	v_addc_co_u32_e32 v33, vcc, 0, v31, vcc
	v_add_co_u32_e32 v34, vcc, s59, v30
	s_nop 1
	v_addc_co_u32_e32 v35, vcc, 0, v31, vcc
	v_add_co_u32_e32 v36, vcc, s60, v30
	s_nop 1
	v_addc_co_u32_e32 v37, vcc, 0, v31, vcc
	v_add_co_u32_e32 v50, vcc, s61, v30
	s_nop 1
	v_addc_co_u32_e32 v51, vcc, 0, v31, vcc
	global_load_dword v22, v[22:23], off offset:512 nt
	s_nop 0
	global_load_dword v23, v[24:25], off offset:512 nt
	s_nop 0
	global_load_dword v26, v[26:27], off offset:512 nt
	s_nop 0
	global_load_dword v27, v[28:29], off offset:512 nt
	global_load_dword v24, v[32:33], off offset:512 nt
	global_load_dword v25, v[34:35], off offset:512 nt
	s_nop 0
	global_load_dword v28, v[36:37], off offset:512 nt
	global_load_dword v29, v[50:51], off offset:512 nt
	v_add_co_u32_e32 v32, vcc, s62, v30
	s_nop 1
	v_addc_co_u32_e32 v33, vcc, 0, v31, vcc
	v_add_co_u32_e32 v34, vcc, s63, v30
	s_nop 1
	v_addc_co_u32_e32 v35, vcc, 0, v31, vcc
	v_add_co_u32_e32 v36, vcc, s64, v30
	s_nop 1
	v_addc_co_u32_e32 v37, vcc, 0, v31, vcc
	v_add_co_u32_e32 v50, vcc, s65, v30
	s_nop 1
	v_addc_co_u32_e32 v51, vcc, 0, v31, vcc
	v_add_co_u32_e32 v52, vcc, s66, v30
	s_nop 1
	v_addc_co_u32_e32 v53, vcc, 0, v31, vcc
	v_add_co_u32_e32 v54, vcc, 0x74000, v30
	s_nop 1
	v_addc_co_u32_e32 v55, vcc, 0, v31, vcc
	v_add_co_u32_e32 v56, vcc, 0x78000, v30
	s_nop 1
	v_addc_co_u32_e32 v57, vcc, 0, v31, vcc
	v_add_co_u32_e32 v58, vcc, 0x7c000, v30
	s_nop 1
	v_addc_co_u32_e32 v59, vcc, 0, v31, vcc
	global_load_dword v30, v[32:33], off offset:512 nt
	global_load_dword v31, v[34:35], off offset:512 nt
	s_nop 0
	global_load_dword v36, v[36:37], off offset:512 nt
	s_nop 0
	global_load_dword v37, v[50:51], off offset:512 nt
	global_load_dword v34, v[52:53], off offset:512 nt
	global_load_dword v35, v[54:55], off offset:512 nt
	global_load_dword v32, v[56:57], off offset:512 nt
	global_load_dword v33, v[58:59], off offset:512 nt
	s_and_b64 vcc, exec, s[0:1]
	s_cbranch_vccnz .LBB0_49
; __device__ __forceinline__ void transpose_item(const float* __restrict__ W, int K, int N, bf16_t* __restrict__ WT, int id, const float* __restrict__ gk, LAS float* scr, int item, int nblk, int lane) {
;     ...
;     if (gk) {
; #pragma unroll
;         for (int i = 0; i < 32; ++i) v[i] *= gk[k0 + 2 * i + (lane >> 5)];
;     }
	s_ashr_i32 s13, s12, 31
	s_lshl_b64 s[12:13], s[12:13], 2
	v_readlane_b32 s72, v251, 5
	v_readlane_b32 s73, v251, 6
	s_add_u32 s12, s72, s12
	s_addc_u32 s13, s73, s13
	v_lshlrev_b32_e32 v4, 2, v48
	global_load_dword v48, v4, s[12:13] nt
	global_load_dword v49, v4, s[12:13] offset:8 nt
	global_load_dword v50, v4, s[12:13] offset:16 nt
	global_load_dword v51, v4, s[12:13] offset:24 nt
	global_load_dword v52, v4, s[12:13] offset:32 nt
	global_load_dword v53, v4, s[12:13] offset:40 nt
	global_load_dword v54, v4, s[12:13] offset:48 nt
	global_load_dword v55, v4, s[12:13] offset:56 nt
	global_load_dword v56, v4, s[12:13] offset:64 nt
	global_load_dword v57, v4, s[12:13] offset:72 nt
	global_load_dword v58, v4, s[12:13] offset:80 nt
	global_load_dword v59, v4, s[12:13] offset:88 nt
	global_load_dword v60, v4, s[12:13] offset:96 nt
	global_load_dword v61, v4, s[12:13] offset:104 nt
	global_load_dword v62, v4, s[12:13] offset:112 nt
	global_load_dword v63, v4, s[12:13] offset:120 nt
	global_load_dword v64, v4, s[12:13] offset:128 nt
	global_load_dword v65, v4, s[12:13] offset:136 nt
	global_load_dword v66, v4, s[12:13] offset:144 nt
	global_load_dword v67, v4, s[12:13] offset:152 nt
	global_load_dword v68, v4, s[12:13] offset:160 nt
	global_load_dword v69, v4, s[12:13] offset:168 nt
	global_load_dword v70, v4, s[12:13] offset:176 nt
	global_load_dword v71, v4, s[12:13] offset:184 nt
	global_load_dword v72, v4, s[12:13] offset:192 nt
	global_load_dword v73, v4, s[12:13] offset:200 nt
	global_load_dword v74, v4, s[12:13] offset:208 nt
	global_load_dword v75, v4, s[12:13] offset:216 nt
	global_load_dword v76, v4, s[12:13] offset:224 nt
	global_load_dword v77, v4, s[12:13] offset:232 nt
	global_load_dword v78, v4, s[12:13] offset:240 nt
	global_load_dword v79, v4, s[12:13] offset:248 nt
	v_readlane_b32 s74, v251, 7
	v_readlane_b32 s75, v251, 8
	v_readlane_b32 s76, v251, 9
	v_readlane_b32 s77, v251, 10
	v_readlane_b32 s78, v251, 11
	v_readlane_b32 s79, v251, 12
	v_readlane_b32 s80, v251, 13
	v_readlane_b32 s81, v251, 14
	v_readlane_b32 s82, v251, 15
	v_readlane_b32 s83, v251, 16
	v_readlane_b32 s84, v251, 17
	v_readlane_b32 s85, v251, 18
	v_readlane_b32 s86, v251, 19
	v_readlane_b32 s87, v251, 20
	s_waitcnt vmcnt(30)
	v_pk_mul_f32 v[6:7], v[6:7], v[48:49]
	s_waitcnt vmcnt(28)
	v_pk_mul_f32 v[10:11], v[10:11], v[50:51]
	s_waitcnt vmcnt(26)
	v_pk_mul_f32 v[8:9], v[8:9], v[52:53]
	s_waitcnt vmcnt(24)
	v_pk_mul_f32 v[12:13], v[12:13], v[54:55]
	s_waitcnt vmcnt(22)
	v_pk_mul_f32 v[14:15], v[14:15], v[56:57]
	s_waitcnt vmcnt(20)
	v_pk_mul_f32 v[18:19], v[18:19], v[58:59]
	s_waitcnt vmcnt(18)
	v_pk_mul_f32 v[16:17], v[16:17], v[60:61]
	s_waitcnt vmcnt(16)
	v_pk_mul_f32 v[20:21], v[20:21], v[62:63]
	s_waitcnt vmcnt(14)
	v_pk_mul_f32 v[22:23], v[22:23], v[64:65]
	s_waitcnt vmcnt(12)
	v_pk_mul_f32 v[26:27], v[26:27], v[66:67]
	s_waitcnt vmcnt(10)
	v_pk_mul_f32 v[24:25], v[24:25], v[68:69]
	s_waitcnt vmcnt(8)
	v_pk_mul_f32 v[28:29], v[28:29], v[70:71]
	s_waitcnt vmcnt(6)
	v_pk_mul_f32 v[30:31], v[30:31], v[72:73]
	s_waitcnt vmcnt(4)
	v_pk_mul_f32 v[36:37], v[36:37], v[74:75]
	s_waitcnt vmcnt(2)
	v_pk_mul_f32 v[34:35], v[34:35], v[76:77]
	s_waitcnt vmcnt(0)
	v_pk_mul_f32 v[32:33], v[32:33], v[78:79]

; __device__ __forceinline__ void transpose_item(const float* __restrict__ W, int K, int N, bf16_t* __restrict__ WT, int id, const float* __restrict__ gk, LAS float* scr, int item, int nblk, int lane) {
;     const int kb = item / nblk, nb = item % nblk, k0 = 64 * kb, n0 = 32 * nb;
;     const int sc = srccol(id, n0 + (lane & 31));
;     const float* src = W + (size_t)(k0 + (lane >> 5)) * N + (sc < 0 ? 0 : sc);
;     float v[32];
; #pragma unroll
;     for (int i = 0; i < 32; ++i) v[i] = src[(size_t)(2 * i) * N];
; __device__ __forceinline__ void prologue_phase(const Args& A, LAS unsigned char* lds, int G, const int wv) {
;     ...
;         if (r < I_KVK) { transpose_item(A.w_ukv + (size_t)l * 256 * 2048, 256, 2048, (bf16_t*)(ws + WS_WUKVK) + (size_t)l * 1024 * 256, 3, A.kv_norm + l * 256, scr, r, 32, lane); continue; } r -= I_KVK;
.LBB0_50:
	s_and_b64 vcc, exec, s[12:13]
	s_cbranch_vccz .LBB0_97
	s_lshl_b32 s12, s10, 8
	s_sub_i32 s11, s35, s12
	s_mov_b32 s91, s90
	s_mov_b32 s90, s88
	s_mov_b32 s88, s25
	s_mov_b32 s25, s24
	s_mov_b32 s24, s8
	s_mov_b32 s8, s23
	s_mov_b32 s23, s21
	s_mov_b32 s21, s18
	s_and_b32 s18, s11, 0x1c0
	s_mul_i32 s11, s10, 0xfff4b000
	s_add_i32 s11, s33, s11
	s_and_b32 s13, s37, 0x700
	s_and_b32 vcc_lo, s11, 0x60
	s_or_b32 s13, vcc_lo, s13
	v_bitop3_b32 v48, s18, v3, v47 bitop3:0xde
	v_or_b32_e32 v8, s13, v38
	v_lshlrev_b32_e32 v4, 13, v48
	v_lshl_add_u64 v[6:7], s[6:7], 0, v[4:5]
	v_lshlrev_b32_e32 v4, 2, v8
	v_lshl_add_u64 v[30:31], v[6:7], 0, v[4:5]
	v_add_co_u32_e32 v8, vcc, s39, v30
	s_nop 1
	v_addc_co_u32_e32 v9, vcc, 0, v31, vcc
	v_add_co_u32_e32 v10, vcc, s40, v30
	s_nop 1
	v_addc_co_u32_e32 v11, vcc, 0, v31, vcc
	v_add_co_u32_e32 v12, vcc, s41, v30
	s_nop 1
	v_addc_co_u32_e32 v13, vcc, 0, v31, vcc
	v_add_co_u32_e32 v14, vcc, s42, v30
	s_nop 1
	v_addc_co_u32_e32 v15, vcc, 0, v31, vcc
	v_add_co_u32_e32 v16, vcc, s43, v30
	s_nop 1
	v_addc_co_u32_e32 v17, vcc, 0, v31, vcc
	v_add_co_u32_e32 v18, vcc, s44, v30
	s_nop 1
	v_addc_co_u32_e32 v19, vcc, 0, v31, vcc
	v_add_co_u32_e32 v20, vcc, s45, v30
	s_nop 1
	v_addc_co_u32_e32 v21, vcc, 0, v31, vcc
	global_load_dword v6, v[30:31], off nt
	global_load_dword v7, v[8:9], off nt
	s_nop 0
	global_load_dword v10, v[10:11], off nt
	s_nop 0
	global_load_dword v11, v[12:13], off nt
	global_load_dword v8, v[14:15], off nt
	global_load_dword v9, v[16:17], off nt
	s_nop 0
	global_load_dword v12, v[18:19], off nt
	global_load_dword v13, v[20:21], off nt
	v_add_co_u32_e32 v14, vcc, s46, v30
	s_nop 1
	v_addc_co_u32_e32 v15, vcc, 0, v31, vcc
	v_add_co_u32_e32 v16, vcc, s47, v30
	s_nop 1
	v_addc_co_u32_e32 v17, vcc, 0, v31, vcc
	v_add_co_u32_e32 v18, vcc, s48, v30
	s_nop 1
	v_addc_co_u32_e32 v19, vcc, 0, v31, vcc
	v_add_co_u32_e32 v20, vcc, s49, v30
	s_nop 1
	v_addc_co_u32_e32 v21, vcc, 0, v31, vcc
	v_add_co_u32_e32 v22, vcc, s50, v30
	s_nop 1
	v_addc_co_u32_e32 v23, vcc, 0, v31, vcc
	v_add_co_u32_e32 v24, vcc, s51, v30
	s_nop 1
	v_addc_co_u32_e32 v25, vcc, 0, v31, vcc
	v_add_co_u32_e32 v26, vcc, s52, v30
	s_nop 1
	v_addc_co_u32_e32 v27, vcc, 0, v31, vcc
	v_add_co_u32_e32 v28, vcc, s53, v30
	s_nop 1
	v_addc_co_u32_e32 v29, vcc, 0, v31, vcc
	global_load_dword v14, v[14:15], off nt
	s_nop 0
	global_load_dword v15, v[16:17], off nt
	s_nop 0
	global_load_dword v18, v[18:19], off nt
	s_nop 0
	global_load_dword v19, v[20:21], off nt
	global_load_dword v16, v[22:23], off nt
	global_load_dword v17, v[24:25], off nt
	s_nop 0
	global_load_dword v20, v[26:27], off nt
	global_load_dword v21, v[28:29], off nt
	v_add_co_u32_e32 v22, vcc, s54, v30
	s_nop 1
	v_addc_co_u32_e32 v23, vcc, 0, v31, vcc
	v_add_co_u32_e32 v24, vcc, s55, v30
	s_nop 1
	v_addc_co_u32_e32 v25, vcc, 0, v31, vcc
	v_add_co_u32_e32 v26, vcc, s56, v30
	s_nop 1
	v_addc_co_u32_e32 v27, vcc, 0, v31, vcc
	v_add_co_u32_e32 v28, vcc, s57, v30
	s_nop 1
	v_addc_co_u32_e32 v29, vcc, 0, v31, vcc
	v_add_co_u32_e32 v32, vcc, s58, v30
	s_nop 1
	v_addc_co_u32_e32 v33, vcc, 0, v31, vcc
	v_add_co_u32_e32 v34, vcc, s59, v30
	s_nop 1
	v_addc_co_u32_e32 v35, vcc, 0, v31, vcc
	v_add_co_u32_e32 v36, vcc, s60, v30
	s_nop 1
	v_addc_co_u32_e32 v37, vcc, 0, v31, vcc
	v_add_co_u32_e32 v50, vcc, s61, v30
	s_nop 1
	v_addc_co_u32_e32 v51, vcc, 0, v31, vcc
	global_load_dword v22, v[22:23], off nt
	s_nop 0
	global_load_dword v23, v[24:25], off nt
	s_nop 0
	global_load_dword v26, v[26:27], off nt
	s_nop 0
	global_load_dword v27, v[28:29], off nt
	global_load_dword v24, v[32:33], off nt
	global_load_dword v25, v[34:35], off nt
	s_nop 0
	global_load_dword v28, v[36:37], off nt
	global_load_dword v29, v[50:51], off nt
	v_add_co_u32_e32 v32, vcc, s62, v30
	s_nop 1
	v_addc_co_u32_e32 v33, vcc, 0, v31, vcc
	v_add_co_u32_e32 v34, vcc, s63, v30
	s_nop 1
	v_addc_co_u32_e32 v35, vcc, 0, v31, vcc
	v_add_co_u32_e32 v36, vcc, s64, v30
	s_nop 1
	v_addc_co_u32_e32 v37, vcc, 0, v31, vcc
	v_add_co_u32_e32 v50, vcc, s65, v30
	s_nop 1
	v_addc_co_u32_e32 v51, vcc, 0, v31, vcc
	v_add_co_u32_e32 v52, vcc, s66, v30
	s_nop 1
	v_addc_co_u32_e32 v53, vcc, 0, v31, vcc
	v_add_co_u32_e32 v54, vcc, 0x74000, v30
	s_nop 1
	v_addc_co_u32_e32 v55, vcc, 0, v31, vcc
	v_add_co_u32_e32 v56, vcc, 0x78000, v30
	s_nop 1
	v_addc_co_u32_e32 v57, vcc, 0, v31, vcc
	v_add_co_u32_e32 v58, vcc, 0x7c000, v30
	s_nop 1
	v_addc_co_u32_e32 v59, vcc, 0, v31, vcc
	global_load_dword v30, v[32:33], off nt
	global_load_dword v31, v[34:35], off nt
	s_nop 0
	global_load_dword v36, v[36:37], off nt
	s_nop 0
	global_load_dword v37, v[50:51], off nt
	global_load_dword v34, v[52:53], off nt
	global_load_dword v35, v[54:55], off nt
	global_load_dword v32, v[56:57], off nt
	global_load_dword v33, v[58:59], off nt
	s_and_b64 vcc, exec, s[0:1]
	s_cbranch_vccnz .LBB0_53
; __device__ __forceinline__ void transpose_item(const float* __restrict__ W, int K, int N, bf16_t* __restrict__ WT, int id, const float* __restrict__ gk, LAS float* scr, int item, int nblk, int lane) {
;     ...
;     if (gk) {
; #pragma unroll
;         for (int i = 0; i < 32; ++i) v[i] *= gk[k0 + 2 * i + (lane >> 5)];
;     }
	s_ashr_i32 s13, s12, 31
	s_lshl_b64 s[0:1], s[12:13], 2
	v_readlane_b32 s72, v251, 5
	v_readlane_b32 s73, v251, 6
	s_add_u32 s0, s72, s0
	s_addc_u32 s1, s73, s1
	v_lshlrev_b32_e32 v4, 2, v48
	global_load_dword v48, v4, s[0:1] nt
	global_load_dword v49, v4, s[0:1] offset:8 nt
	global_load_dword v50, v4, s[0:1] offset:16 nt
	global_load_dword v51, v4, s[0:1] offset:24 nt
	global_load_dword v52, v4, s[0:1] offset:32 nt
	global_load_dword v53, v4, s[0:1] offset:40 nt
	global_load_dword v54, v4, s[0:1] offset:48 nt
	global_load_dword v55, v4, s[0:1] offset:56 nt
	global_load_dword v56, v4, s[0:1] offset:64 nt
	global_load_dword v57, v4, s[0:1] offset:72 nt
	global_load_dword v58, v4, s[0:1] offset:80 nt
	global_load_dword v59, v4, s[0:1] offset:88 nt
	global_load_dword v60, v4, s[0:1] offset:96 nt
	global_load_dword v61, v4, s[0:1] offset:104 nt
	global_load_dword v62, v4, s[0:1] offset:112 nt
	global_load_dword v63, v4, s[0:1] offset:120 nt
	global_load_dword v64, v4, s[0:1] offset:128 nt
	global_load_dword v65, v4, s[0:1] offset:136 nt
	global_load_dword v66, v4, s[0:1] offset:144 nt
	global_load_dword v67, v4, s[0:1] offset:152 nt
	global_load_dword v68, v4, s[0:1] offset:160 nt
	global_load_dword v69, v4, s[0:1] offset:168 nt
	global_load_dword v70, v4, s[0:1] offset:176 nt
	global_load_dword v71, v4, s[0:1] offset:184 nt
	global_load_dword v72, v4, s[0:1] offset:192 nt
	global_load_dword v73, v4, s[0:1] offset:200 nt
	global_load_dword v74, v4, s[0:1] offset:208 nt
	global_load_dword v75, v4, s[0:1] offset:216 nt
	global_load_dword v76, v4, s[0:1] offset:224 nt
	global_load_dword v77, v4, s[0:1] offset:232 nt
	global_load_dword v78, v4, s[0:1] offset:240 nt
	global_load_dword v79, v4, s[0:1] offset:248 nt
	v_readlane_b32 s74, v251, 7
	v_readlane_b32 s75, v251, 8
	v_readlane_b32 s76, v251, 9
	v_readlane_b32 s77, v251, 10
	v_readlane_b32 s78, v251, 11
	v_readlane_b32 s79, v251, 12
	v_readlane_b32 s80, v251, 13
	v_readlane_b32 s81, v251, 14
	v_readlane_b32 s82, v251, 15
	v_readlane_b32 s83, v251, 16
	v_readlane_b32 s84, v251, 17
	v_readlane_b32 s85, v251, 18
	v_readlane_b32 s86, v251, 19
	v_readlane_b32 s87, v251, 20
	s_waitcnt vmcnt(30)
	v_pk_mul_f32 v[6:7], v[6:7], v[48:49]
	s_waitcnt vmcnt(28)
	v_pk_mul_f32 v[10:11], v[10:11], v[50:51]
	s_waitcnt vmcnt(26)
	v_pk_mul_f32 v[8:9], v[8:9], v[52:53]
	s_waitcnt vmcnt(24)
	v_pk_mul_f32 v[12:13], v[12:13], v[54:55]
	s_waitcnt vmcnt(22)
	v_pk_mul_f32 v[14:15], v[14:15], v[56:57]
	s_waitcnt vmcnt(20)
	v_pk_mul_f32 v[18:19], v[18:19], v[58:59]
	s_waitcnt vmcnt(18)
	v_pk_mul_f32 v[16:17], v[16:17], v[60:61]
	s_waitcnt vmcnt(16)
	v_pk_mul_f32 v[20:21], v[20:21], v[62:63]
	s_waitcnt vmcnt(14)
	v_pk_mul_f32 v[22:23], v[22:23], v[64:65]
	s_waitcnt vmcnt(12)
	v_pk_mul_f32 v[26:27], v[26:27], v[66:67]
	s_waitcnt vmcnt(10)
	v_pk_mul_f32 v[24:25], v[24:25], v[68:69]
	s_waitcnt vmcnt(8)
	v_pk_mul_f32 v[28:29], v[28:29], v[70:71]
	s_waitcnt vmcnt(6)
	v_pk_mul_f32 v[30:31], v[30:31], v[72:73]
	s_waitcnt vmcnt(4)
	v_pk_mul_f32 v[36:37], v[36:37], v[74:75]
	s_waitcnt vmcnt(2)
	v_pk_mul_f32 v[34:35], v[34:35], v[76:77]
	s_waitcnt vmcnt(0)
	v_pk_mul_f32 v[32:33], v[32:33], v[78:79]

; __device__ __forceinline__ int srccol(int id, int r) {
;     ...
;     if (id == 2) { const int h = r / 192, w = r % 192; if (w < 128) return h * 192 + w; const int j = w - 128; return h * 192 + 128 + (j >> 1) + (j & 1) * 32; }
; __device__ __forceinline__ void transpose_item(const float* __restrict__ W, int K, int N, bf16_t* __restrict__ WT, int id, const float* __restrict__ gk, LAS float* scr, int item, int nblk, int lane) {
;     const int kb = item / nblk, nb = item % nblk, k0 = 64 * kb, n0 = 32 * nb;
;     const int sc = srccol(id, n0 + (lane & 31));
;     const float* src = W + (size_t)(k0 + (lane >> 5)) * N + (sc < 0 ? 0 : sc);
;     float v[32];
; #pragma unroll
;     for (int i = 0; i < 32; ++i) v[i] = src[(size_t)(2 * i) * N];
; __device__ __forceinline__ void prologue_phase(const Args& A, LAS unsigned char* lds, int G, const int wv) {
;     ...
;         if (r < I_UQ) { transpose_item(A.w_uq + (size_t)l * 512 * 1536, 512, 1536, (bf16_t*)(ws + WS_WUQ) + (size_t)l * 1536 * 512, 2, A.q_norm + l * 512, scr, r, 48, lane); continue; } r -= I_UQ;
.LBB0_55:
	s_add_i32 s0, s17, 0xa800
	s_and_b32 s1, s0, 0xffff
	s_mul_i32 s1, s1, 0xaaab
	s_lshr_b32 s4, s1, 21
	s_mul_i32 s1, s4, 48
	s_sub_i32 s0, s0, s1
	s_lshl_b32 s0, s0, 5
	s_and_b32 s11, s0, 0xffe0
	v_or_b32_e32 v12, s11, v38
	v_mul_u32_u24_e32 v4, 0x2aab, v12
	v_lshrrev_b32_e32 v4, 21, v4
	v_mul_lo_u16_e32 v4, 0xc0, v4
	v_sub_u16_e32 v4, v12, v4
	s_movk_i32 s0, 0x7f
	v_cmp_lt_u16_e32 vcc, s0, v4
	s_and_saveexec_b64 s[0:1], vcc
	v_add_u32_e32 v6, 0xffffff80, v4
	v_lshrrev_b32_e32 v6, 1, v6
	v_lshlrev_b32_e32 v7, 5, v4
	v_sub_u32_e32 v4, v12, v4
	v_and_b32_e32 v7, 32, v7
	v_add_u32_e32 v4, v4, v6
	s_movk_i32 s5, 0x80
	v_add3_u32 v12, v4, v7, s5
	s_or_b64 exec, exec, s[0:1]
	v_readlane_b32 s72, v251, 25
	s_mul_i32 s0, s10, 0x300000
	v_readlane_b32 s86, v251, 39
	s_mul_hi_i32 s1, s10, 0x300000
	v_readlane_b32 s87, v251, 40
	s_add_u32 s0, s86, s0
	s_addc_u32 s1, s87, s1
	s_and_b32 s4, 0xffff, s4
	s_lshl_b32 s12, s4, 6
	v_or_b32_e32 v48, s12, v3
	v_mov_b64_e32 v[6:7], s[0:1]
	s_movk_i32 s0, 0x1800
	v_mad_u64_u32 v[6:7], s[0:1], v48, s0, v[6:7]
	v_max_i32_e32 v4, 0, v12
	v_lshl_add_u64 v[6:7], v[4:5], 2, v[6:7]
	s_movk_i32 s0, 0x3000
	v_add_co_u32_e32 v8, vcc, s0, v6
	s_movk_i32 s0, 0x6000
	s_nop 0
	v_addc_co_u32_e32 v9, vcc, 0, v7, vcc
	v_add_co_u32_e32 v10, vcc, s0, v6
	s_mov_b32 s0, 0x9000
	s_nop 0
	v_addc_co_u32_e32 v11, vcc, 0, v7, vcc
	v_add_co_u32_e32 v14, vcc, s0, v6
	s_mov_b32 s4, 0x12000
	s_nop 0
	v_addc_co_u32_e32 v15, vcc, 0, v7, vcc
	v_add_co_u32_e32 v16, vcc, s9, v6
	s_mov_b64 s[0:1], vcc
	v_add_co_u32_e32 v18, vcc, s4, v6
	s_mov_b32 s6, 0x15000
	s_mov_b64 s[4:5], vcc
	v_add_co_u32_e32 v20, vcc, s6, v6
	v_add_co_u32_e64 v22, s[6:7], s44, v6
	s_mov_b32 s13, 0x1b000
	s_nop 0
	v_addc_co_u32_e64 v23, s[6:7], 0, v7, s[6:7]
	s_mov_b64 s[6:7], vcc
	v_add_co_u32_e32 v24, vcc, s13, v6
	s_mov_b32 s13, 0x21000
	s_nop 0
	v_addc_co_u32_e32 v25, vcc, 0, v7, vcc
	v_add_co_u32_e32 v26, vcc, s19, v6
	v_readlane_b32 s84, v251, 37
	s_nop 0
	v_addc_co_u32_e32 v27, vcc, 0, v7, vcc
	v_add_co_u32_e32 v28, vcc, s13, v6
	s_mov_b32 s13, 0x27000
	s_nop 0
	v_addc_co_u32_e32 v29, vcc, 0, v7, vcc
	v_add_co_u32_e32 v30, vcc, s47, v6
	v_readlane_b32 s85, v251, 38
	s_nop 0
	v_addc_co_u32_e32 v31, vcc, 0, v7, vcc
	v_add_co_u32_e32 v32, vcc, s13, v6
	s_mov_b32 s13, 0x2a000
	s_nop 0
	v_addc_co_u32_e32 v33, vcc, 0, v7, vcc
	v_add_co_u32_e32 v34, vcc, s13, v6
	s_mov_b32 s13, 0x33000
	s_nop 0
	v_addc_co_u32_e32 v35, vcc, 0, v7, vcc
	v_add_co_u32_e32 v36, vcc, s20, v6
	v_readlane_b32 s73, v251, 26
	s_nop 0
	v_addc_co_u32_e32 v37, vcc, 0, v7, vcc
	v_add_co_u32_e32 v50, vcc, s50, v6
	v_readlane_b32 s74, v251, 27
	s_nop 0
	v_addc_co_u32_e32 v51, vcc, 0, v7, vcc
	v_add_co_u32_e32 v52, vcc, s13, v6
	s_mov_b32 s13, 0x36000
	s_nop 0
	v_addc_co_u32_e32 v53, vcc, 0, v7, vcc
	v_add_co_u32_e32 v54, vcc, s13, v6
	s_mov_b32 s13, 0x39000
	s_nop 0
	v_addc_co_u32_e32 v55, vcc, 0, v7, vcc
	v_add_co_u32_e32 v56, vcc, s13, v6
	s_mov_b32 s13, 0x3f000
	s_nop 0
	v_addc_co_u32_e32 v57, vcc, 0, v7, vcc
	v_add_co_u32_e32 v58, vcc, s53, v6
	v_readlane_b32 s75, v251, 28
	s_nop 0
	v_addc_co_u32_e32 v59, vcc, 0, v7, vcc
	v_add_co_u32_e32 v60, vcc, s13, v6
	s_mov_b32 s13, 0x42000
	s_nop 0
	v_addc_co_u32_e32 v61, vcc, 0, v7, vcc
	v_add_co_u32_e32 v62, vcc, s13, v6
	s_mov_b32 s13, 0x45000
	s_nop 0
	v_addc_co_u32_e32 v63, vcc, 0, v7, vcc
	v_add_co_u32_e32 v64, vcc, s13, v6
	s_mov_b32 s13, 0x4b000
	s_nop 0
	v_addc_co_u32_e32 v65, vcc, 0, v7, vcc
	v_add_co_u32_e32 v66, vcc, s56, v6
	v_readlane_b32 s76, v251, 29
	s_nop 0
	v_addc_co_u32_e32 v67, vcc, 0, v7, vcc
	v_add_co_u32_e32 v68, vcc, s13, v6
	s_mov_b32 s13, 0x4e000
	s_nop 0
	v_addc_co_u32_e32 v69, vcc, 0, v7, vcc
	v_add_co_u32_e32 v70, vcc, s13, v6
	s_mov_b32 s13, 0x51000
	s_nop 0
	v_addc_co_u32_e32 v71, vcc, 0, v7, vcc
	v_add_co_u32_e32 v72, vcc, s13, v6
	s_mov_b32 s13, 0x57000
	s_nop 0
	v_addc_co_u32_e32 v73, vcc, 0, v7, vcc
	v_add_co_u32_e32 v74, vcc, s59, v6
	v_readlane_b32 s77, v251, 30
	s_nop 0
	v_addc_co_u32_e32 v75, vcc, 0, v7, vcc
	v_add_co_u32_e32 v76, vcc, s13, v6
	s_mov_b32 s13, 0x5a000
	s_nop 0
	v_addc_co_u32_e32 v77, vcc, 0, v7, vcc
	v_add_co_u32_e32 v78, vcc, s13, v6
	s_mov_b32 s13, 0x5d000
	s_nop 0
	v_addc_co_u32_e32 v79, vcc, 0, v7, vcc
	v_add_co_u32_e32 v80, vcc, s13, v6
	v_readlane_b32 s78, v251, 31
	s_nop 0
	v_addc_co_u32_e32 v81, vcc, 0, v7, vcc
	global_load_dword v4, v[66:67], off nt
	global_load_dword v13, v[68:69], off nt
	global_load_dword v49, v[70:71], off nt
	s_nop 0
	global_load_dword v66, v[72:73], off nt
	global_load_dword v67, v[74:75], off nt
	global_load_dword v68, v[76:77], off nt
	global_load_dword v69, v[78:79], off nt
	global_load_dword v70, v[80:81], off nt
	s_nop 0
	global_load_dword v50, v[50:51], off nt
	s_nop 0
	global_load_dword v51, v[52:53], off nt
	s_nop 0
	global_load_dword v52, v[54:55], off nt
	global_load_dword v53, v[56:57], off nt
	s_nop 0
	global_load_dword v54, v[58:59], off nt
	global_load_dword v55, v[60:61], off nt
	global_load_dword v56, v[62:63], off nt
	global_load_dword v57, v[64:65], off nt
	s_nop 0
	global_load_dword v58, v[22:23], off nt
	global_load_dword v59, v[24:25], off nt
	s_nop 0
	global_load_dword v26, v[26:27], off nt
	s_nop 0
	global_load_dword v27, v[28:29], off nt
	global_load_dword v24, v[30:31], off nt
	global_load_dword v25, v[32:33], off nt
	s_nop 0
	global_load_dword v28, v[34:35], off nt
	global_load_dword v29, v[36:37], off nt
	v_add_co_u32_e32 v22, vcc, s41, v6
	v_readlane_b32 s79, v251, 32
	s_nop 0
	v_addc_co_u32_e32 v23, vcc, 0, v7, vcc
	v_addc_co_u32_e64 v21, vcc, 0, v7, s[6:7]
	v_addc_co_u32_e64 v17, vcc, 0, v7, s[0:1]
	v_addc_co_u32_e64 v19, vcc, 0, v7, s[4:5]
	global_load_dword v30, v[20:21], off nt
	global_load_dword v32, v[18:19], off nt
	global_load_dword v33, v[16:17], off nt
	global_load_dword v34, v[22:23], off nt
	global_load_dword v35, v[14:15], off nt
	global_load_dword v36, v[10:11], off nt
	global_load_dword v37, v[8:9], off nt
	global_load_dword v60, v[6:7], off nt
	v_readlane_b32 s4, v251, 56
	v_cmp_lt_i32_e64 s[0:1], -1, v12
	v_readlane_b32 s5, v251, 57
	s_andn2_b64 vcc, exec, s[4:5]
	v_readlane_b32 s80, v251, 33
	v_readlane_b32 s81, v251, 34
	v_readlane_b32 s82, v251, 35
	v_readlane_b32 s83, v251, 36
	s_waitcnt vmcnt(31)
; __device__ __forceinline__ void transpose_item(const float* __restrict__ W, int K, int N, bf16_t* __restrict__ WT, int id, const float* __restrict__ gk, LAS float* scr, int item, int nblk, int lane) {
;     ...
;     if (sc < 0) {
; #pragma unroll
;         for (int i = 0; i < 32; ++i) v[i] = 0.f;
;     }
;     if (gk) {
; #pragma unroll
;         for (int i = 0; i < 32; ++i) v[i] *= gk[k0 + 2 * i + (lane >> 5)];
;     }
	v_cndmask_b32_e64 v12, 0, v4, s[0:1]
	s_waitcnt vmcnt(30)
	v_cndmask_b32_e64 v13, 0, v13, s[0:1]
	s_waitcnt vmcnt(29)
	v_cndmask_b32_e64 v10, 0, v49, s[0:1]
	s_waitcnt vmcnt(28)
	v_cndmask_b32_e64 v11, 0, v66, s[0:1]
	s_waitcnt vmcnt(27)
	v_cndmask_b32_e64 v8, 0, v67, s[0:1]
	s_waitcnt vmcnt(26)
	v_cndmask_b32_e64 v9, 0, v68, s[0:1]
	s_waitcnt vmcnt(25)
	v_cndmask_b32_e64 v6, 0, v69, s[0:1]
	s_waitcnt vmcnt(24)
	v_cndmask_b32_e64 v7, 0, v70, s[0:1]
	s_waitcnt vmcnt(23)
	v_cndmask_b32_e64 v20, 0, v50, s[0:1]
	s_waitcnt vmcnt(22)
	v_cndmask_b32_e64 v21, 0, v51, s[0:1]
	s_waitcnt vmcnt(21)
	v_cndmask_b32_e64 v18, 0, v52, s[0:1]
	s_waitcnt vmcnt(20)
	v_cndmask_b32_e64 v19, 0, v53, s[0:1]
	s_waitcnt vmcnt(19)
	v_cndmask_b32_e64 v16, 0, v54, s[0:1]
	s_waitcnt vmcnt(18)
	v_cndmask_b32_e64 v17, 0, v55, s[0:1]
	s_waitcnt vmcnt(17)
	v_cndmask_b32_e64 v14, 0, v56, s[0:1]
	s_waitcnt vmcnt(16)
	v_cndmask_b32_e64 v15, 0, v57, s[0:1]
	s_waitcnt vmcnt(13)
	v_cndmask_b32_e64 v26, 0, v26, s[0:1]
	s_waitcnt vmcnt(12)
	v_cndmask_b32_e64 v27, 0, v27, s[0:1]
	s_waitcnt vmcnt(11)
	v_cndmask_b32_e64 v24, 0, v24, s[0:1]
	s_waitcnt vmcnt(10)
	v_cndmask_b32_e64 v25, 0, v25, s[0:1]
	s_waitcnt vmcnt(9)
	v_cndmask_b32_e64 v22, 0, v28, s[0:1]
	s_waitcnt vmcnt(8)
	v_cndmask_b32_e64 v23, 0, v29, s[0:1]
	v_cndmask_b32_e64 v29, 0, v59, s[0:1]
	v_cndmask_b32_e64 v28, 0, v58, s[0:1]
	s_waitcnt vmcnt(7)
	v_cndmask_b32_e64 v31, 0, v30, s[0:1]
	s_waitcnt vmcnt(6)
	v_cndmask_b32_e64 v30, 0, v32, s[0:1]
	s_waitcnt vmcnt(5)
	v_cndmask_b32_e64 v33, 0, v33, s[0:1]
	s_waitcnt vmcnt(4)
	v_cndmask_b32_e64 v32, 0, v34, s[0:1]
	s_waitcnt vmcnt(3)
	v_cndmask_b32_e64 v35, 0, v35, s[0:1]
	s_waitcnt vmcnt(2)
	v_cndmask_b32_e64 v34, 0, v36, s[0:1]
	s_waitcnt vmcnt(1)
	v_cndmask_b32_e64 v37, 0, v37, s[0:1]
	s_waitcnt vmcnt(0)
	v_cndmask_b32_e64 v36, 0, v60, s[0:1]
	s_cbranch_vccnz .LBB0_59
	s_lshl_b32 s0, s10, 9
	s_ashr_i32 s1, s0, 31
	s_lshl_b64 s[0:1], s[0:1], 2
	s_add_u32 s0, s84, s0
	s_addc_u32 s1, s85, s1
	v_lshlrev_b32_e32 v4, 2, v48
	global_load_dword v48, v4, s[0:1] offset:128 nt
	global_load_dword v49, v4, s[0:1] offset:136 nt
	global_load_dword v50, v4, s[0:1] offset:144 nt
	global_load_dword v51, v4, s[0:1] offset:152 nt
	global_load_dword v52, v4, s[0:1] offset:160 nt
	global_load_dword v53, v4, s[0:1] offset:168 nt
	global_load_dword v54, v4, s[0:1] offset:176 nt
	global_load_dword v55, v4, s[0:1] offset:184 nt
	global_load_dword v56, v4, s[0:1] offset:192 nt
	global_load_dword v57, v4, s[0:1] offset:200 nt
	global_load_dword v58, v4, s[0:1] offset:208 nt
	global_load_dword v59, v4, s[0:1] offset:216 nt
	global_load_dword v60, v4, s[0:1] offset:224 nt
	global_load_dword v61, v4, s[0:1] offset:232 nt
	global_load_dword v62, v4, s[0:1] offset:240 nt
	global_load_dword v63, v4, s[0:1] offset:248 nt
	global_load_dword v64, v4, s[0:1] offset:64 nt
	global_load_dword v65, v4, s[0:1] offset:72 nt
	global_load_dword v66, v4, s[0:1] offset:80 nt
	global_load_dword v67, v4, s[0:1] offset:88 nt
	global_load_dword v68, v4, s[0:1] offset:96 nt
	global_load_dword v69, v4, s[0:1] offset:104 nt
	global_load_dword v70, v4, s[0:1] offset:112 nt
	global_load_dword v71, v4, s[0:1] offset:120 nt
	global_load_dword v72, v4, s[0:1] offset:16 nt
	global_load_dword v73, v4, s[0:1] offset:24 nt
	global_load_dword v74, v4, s[0:1] offset:32 nt
	global_load_dword v76, v4, s[0:1] offset:48 nt
	global_load_dword v77, v4, s[0:1] offset:56 nt
	global_load_dword v75, v4, s[0:1] offset:40 nt
	global_load_dword v78, v4, s[0:1] nt
	global_load_dword v79, v4, s[0:1] offset:8 nt
	s_waitcnt vmcnt(30)
	v_pk_mul_f32 v[20:21], v[20:21], v[48:49]
	s_waitcnt vmcnt(28)
	v_pk_mul_f32 v[18:19], v[18:19], v[50:51]
	s_waitcnt vmcnt(26)
	v_pk_mul_f32 v[16:17], v[16:17], v[52:53]
	s_waitcnt vmcnt(24)
	v_pk_mul_f32 v[14:15], v[14:15], v[54:55]
	s_waitcnt vmcnt(22)
	v_pk_mul_f32 v[12:13], v[12:13], v[56:57]
	s_waitcnt vmcnt(20)
	v_pk_mul_f32 v[10:11], v[10:11], v[58:59]
	s_waitcnt vmcnt(18)
	v_pk_mul_f32 v[8:9], v[8:9], v[60:61]
	s_waitcnt vmcnt(16)
	v_pk_mul_f32 v[6:7], v[6:7], v[62:63]
	s_waitcnt vmcnt(14)
	v_pk_mul_f32 v[28:29], v[28:29], v[64:65]
	s_waitcnt vmcnt(12)
	v_pk_mul_f32 v[26:27], v[26:27], v[66:67]
	s_waitcnt vmcnt(10)
	v_pk_mul_f32 v[24:25], v[24:25], v[68:69]
	s_waitcnt vmcnt(8)
	v_pk_mul_f32 v[22:23], v[22:23], v[70:71]
	s_waitcnt vmcnt(6)
	v_pk_mul_f32 v[34:35], v[34:35], v[72:73]
	s_waitcnt vmcnt(3)
	v_pk_mul_f32 v[30:31], v[30:31], v[76:77]
	s_waitcnt vmcnt(2)
	v_pk_mul_f32 v[32:33], v[32:33], v[74:75]
	s_waitcnt vmcnt(0)
	v_pk_mul_f32 v[36:37], v[36:37], v[78:79]

; __device__ __forceinline__ int srccol(int id, int r) {
;     ...
;     if (id == 1) return r < 512 ? 1856 + r : 3392 + (r - 512);
; __device__ __forceinline__ void transpose_item(const float* __restrict__ W, int K, int N, bf16_t* __restrict__ WT, int id, const float* __restrict__ gk, LAS float* scr, int item, int nblk, int lane) {
;     const int kb = item / nblk, nb = item % nblk, k0 = 64 * kb, n0 = 32 * nb;
;     const int sc = srccol(id, n0 + (lane & 31));
;     const float* src = W + (size_t)(k0 + (lane >> 5)) * N + (sc < 0 ? 0 : sc);
;     float v[32];
; #pragma unroll
;     for (int i = 0; i < 32; ++i) v[i] = src[(size_t)(2 * i) * N];
; __device__ __forceinline__ void prologue_phase(const Args& A, LAS unsigned char* lds, int G, const int wv) {
;     ...
;         if (r < I_INV) { transpose_item(A.w_in + (size_t)l * DM * INW, DM, INW, (bf16_t*)(ws + WS_WINV) + (size_t)l * 1024 * DM, 1, nullptr, scr, r, 32, lane); continue; } r -= I_INV;
.LBB0_61:
	s_andn2_b64 vcc, exec, s[0:1]
	s_cbranch_vccnz .LBB0_63
	v_readlane_b32 s72, v251, 25
	s_ashr_i32 s11, s10, 31
	s_mul_i32 s1, s10, 0x1e90000
	v_readlane_b32 s82, v251, 35
	s_mul_hi_i32 s0, s10, 0x1e90000
	v_readlane_b32 s83, v251, 36
	s_add_u32 s6, s82, s1
	s_addc_u32 s7, s83, s0
	s_lshl_b64 s[0:1], s[10:11], 22
	s_add_u32 s4, s24, s0
	s_mul_i32 s0, s10, 0xffff4b00
	s_addc_u32 s1, s25, s1
	s_add_i32 s0, s35, s0
	s_add_i32 s0, s0, 0x15800
	s_and_b32 s5, s0, 0x1ffc0
	s_and_b32 s0, s33, 0x3e0
	v_or_b32_e32 v4, s5, v3
	s_cmpk_lt_u32 s0, 0x200
	s_movk_i32 s11, 0x740
	v_mul_u32_u24_e32 v4, 0xf48, v4
	v_or_b32_e32 v8, s0, v38
	s_cselect_b32 s11, s11, 0xb40
	v_lshlrev_b32_e32 v4, 2, v4
	v_lshl_add_u64 v[6:7], s[6:7], 0, v[4:5]
	v_add_lshl_u32 v4, v8, s11, 2
	v_lshl_add_u64 v[6:7], v[6:7], 0, v[4:5]
	v_add_co_u32_e32 v8, vcc, s91, v6
	s_mov_b32 s6, 0x16000
	s_nop 0
	v_addc_co_u32_e32 v9, vcc, 0, v7, vcc
	v_add_co_u32_e32 v10, vcc, s9, v6
	s_lshl_b32 s5, s5, 1
	s_nop 0
	v_addc_co_u32_e32 v11, vcc, 0, v7, vcc
	v_add_co_u32_e32 v12, vcc, s6, v6
	s_mov_b32 s6, 0x26000
	s_nop 0
	v_addc_co_u32_e32 v13, vcc, 0, v7, vcc
	v_add_co_u32_e32 v14, vcc, s19, v6
	s_add_u32 s4, s4, s5
	s_nop 0
	v_addc_co_u32_e32 v15, vcc, 0, v7, vcc
	v_add_co_u32_e32 v16, vcc, s6, v6
	s_mov_b32 s6, 0x35000
	s_nop 0
	v_addc_co_u32_e32 v17, vcc, 0, v7, vcc
	v_add_co_u32_e32 v18, vcc, s20, v6
	s_addc_u32 s5, s1, 0
	s_nop 0
	v_addc_co_u32_e32 v19, vcc, 0, v7, vcc
	v_add_co_u32_e32 v20, vcc, s6, v6
	s_mov_b32 s6, 0x3d000
	s_nop 0
	v_addc_co_u32_e32 v21, vcc, 0, v7, vcc
	global_load_dword v4, v[6:7], off nt
	global_load_dword v24, v[8:9], off offset:2624 nt
	global_load_dword v25, v[10:11], off offset:1152 nt
	global_load_dword v26, v[12:13], off offset:3776 nt
	global_load_dword v27, v[14:15], off offset:2304 nt
	global_load_dword v28, v[16:17], off offset:832 nt
	global_load_dword v29, v[18:19], off offset:3456 nt
	global_load_dword v30, v[20:21], off offset:1984 nt
	v_add_co_u32_e32 v8, vcc, s6, v6
	s_mov_b32 s6, 0x5b000
	s_nop 0
	v_addc_co_u32_e32 v9, vcc, 0, v7, vcc
	v_add_co_u32_e32 v10, vcc, s55, v6
	v_readlane_b32 s73, v251, 26
	s_nop 0
	v_addc_co_u32_e32 v11, vcc, 0, v7, vcc
	v_add_co_u32_e32 v12, vcc, s57, v6
	v_readlane_b32 s74, v251, 27
	s_nop 0
	v_addc_co_u32_e32 v13, vcc, 0, v7, vcc
	v_add_co_u32_e32 v14, vcc, s59, v6
	v_readlane_b32 s75, v251, 28
	s_nop 0
	v_addc_co_u32_e32 v15, vcc, 0, v7, vcc
	v_add_co_u32_e32 v16, vcc, s6, v6
	s_mov_b32 s6, 0x63000
	s_nop 0
	v_addc_co_u32_e32 v17, vcc, 0, v7, vcc
	v_add_co_u32_e32 v18, vcc, s6, v6
	s_mov_b32 s6, 0x6a000
	s_nop 0
	v_addc_co_u32_e32 v19, vcc, 0, v7, vcc
	v_add_co_u32_e32 v20, vcc, s6, v6
	s_mov_b32 s6, 0x72000
	s_nop 0
	v_addc_co_u32_e32 v21, vcc, 0, v7, vcc
	v_add_co_u32_e32 v22, vcc, s6, v6
	s_mov_b32 s6, 0x7a000
	s_nop 0
	v_addc_co_u32_e32 v23, vcc, 0, v7, vcc
	global_load_dword v31, v[8:9], off offset:512 nt
	global_load_dword v32, v[10:11], off offset:3136 nt
	global_load_dword v33, v[12:13], off offset:1664 nt
	global_load_dword v34, v[14:15], off offset:192 nt
	global_load_dword v35, v[16:17], off offset:2816 nt
	global_load_dword v36, v[18:19], off offset:1344 nt
	global_load_dword v37, v[20:21], off offset:3968 nt
	global_load_dword v48, v[22:23], off offset:2496 nt
	v_add_co_u32_e32 v8, vcc, s6, v6
	s_mov_b32 s6, 0x81000
	s_nop 0
	v_addc_co_u32_e32 v9, vcc, 0, v7, vcc
	v_add_co_u32_e32 v10, vcc, s6, v6
	s_mov_b32 s6, 0x89000
	s_nop 0
	v_addc_co_u32_e32 v11, vcc, 0, v7, vcc
	v_add_co_u32_e32 v12, vcc, s6, v6
	s_mov_b32 s6, 0x91000
	s_nop 0
	v_addc_co_u32_e32 v13, vcc, 0, v7, vcc
	v_add_co_u32_e32 v14, vcc, s6, v6
	s_mov_b32 s6, 0x98000
	s_nop 0
	v_addc_co_u32_e32 v15, vcc, 0, v7, vcc
	v_add_co_u32_e32 v16, vcc, s6, v6
	s_mov_b32 s6, 0xa8000
	s_nop 0
	v_addc_co_u32_e32 v17, vcc, 0, v7, vcc
	v_add_co_u32_e32 v18, vcc, s89, v6
	v_readlane_b32 s76, v251, 29
	s_nop 0
	v_addc_co_u32_e32 v19, vcc, 0, v7, vcc
	v_add_co_u32_e32 v20, vcc, s6, v6
	s_mov_b32 s6, 0xaf000
	s_nop 0
	v_addc_co_u32_e32 v21, vcc, 0, v7, vcc
	v_add_co_u32_e32 v22, vcc, s6, v6
	v_readlane_b32 s77, v251, 30
	s_nop 0
	v_addc_co_u32_e32 v23, vcc, 0, v7, vcc
	global_load_dword v49, v[8:9], off offset:1024 nt
	global_load_dword v50, v[10:11], off offset:3648 nt
	global_load_dword v51, v[12:13], off offset:2176 nt
	global_load_dword v52, v[14:15], off offset:704 nt
	global_load_dword v53, v[16:17], off offset:3328 nt
	global_load_dword v54, v[18:19], off offset:1856 nt
	global_load_dword v55, v[20:21], off offset:384 nt
	s_nop 0
	global_load_dword v22, v[22:23], off offset:3008 nt
	v_add_co_u32_e32 v8, vcc, s92, v6
	v_readlane_b32 s78, v251, 31
	s_nop 0
	v_addc_co_u32_e32 v9, vcc, 0, v7, vcc
	v_add_co_u32_e32 v10, vcc, s93, v6
	v_readlane_b32 s79, v251, 32
	s_nop 0
	v_addc_co_u32_e32 v11, vcc, 0, v7, vcc
	v_add_co_u32_e32 v12, vcc, s94, v6
	v_readlane_b32 s80, v251, 33
	s_nop 0
	v_addc_co_u32_e32 v13, vcc, 0, v7, vcc
	v_add_co_u32_e32 v14, vcc, s95, v6
	v_readlane_b32 s81, v251, 34
	s_nop 0
	v_addc_co_u32_e32 v15, vcc, 0, v7, vcc
	v_add_co_u32_e32 v16, vcc, s96, v6
	v_readlane_b32 s84, v251, 37
	s_nop 0
	v_addc_co_u32_e32 v17, vcc, 0, v7, vcc
	v_add_co_u32_e32 v18, vcc, s97, v6
	v_readlane_b32 s85, v251, 38
	s_nop 0
	v_addc_co_u32_e32 v19, vcc, 0, v7, vcc
	v_add_co_u32_e32 v20, vcc, s15, v6
	v_readlane_b32 s86, v251, 39
	s_nop 0
	v_addc_co_u32_e32 v21, vcc, 0, v7, vcc
	v_add_co_u32_e32 v6, vcc, s16, v6
	v_readlane_b32 s87, v251, 40
	s_nop 0
	v_addc_co_u32_e32 v7, vcc, 0, v7, vcc
	global_load_dword v8, v[8:9], off offset:1536 nt
	s_nop 0
	global_load_dword v9, v[10:11], off offset:64 nt
	s_nop 0
	global_load_dword v10, v[12:13], off offset:2688 nt
	global_load_dword v11, v[14:15], off offset:1216 nt
	s_nop 0
	global_load_dword v12, v[16:17], off offset:3840 nt
	global_load_dword v13, v[18:19], off offset:2368 nt
	global_load_dword v14, v[20:21], off offset:896 nt
	s_nop 0
	global_load_dword v6, v[6:7], off offset:3520 nt
	s_waitcnt vmcnt(30)
; #define LAS __attribute__((address_space(3)))
; __device__ __forceinline__ unsigned pk2(float lo, float hi) { return f2bf(lo) | (f2bf(hi) << 16); }
; __device__ __forceinline__ void transpose_item(const float* __restrict__ W, int K, int N, bf16_t* __restrict__ WT, int id, const float* __restrict__ gk, LAS float* scr, int item, int nblk, int lane) {
;     ...
;     for (int i = 0; i < 32; ++i) scr[(2 * i + (lane >> 5)) * 33 + (lane & 31)] = v[i];
;     asm volatile("s_waitcnt lgkmcnt(0)" ::: "memory");
;     const int c = lane & 7;
; #pragma unroll
;     for (int j = 0; j < 4; ++j) { const int n = (lane >> 3) + 8 * j; const LAS float* s = scr + (8 * c) * 33 + n;
;         u32x4 o; o.x = pk2(s[0 * 33], s[1 * 33]); o.y = pk2(s[2 * 33], s[3 * 33]); o.z = pk2(s[4 * 33], s[5 * 33]); o.w = pk2(s[6 * 33], s[7 * 33]);
;         *(u32x4*)(WT + (size_t)(n0 + n) * K + k0 + 8 * c) = o; }
;     asm volatile("s_waitcnt lgkmcnt(0)" ::: "memory");
	ds_write2_b32 v39, v4, v24 offset1:66
	s_waitcnt vmcnt(28)
	ds_write2_b32 v39, v25, v26 offset0:132 offset1:198
	v_add_u32_e32 v4, 0x400, v39
	s_waitcnt vmcnt(26)
	ds_write2_b32 v4, v27, v28 offset0:8 offset1:74
	s_waitcnt vmcnt(24)
	ds_write2_b32 v4, v29, v30 offset0:140 offset1:206
	v_add_u32_e32 v4, 0x800, v39
	s_waitcnt vmcnt(22)
	ds_write2_b32 v4, v31, v32 offset0:16 offset1:82
	s_waitcnt vmcnt(20)
	ds_write2_b32 v4, v33, v34 offset0:148 offset1:214
	v_add_u32_e32 v4, 0xc00, v39
	s_waitcnt vmcnt(18)
	ds_write2_b32 v4, v35, v36 offset0:24 offset1:90
	s_waitcnt vmcnt(16)
	ds_write2_b32 v4, v37, v48 offset0:156 offset1:222
	v_add_u32_e32 v4, 0x1000, v39
	s_waitcnt vmcnt(14)
	ds_write2_b32 v4, v49, v50 offset0:32 offset1:98
	s_waitcnt vmcnt(12)
	ds_write2_b32 v4, v51, v52 offset0:164 offset1:230
	v_add_u32_e32 v4, 0x1400, v39
	s_waitcnt vmcnt(10)
	ds_write2_b32 v4, v53, v54 offset0:40 offset1:106
	s_waitcnt vmcnt(8)
	ds_write2_b32 v4, v55, v22 offset0:172 offset1:238
	v_add_u32_e32 v4, 0x1800, v39
	s_waitcnt vmcnt(6)
	ds_write2_b32 v4, v8, v9 offset0:48 offset1:114
	s_waitcnt vmcnt(4)
	ds_write2_b32 v4, v10, v11 offset0:180 offset1:246
	v_add_u32_e32 v4, 0x1c00, v39
	s_waitcnt vmcnt(2)
	ds_write2_b32 v4, v12, v13 offset0:56 offset1:122
	s_waitcnt vmcnt(0)
	ds_write2_b32 v4, v14, v6 offset0:188 offset1:254
	s_waitcnt lgkmcnt(0)
	ds_read2_b32 v[10:11], v41 offset1:8
	ds_read2_b32 v[14:15], v41 offset0:33 offset1:41
	ds_read2_b32 v[16:17], v41 offset0:66 offset1:74
	v_lshlrev_b32_e32 v4, 1, v2
	ds_read2_b32 v[18:19], v41 offset0:99 offset1:107
	v_lshl_add_u64 v[12:13], s[4:5], 0, v[4:5]
	s_waitcnt lgkmcnt(3)
	v_bfe_u32 v4, v10, 16, 1
	v_add3_u32 v4, v10, v4, s70
	s_waitcnt lgkmcnt(2)
	v_bfe_u32 v6, v14, 16, 1
	ds_read2_b32 v[20:21], v41 offset0:132 offset1:140
	v_lshrrev_b32_e32 v4, 16, v4
	v_add3_u32 v6, v14, v6, s70
	ds_read2_b32 v[22:23], v41 offset0:165 offset1:173
	v_and_or_b32 v6, v6, s71, v4
	s_waitcnt lgkmcnt(3)
	v_bfe_u32 v4, v16, 16, 1
	v_add3_u32 v4, v16, v4, s70
	s_waitcnt lgkmcnt(2)
	v_bfe_u32 v7, v18, 16, 1
	ds_read2_b32 v[24:25], v41 offset0:198 offset1:206
	v_lshrrev_b32_e32 v4, 16, v4
	v_add3_u32 v7, v18, v7, s70
	ds_read2_b32 v[26:27], v41 offset0:231 offset1:239
	v_and_or_b32 v7, v7, s71, v4
	s_waitcnt lgkmcnt(3)
	v_bfe_u32 v4, v20, 16, 1
	v_add3_u32 v4, v20, v4, s70
	s_waitcnt lgkmcnt(2)
	v_bfe_u32 v8, v22, 16, 1
	v_lshrrev_b32_e32 v4, 16, v4
	v_add3_u32 v8, v22, v8, s70
	v_and_or_b32 v8, v8, s71, v4
	s_waitcnt lgkmcnt(1)
	v_bfe_u32 v4, v24, 16, 1
	v_add3_u32 v4, v24, v4, s70
	s_waitcnt lgkmcnt(0)
	v_bfe_u32 v9, v26, 16, 1
	v_lshrrev_b32_e32 v4, 16, v4
	v_add3_u32 v9, v26, v9, s70
	v_and_or_b32 v9, v9, s71, v4
	v_or_b32_e32 v4, s0, v40
	v_lshlrev_b32_e32 v4, 12, v4
	v_lshl_add_u64 v[28:29], v[12:13], 0, v[4:5]
	v_bfe_u32 v4, v11, 16, 1
	global_store_dwordx4 v[28:29], v[6:9], off
	v_add3_u32 v4, v11, v4, s70
	v_lshrrev_b32_e32 v4, 16, v4
	v_bfe_u32 v6, v15, 16, 1
	v_add3_u32 v6, v15, v6, s70
	v_and_or_b32 v6, v6, s71, v4
	v_bfe_u32 v4, v17, 16, 1
	v_add3_u32 v4, v17, v4, s70
	v_bfe_u32 v7, v19, 16, 1
	v_lshrrev_b32_e32 v4, 16, v4
	v_add3_u32 v7, v19, v7, s70
	v_and_or_b32 v7, v7, s71, v4
	v_bfe_u32 v4, v21, 16, 1
	v_add3_u32 v4, v21, v4, s70
	v_bfe_u32 v8, v23, 16, 1
	v_lshrrev_b32_e32 v4, 16, v4
	v_add3_u32 v8, v23, v8, s70
	v_and_or_b32 v8, v8, s71, v4
	v_bfe_u32 v4, v25, 16, 1
	v_add3_u32 v4, v25, v4, s70
	v_bfe_u32 v9, v27, 16, 1
	v_lshrrev_b32_e32 v4, 16, v4
	v_add3_u32 v9, v27, v9, s70
	v_and_or_b32 v9, v9, s71, v4
	v_or_b32_e32 v4, s0, v42
	v_lshlrev_b32_e32 v4, 12, v4
	ds_read2_b32 v[10:11], v41 offset0:16 offset1:24
	v_lshl_add_u64 v[14:15], v[12:13], 0, v[4:5]
	global_store_dwordx4 v[14:15], v[6:9], off
	ds_read2_b32 v[14:15], v41 offset0:49 offset1:57
	ds_read2_b32 v[16:17], v41 offset0:82 offset1:90
	ds_read2_b32 v[18:19], v41 offset0:115 offset1:123
	s_waitcnt lgkmcnt(3)
	v_bfe_u32 v4, v10, 16, 1
	v_add3_u32 v4, v10, v4, s70
	s_waitcnt lgkmcnt(2)
	v_bfe_u32 v6, v14, 16, 1
	ds_read2_b32 v[20:21], v41 offset0:148 offset1:156
	v_lshrrev_b32_e32 v4, 16, v4
	v_add3_u32 v6, v14, v6, s70
	ds_read2_b32 v[22:23], v41 offset0:181 offset1:189
	v_and_or_b32 v6, v6, s71, v4
	s_waitcnt lgkmcnt(3)
	v_bfe_u32 v4, v16, 16, 1
	v_add3_u32 v4, v16, v4, s70
	s_waitcnt lgkmcnt(2)
	v_bfe_u32 v7, v18, 16, 1
	ds_read2_b32 v[24:25], v41 offset0:214 offset1:222
	v_lshrrev_b32_e32 v4, 16, v4
	v_add3_u32 v7, v18, v7, s70
	ds_read2_b32 v[26:27], v41 offset0:247 offset1:255
	v_and_or_b32 v7, v7, s71, v4
	s_waitcnt lgkmcnt(3)
	v_bfe_u32 v4, v20, 16, 1
	v_add3_u32 v4, v20, v4, s70
	s_waitcnt lgkmcnt(2)
	v_bfe_u32 v8, v22, 16, 1
	v_lshrrev_b32_e32 v4, 16, v4
	v_add3_u32 v8, v22, v8, s70
	v_and_or_b32 v8, v8, s71, v4
	s_waitcnt lgkmcnt(1)
	v_bfe_u32 v4, v24, 16, 1
	v_add3_u32 v4, v24, v4, s70
	s_waitcnt lgkmcnt(0)
	v_bfe_u32 v9, v26, 16, 1
	v_lshrrev_b32_e32 v4, 16, v4
	v_add3_u32 v9, v26, v9, s70
	v_and_or_b32 v9, v9, s71, v4
	v_or_b32_e32 v4, s0, v43
	v_lshlrev_b32_e32 v4, 12, v4
	v_lshl_add_u64 v[28:29], v[12:13], 0, v[4:5]
	v_bfe_u32 v4, v11, 16, 1
	global_store_dwordx4 v[28:29], v[6:9], off
	v_add3_u32 v4, v11, v4, s70
	v_lshrrev_b32_e32 v4, 16, v4
	v_bfe_u32 v6, v15, 16, 1
	v_add3_u32 v6, v15, v6, s70
	v_and_or_b32 v6, v6, s71, v4
	v_bfe_u32 v4, v17, 16, 1
	v_add3_u32 v4, v17, v4, s70
	v_bfe_u32 v7, v19, 16, 1
	v_lshrrev_b32_e32 v4, 16, v4
	v_add3_u32 v7, v19, v7, s70
	v_and_or_b32 v7, v7, s71, v4
	v_bfe_u32 v4, v21, 16, 1
	v_add3_u32 v4, v21, v4, s70
	v_bfe_u32 v8, v23, 16, 1
	v_lshrrev_b32_e32 v4, 16, v4
	v_add3_u32 v8, v23, v8, s70
	v_and_or_b32 v8, v8, s71, v4
	v_bfe_u32 v4, v25, 16, 1
	v_add3_u32 v4, v25, v4, s70
	v_bfe_u32 v9, v27, 16, 1
	v_lshrrev_b32_e32 v4, 16, v4
	v_add3_u32 v9, v27, v9, s70
	v_and_or_b32 v9, v9, s71, v4
	v_or_b32_e32 v4, s0, v44
	v_lshlrev_b32_e32 v4, 12, v4
	v_lshl_add_u64 v[10:11], v[12:13], 0, v[4:5]
	global_store_dwordx4 v[10:11], v[6:9], off
	s_waitcnt lgkmcnt(0)

; __device__ __forceinline__ void transpose_item(const float* __restrict__ W, int K, int N, bf16_t* __restrict__ WT, int id, const float* __restrict__ gk, LAS float* scr, int item, int nblk, int lane) {
;     const int kb = item / nblk, nb = item % nblk, k0 = 64 * kb, n0 = 32 * nb;
;     const int sc = srccol(id, n0 + (lane & 31));
;     const float* src = W + (size_t)(k0 + (lane >> 5)) * N + (sc < 0 ? 0 : sc);
;     float v[32];
; #pragma unroll
;     for (int i = 0; i < 32; ++i) v[i] = src[(size_t)(2 * i) * N];
;     if (sc < 0) {
; #pragma unroll
;         for (int i = 0; i < 32; ++i) v[i] = 0.f;
;     }
;     if (gk) {
; #pragma unroll
;         for (int i = 0; i < 32; ++i) v[i] *= gk[k0 + 2 * i + (lane >> 5)];
;     }
; #pragma unroll
;     for (int i = 0; i < 32; ++i) scr[(2 * i + (lane >> 5)) * 33 + (lane & 31)] = v[i];
; __device__ __forceinline__ void prologue_phase(const Args& A, LAS unsigned char* lds, int G, const int wv) {
;     ...
;         if (r < I_OUT) { transpose_item(A.w_out + (size_t)l * DM * DM, DM, DM, (bf16_t*)(ws + WS_WOUT) + (size_t)l * DM * DM, 5, nullptr, scr, r, 64, lane); continue; } r -= I_OUT;
.LBB0_64:
	s_andn2_b64 vcc, exec, s[0:1]
	s_cbranch_vccnz .LBB0_66
	s_ashr_i32 s11, s10, 31
	v_readlane_b32 s72, v251, 5
	s_lshl_b64 s[0:1], s[10:11], 24
	v_readlane_b32 s80, v251, 13
	v_readlane_b32 s81, v251, 14
	s_add_u32 s6, s80, s0
	s_addc_u32 s7, s81, s1
	s_lshl_b64 s[0:1], s[10:11], 23
	s_add_u32 s4, s88, s0
	s_addc_u32 s1, s90, s1
	s_add_i32 s0, s17, 0xb400
	s_and_b32 s5, s0, 0xffc0
	s_and_b32 s0, s33, 0x7e0
	v_or_b32_e32 v4, s5, v3
	v_or_b32_e32 v8, s0, v38
	v_lshlrev_b32_e32 v4, 13, v4
	v_lshl_add_u64 v[6:7], s[6:7], 0, v[4:5]
	v_lshlrev_b32_e32 v4, 2, v8
	v_lshl_add_u64 v[6:7], v[6:7], 0, v[4:5]
	v_add_co_u32_e32 v8, vcc, s39, v6
	s_lshl_b32 s5, s5, 1
	s_nop 0
	v_addc_co_u32_e32 v9, vcc, 0, v7, vcc
	v_add_co_u32_e32 v10, vcc, s40, v6
	s_add_u32 s4, s4, s5
	s_nop 0
	v_addc_co_u32_e32 v11, vcc, 0, v7, vcc
	v_add_co_u32_e32 v12, vcc, s41, v6
	s_addc_u32 s5, s1, 0
	s_nop 0
	v_addc_co_u32_e32 v13, vcc, 0, v7, vcc
	v_add_co_u32_e32 v14, vcc, s42, v6
	v_readlane_b32 s73, v251, 6
	s_nop 0
	v_addc_co_u32_e32 v15, vcc, 0, v7, vcc
	v_add_co_u32_e32 v16, vcc, s43, v6
	v_readlane_b32 s74, v251, 7
	s_nop 0
	v_addc_co_u32_e32 v17, vcc, 0, v7, vcc
	v_add_co_u32_e32 v18, vcc, s44, v6
	v_readlane_b32 s75, v251, 8
	s_nop 0
	v_addc_co_u32_e32 v19, vcc, 0, v7, vcc
	v_add_co_u32_e32 v20, vcc, s45, v6
	v_readlane_b32 s76, v251, 9
	s_nop 0
	v_addc_co_u32_e32 v21, vcc, 0, v7, vcc
	global_load_dword v4, v[6:7], off nt
	global_load_dword v24, v[8:9], off nt
	global_load_dword v25, v[10:11], off nt
	global_load_dword v26, v[12:13], off nt
	global_load_dword v27, v[14:15], off nt
	global_load_dword v28, v[16:17], off nt
	global_load_dword v29, v[18:19], off nt
	global_load_dword v30, v[20:21], off nt
	v_add_co_u32_e32 v8, vcc, s46, v6
	v_readlane_b32 s77, v251, 10
	s_nop 0
	v_addc_co_u32_e32 v9, vcc, 0, v7, vcc
	v_add_co_u32_e32 v10, vcc, s47, v6
	v_readlane_b32 s78, v251, 11
	s_nop 0
	v_addc_co_u32_e32 v11, vcc, 0, v7, vcc
	v_add_co_u32_e32 v12, vcc, s48, v6
	v_readlane_b32 s79, v251, 12
	s_nop 0
	v_addc_co_u32_e32 v13, vcc, 0, v7, vcc
	v_add_co_u32_e32 v14, vcc, s49, v6
	v_readlane_b32 s82, v251, 15
	s_nop 0
	v_addc_co_u32_e32 v15, vcc, 0, v7, vcc
	v_add_co_u32_e32 v16, vcc, s50, v6
	v_readlane_b32 s83, v251, 16
	s_nop 0
	v_addc_co_u32_e32 v17, vcc, 0, v7, vcc
	v_add_co_u32_e32 v18, vcc, s51, v6
	v_readlane_b32 s84, v251, 17
	s_nop 0
	v_addc_co_u32_e32 v19, vcc, 0, v7, vcc
	v_add_co_u32_e32 v20, vcc, s52, v6
	v_readlane_b32 s85, v251, 18
	s_nop 0
	v_addc_co_u32_e32 v21, vcc, 0, v7, vcc
	v_add_co_u32_e32 v22, vcc, s53, v6
	v_readlane_b32 s86, v251, 19
	s_nop 0
	v_addc_co_u32_e32 v23, vcc, 0, v7, vcc
	global_load_dword v31, v[8:9], off nt
	global_load_dword v32, v[10:11], off nt
	global_load_dword v33, v[12:13], off nt
	global_load_dword v34, v[14:15], off nt
	global_load_dword v35, v[16:17], off nt
	global_load_dword v36, v[18:19], off nt
	global_load_dword v37, v[20:21], off nt
	global_load_dword v48, v[22:23], off nt
	v_add_co_u32_e32 v8, vcc, s54, v6
	v_readlane_b32 s87, v251, 20
	s_nop 0
	v_addc_co_u32_e32 v9, vcc, 0, v7, vcc
	v_add_co_u32_e32 v10, vcc, s55, v6
	s_nop 1
	v_addc_co_u32_e32 v11, vcc, 0, v7, vcc
	v_add_co_u32_e32 v12, vcc, s56, v6
	s_nop 1
	v_addc_co_u32_e32 v13, vcc, 0, v7, vcc
	v_add_co_u32_e32 v14, vcc, s57, v6
	s_nop 1
	v_addc_co_u32_e32 v15, vcc, 0, v7, vcc
	v_add_co_u32_e32 v16, vcc, s58, v6
	s_nop 1
	v_addc_co_u32_e32 v17, vcc, 0, v7, vcc
	v_add_co_u32_e32 v18, vcc, s59, v6
	s_nop 1
	v_addc_co_u32_e32 v19, vcc, 0, v7, vcc
	v_add_co_u32_e32 v20, vcc, s60, v6
	s_nop 1
	v_addc_co_u32_e32 v21, vcc, 0, v7, vcc
	v_add_co_u32_e32 v22, vcc, s61, v6
	s_nop 1
	v_addc_co_u32_e32 v23, vcc, 0, v7, vcc
	global_load_dword v49, v[8:9], off nt
	global_load_dword v50, v[10:11], off nt
	global_load_dword v51, v[12:13], off nt
	global_load_dword v52, v[14:15], off nt
	global_load_dword v53, v[16:17], off nt
	global_load_dword v54, v[18:19], off nt
	global_load_dword v55, v[20:21], off nt
	s_nop 0
	global_load_dword v22, v[22:23], off nt
	v_add_co_u32_e32 v8, vcc, s62, v6
	s_nop 1
	v_addc_co_u32_e32 v9, vcc, 0, v7, vcc
	v_add_co_u32_e32 v10, vcc, s63, v6
	s_nop 1
	v_addc_co_u32_e32 v11, vcc, 0, v7, vcc
	v_add_co_u32_e32 v12, vcc, s64, v6
	s_nop 1
	v_addc_co_u32_e32 v13, vcc, 0, v7, vcc
	v_add_co_u32_e32 v14, vcc, s65, v6
	s_nop 1
	v_addc_co_u32_e32 v15, vcc, 0, v7, vcc
	v_add_co_u32_e32 v16, vcc, s66, v6
	s_nop 1
	v_addc_co_u32_e32 v17, vcc, 0, v7, vcc
	v_add_co_u32_e32 v18, vcc, s67, v6
	s_nop 1
	v_addc_co_u32_e32 v19, vcc, 0, v7, vcc
	v_add_co_u32_e32 v20, vcc, s68, v6
	s_nop 1
	v_addc_co_u32_e32 v21, vcc, 0, v7, vcc
	v_add_co_u32_e32 v6, vcc, s69, v6
	s_nop 1
	v_addc_co_u32_e32 v7, vcc, 0, v7, vcc
	global_load_dword v8, v[8:9], off nt
	s_nop 0
	global_load_dword v9, v[10:11], off nt
	s_nop 0
	global_load_dword v10, v[12:13], off nt
	global_load_dword v11, v[14:15], off nt
	s_nop 0
	global_load_dword v12, v[16:17], off nt
	global_load_dword v13, v[18:19], off nt
	global_load_dword v14, v[20:21], off nt
	s_nop 0
	global_load_dword v6, v[6:7], off nt
	s_waitcnt vmcnt(30)
	ds_write2_b32 v39, v4, v24 offset1:66
	s_waitcnt vmcnt(28)
	ds_write2_b32 v39, v25, v26 offset0:132 offset1:198
	v_add_u32_e32 v4, 0x400, v39
	s_waitcnt vmcnt(26)
	ds_write2_b32 v4, v27, v28 offset0:8 offset1:74
	s_waitcnt vmcnt(24)
	ds_write2_b32 v4, v29, v30 offset0:140 offset1:206
	v_add_u32_e32 v4, 0x800, v39
	s_waitcnt vmcnt(22)
	ds_write2_b32 v4, v31, v32 offset0:16 offset1:82
	s_waitcnt vmcnt(20)
; #define LAS __attribute__((address_space(3)))
; __device__ __forceinline__ unsigned pk2(float lo, float hi) { return f2bf(lo) | (f2bf(hi) << 16); }
; __device__ __forceinline__ void transpose_item(const float* __restrict__ W, int K, int N, bf16_t* __restrict__ WT, int id, const float* __restrict__ gk, LAS float* scr, int item, int nblk, int lane) {
;     ...
;     for (int i = 0; i < 32; ++i) scr[(2 * i + (lane >> 5)) * 33 + (lane & 31)] = v[i];
;     asm volatile("s_waitcnt lgkmcnt(0)" ::: "memory");
;     const int c = lane & 7;
; #pragma unroll
;     for (int j = 0; j < 4; ++j) { const int n = (lane >> 3) + 8 * j; const LAS float* s = scr + (8 * c) * 33 + n;
;         u32x4 o; o.x = pk2(s[0 * 33], s[1 * 33]); o.y = pk2(s[2 * 33], s[3 * 33]); o.z = pk2(s[4 * 33], s[5 * 33]); o.w = pk2(s[6 * 33], s[7 * 33]);
;         *(u32x4*)(WT + (size_t)(n0 + n) * K + k0 + 8 * c) = o; }
;     asm volatile("s_waitcnt lgkmcnt(0)" ::: "memory");
	ds_write2_b32 v4, v33, v34 offset0:148 offset1:214
	v_add_u32_e32 v4, 0xc00, v39
	s_waitcnt vmcnt(18)
	ds_write2_b32 v4, v35, v36 offset0:24 offset1:90
	s_waitcnt vmcnt(16)
	ds_write2_b32 v4, v37, v48 offset0:156 offset1:222
	v_add_u32_e32 v4, 0x1000, v39
	s_waitcnt vmcnt(14)
	ds_write2_b32 v4, v49, v50 offset0:32 offset1:98
	s_waitcnt vmcnt(12)
	ds_write2_b32 v4, v51, v52 offset0:164 offset1:230
	v_add_u32_e32 v4, 0x1400, v39
	s_waitcnt vmcnt(10)
	ds_write2_b32 v4, v53, v54 offset0:40 offset1:106
	s_waitcnt vmcnt(8)
	ds_write2_b32 v4, v55, v22 offset0:172 offset1:238
	v_add_u32_e32 v4, 0x1800, v39
	s_waitcnt vmcnt(6)
	ds_write2_b32 v4, v8, v9 offset0:48 offset1:114
	s_waitcnt vmcnt(4)
	ds_write2_b32 v4, v10, v11 offset0:180 offset1:246
	v_add_u32_e32 v4, 0x1c00, v39
	s_waitcnt vmcnt(2)
	ds_write2_b32 v4, v12, v13 offset0:56 offset1:122
	s_waitcnt vmcnt(0)
	ds_write2_b32 v4, v14, v6 offset0:188 offset1:254
	s_waitcnt lgkmcnt(0)
	ds_read2_b32 v[10:11], v41 offset1:8
	ds_read2_b32 v[14:15], v41 offset0:33 offset1:41
	ds_read2_b32 v[16:17], v41 offset0:66 offset1:74
	v_lshlrev_b32_e32 v4, 1, v2
	ds_read2_b32 v[18:19], v41 offset0:99 offset1:107
	v_lshl_add_u64 v[12:13], s[4:5], 0, v[4:5]
	s_waitcnt lgkmcnt(3)
	v_bfe_u32 v4, v10, 16, 1
	v_add3_u32 v4, v10, v4, s70
	s_waitcnt lgkmcnt(2)
	v_bfe_u32 v6, v14, 16, 1
	ds_read2_b32 v[20:21], v41 offset0:132 offset1:140
	v_lshrrev_b32_e32 v4, 16, v4
	v_add3_u32 v6, v14, v6, s70
	ds_read2_b32 v[22:23], v41 offset0:165 offset1:173
	v_and_or_b32 v6, v6, s71, v4
	s_waitcnt lgkmcnt(3)
	v_bfe_u32 v4, v16, 16, 1
	v_add3_u32 v4, v16, v4, s70
	s_waitcnt lgkmcnt(2)
	v_bfe_u32 v7, v18, 16, 1
	ds_read2_b32 v[24:25], v41 offset0:198 offset1:206
	v_lshrrev_b32_e32 v4, 16, v4
	v_add3_u32 v7, v18, v7, s70
	ds_read2_b32 v[26:27], v41 offset0:231 offset1:239
	v_and_or_b32 v7, v7, s71, v4
	s_waitcnt lgkmcnt(3)
	v_bfe_u32 v4, v20, 16, 1
	v_add3_u32 v4, v20, v4, s70
	s_waitcnt lgkmcnt(2)
	v_bfe_u32 v8, v22, 16, 1
	v_lshrrev_b32_e32 v4, 16, v4
	v_add3_u32 v8, v22, v8, s70
	v_and_or_b32 v8, v8, s71, v4
	s_waitcnt lgkmcnt(1)
	v_bfe_u32 v4, v24, 16, 1
	v_add3_u32 v4, v24, v4, s70
	s_waitcnt lgkmcnt(0)
	v_bfe_u32 v9, v26, 16, 1
	v_lshrrev_b32_e32 v4, 16, v4
	v_add3_u32 v9, v26, v9, s70
	v_and_or_b32 v9, v9, s71, v4
	v_or_b32_e32 v4, s0, v40
	v_lshlrev_b32_e32 v4, 12, v4
	v_lshl_add_u64 v[28:29], v[12:13], 0, v[4:5]
	v_bfe_u32 v4, v11, 16, 1
	global_store_dwordx4 v[28:29], v[6:9], off
	v_add3_u32 v4, v11, v4, s70
	v_lshrrev_b32_e32 v4, 16, v4
	v_bfe_u32 v6, v15, 16, 1
	v_add3_u32 v6, v15, v6, s70
	v_and_or_b32 v6, v6, s71, v4
	v_bfe_u32 v4, v17, 16, 1
	v_add3_u32 v4, v17, v4, s70
	v_bfe_u32 v7, v19, 16, 1
	v_lshrrev_b32_e32 v4, 16, v4
	v_add3_u32 v7, v19, v7, s70
	v_and_or_b32 v7, v7, s71, v4
	v_bfe_u32 v4, v21, 16, 1
	v_add3_u32 v4, v21, v4, s70
	v_bfe_u32 v8, v23, 16, 1
	v_lshrrev_b32_e32 v4, 16, v4
	v_add3_u32 v8, v23, v8, s70
	v_and_or_b32 v8, v8, s71, v4
	v_bfe_u32 v4, v25, 16, 1
	v_add3_u32 v4, v25, v4, s70
	v_bfe_u32 v9, v27, 16, 1
	v_lshrrev_b32_e32 v4, 16, v4
	v_add3_u32 v9, v27, v9, s70
	v_and_or_b32 v9, v9, s71, v4
	v_or_b32_e32 v4, s0, v42
	v_lshlrev_b32_e32 v4, 12, v4
	ds_read2_b32 v[10:11], v41 offset0:16 offset1:24
	v_lshl_add_u64 v[14:15], v[12:13], 0, v[4:5]
	global_store_dwordx4 v[14:15], v[6:9], off
	ds_read2_b32 v[14:15], v41 offset0:49 offset1:57
	ds_read2_b32 v[16:17], v41 offset0:82 offset1:90
	ds_read2_b32 v[18:19], v41 offset0:115 offset1:123
	s_waitcnt lgkmcnt(3)
	v_bfe_u32 v4, v10, 16, 1
	v_add3_u32 v4, v10, v4, s70
	s_waitcnt lgkmcnt(2)
	v_bfe_u32 v6, v14, 16, 1
	ds_read2_b32 v[20:21], v41 offset0:148 offset1:156
	v_lshrrev_b32_e32 v4, 16, v4
	v_add3_u32 v6, v14, v6, s70
	ds_read2_b32 v[22:23], v41 offset0:181 offset1:189
	v_and_or_b32 v6, v6, s71, v4
	s_waitcnt lgkmcnt(3)
	v_bfe_u32 v4, v16, 16, 1
	v_add3_u32 v4, v16, v4, s70
	s_waitcnt lgkmcnt(2)
	v_bfe_u32 v7, v18, 16, 1
	ds_read2_b32 v[24:25], v41 offset0:214 offset1:222
	v_lshrrev_b32_e32 v4, 16, v4
	v_add3_u32 v7, v18, v7, s70
	ds_read2_b32 v[26:27], v41 offset0:247 offset1:255
	v_and_or_b32 v7, v7, s71, v4
	s_waitcnt lgkmcnt(3)
	v_bfe_u32 v4, v20, 16, 1
	v_add3_u32 v4, v20, v4, s70
	s_waitcnt lgkmcnt(2)
	v_bfe_u32 v8, v22, 16, 1
	v_lshrrev_b32_e32 v4, 16, v4
	v_add3_u32 v8, v22, v8, s70
	v_and_or_b32 v8, v8, s71, v4
	s_waitcnt lgkmcnt(1)
	v_bfe_u32 v4, v24, 16, 1
	v_add3_u32 v4, v24, v4, s70
	s_waitcnt lgkmcnt(0)
	v_bfe_u32 v9, v26, 16, 1
	v_lshrrev_b32_e32 v4, 16, v4
	v_add3_u32 v9, v26, v9, s70
	v_and_or_b32 v9, v9, s71, v4
	v_or_b32_e32 v4, s0, v43
	v_lshlrev_b32_e32 v4, 12, v4
	v_lshl_add_u64 v[28:29], v[12:13], 0, v[4:5]
	v_bfe_u32 v4, v11, 16, 1
	global_store_dwordx4 v[28:29], v[6:9], off
	v_add3_u32 v4, v11, v4, s70
	v_lshrrev_b32_e32 v4, 16, v4
	v_bfe_u32 v6, v15, 16, 1
	v_add3_u32 v6, v15, v6, s70
	v_and_or_b32 v6, v6, s71, v4
	v_bfe_u32 v4, v17, 16, 1
	v_add3_u32 v4, v17, v4, s70
	v_bfe_u32 v7, v19, 16, 1
	v_lshrrev_b32_e32 v4, 16, v4
	v_add3_u32 v7, v19, v7, s70
	v_and_or_b32 v7, v7, s71, v4
	v_bfe_u32 v4, v21, 16, 1
	v_add3_u32 v4, v21, v4, s70
	v_bfe_u32 v8, v23, 16, 1
	v_lshrrev_b32_e32 v4, 16, v4
	v_add3_u32 v8, v23, v8, s70
	v_and_or_b32 v8, v8, s71, v4
	v_bfe_u32 v4, v25, 16, 1
	v_add3_u32 v4, v25, v4, s70
	v_bfe_u32 v9, v27, 16, 1
	v_lshrrev_b32_e32 v4, 16, v4
	v_add3_u32 v9, v27, v9, s70
	v_and_or_b32 v9, v9, s71, v4
	v_or_b32_e32 v4, s0, v44
	v_lshlrev_b32_e32 v4, 12, v4
	v_lshl_add_u64 v[10:11], v[12:13], 0, v[4:5]
	global_store_dwordx4 v[10:11], v[6:9], off
	s_waitcnt lgkmcnt(0)

; __device__ __forceinline__ int srccol(int id, int r) {
;     ...
;         if (r < 768) return r;
;         if (r < 1280) return 832 + (r - 768);
;         if (r < 1792) return 1344 + (r - 1280);
;         if (r < 2304) return 2368 + (r - 1792);
;         if (r < 2816) return 2880 + (r - 2304);
;         r -= 2816;
;         if (r < 64) return 768 + (r >> 1) + (r & 1) * 32;
;         if (r < 72) return 3904 + (r - 64);
;         return -1;
; __device__ __forceinline__ void transpose_item(const float* __restrict__ W, int K, int N, bf16_t* __restrict__ WT, int id, const float* __restrict__ gk, LAS float* scr, int item, int nblk, int lane) {
;     const int kb = item / nblk, nb = item % nblk, k0 = 64 * kb, n0 = 32 * nb;
;     const int sc = srccol(id, n0 + (lane & 31));
;     const float* src = W + (size_t)(k0 + (lane >> 5)) * N + (sc < 0 ? 0 : sc);
;     float v[32];
; #pragma unroll
;     for (int i = 0; i < 32; ++i) v[i] = src[(size_t)(2 * i) * N];
; __device__ __forceinline__ void prologue_phase(const Args& A, LAS unsigned char* lds, int G, const int wv) {
;     ...
;         if (r < I_IN) { transpose_item(A.w_in + (size_t)l * DM * INW, DM, INW, (bf16_t*)(ws + WS_WIN) + (size_t)l * 3072 * DM, 0, nullptr, scr, r, 96, lane); continue; } r -= I_IN;
.LBB0_90:
	v_readlane_b32 s72, v251, 25
	s_mul_i32 s1, s10, 0x1e90000
	v_readlane_b32 s82, v251, 35
	s_mul_hi_i32 s0, s10, 0x1e90000
	v_readlane_b32 s83, v251, 36
	s_add_u32 s6, s82, s1
	s_addc_u32 s7, s83, s0
	s_mul_i32 s1, s10, 0xc00000
	s_mul_hi_i32 s0, s10, 0xc00000
	s_add_u32 s1, s26, s1
	s_addc_u32 s0, s27, s0
	s_lshl_b32 s5, s5, 6
	s_and_b32 s5, s5, 0xffc0
	v_or_b32_e32 v4, s5, v3
	v_mul_u32_u24_e32 v4, 0xf48, v4
	v_lshlrev_b32_e32 v4, 2, v4
	v_lshl_add_u64 v[8:9], s[6:7], 0, v[4:5]
	v_max_i32_e32 v4, 0, v6
	v_lshl_add_u64 v[8:9], v[4:5], 2, v[8:9]
	v_add_co_u32_e32 v10, vcc, s91, v8
	s_mov_b32 s6, 0x16000
	s_nop 0
	v_addc_co_u32_e32 v11, vcc, 0, v9, vcc
	v_add_co_u32_e32 v12, vcc, s9, v8
	s_lshl_b32 s5, s5, 1
	s_nop 0
	v_addc_co_u32_e32 v13, vcc, 0, v9, vcc
	v_add_co_u32_e32 v14, vcc, s6, v8
	s_mov_b32 s6, 0x26000
	s_nop 0
	v_addc_co_u32_e32 v15, vcc, 0, v9, vcc
	v_add_co_u32_e32 v16, vcc, s19, v8
	v_readlane_b32 s73, v251, 26
	s_nop 0
	v_addc_co_u32_e32 v17, vcc, 0, v9, vcc
	v_add_co_u32_e32 v18, vcc, s6, v8
	s_mov_b32 s6, 0x3d000
	s_nop 0
	v_addc_co_u32_e32 v19, vcc, 0, v9, vcc
	v_add_co_u32_e32 v20, vcc, s6, v8
	s_mov_b32 s6, 0x5b000
	s_nop 0
	v_addc_co_u32_e32 v21, vcc, 0, v9, vcc
	v_add_co_u32_e32 v22, vcc, s55, v8
	v_readlane_b32 s74, v251, 27
	s_nop 0
	v_addc_co_u32_e32 v23, vcc, 0, v9, vcc
	v_add_co_u32_e32 v24, vcc, s57, v8
	v_readlane_b32 s75, v251, 28
	s_nop 0
	v_addc_co_u32_e32 v25, vcc, 0, v9, vcc
	v_add_co_u32_e32 v26, vcc, s59, v8
	v_readlane_b32 s76, v251, 29
	s_nop 0
	v_addc_co_u32_e32 v27, vcc, 0, v9, vcc
	v_add_co_u32_e32 v28, vcc, s6, v8
	s_mov_b32 s6, 0x63000
	s_nop 0
	v_addc_co_u32_e32 v29, vcc, 0, v9, vcc
	v_add_co_u32_e32 v30, vcc, s6, v8
	s_mov_b32 s6, 0x6a000
	s_nop 0
	v_addc_co_u32_e32 v31, vcc, 0, v9, vcc
	v_add_co_u32_e32 v32, vcc, s6, v8
	s_mov_b32 s6, 0x72000
	s_nop 0
	v_addc_co_u32_e32 v33, vcc, 0, v9, vcc
	v_add_co_u32_e32 v34, vcc, s6, v8
	s_mov_b32 s6, 0x7a000
	s_nop 0
	v_addc_co_u32_e32 v35, vcc, 0, v9, vcc
	v_add_co_u32_e32 v36, vcc, s6, v8
	s_mov_b32 s6, 0x81000
	s_nop 0
	v_addc_co_u32_e32 v37, vcc, 0, v9, vcc
	v_add_co_u32_e32 v48, vcc, s6, v8
	s_mov_b32 s6, 0x89000
	s_nop 0
	v_addc_co_u32_e32 v49, vcc, 0, v9, vcc
	v_add_co_u32_e32 v50, vcc, s6, v8
	s_mov_b32 s6, 0x91000
	s_nop 0
	v_addc_co_u32_e32 v51, vcc, 0, v9, vcc
	v_add_co_u32_e32 v52, vcc, s6, v8
	s_mov_b32 s6, 0x98000
	s_nop 0
	v_addc_co_u32_e32 v53, vcc, 0, v9, vcc
	v_add_co_u32_e32 v54, vcc, s6, v8
	s_mov_b32 s6, 0xa8000
	s_nop 0
	v_addc_co_u32_e32 v55, vcc, 0, v9, vcc
	v_add_co_u32_e32 v56, vcc, s89, v8
	v_readlane_b32 s77, v251, 30
	s_nop 0
	v_addc_co_u32_e32 v57, vcc, 0, v9, vcc
	v_add_co_u32_e32 v58, vcc, s6, v8
	s_mov_b32 s6, 0xaf000
	s_nop 0
	v_addc_co_u32_e32 v59, vcc, 0, v9, vcc
	v_add_co_u32_e32 v60, vcc, s6, v8
	s_mov_b32 s6, 0x35000
	s_nop 0
	v_addc_co_u32_e32 v61, vcc, 0, v9, vcc
	v_add_co_u32_e32 v62, vcc, s92, v8
	v_readlane_b32 s78, v251, 31
	s_nop 0
	v_addc_co_u32_e32 v63, vcc, 0, v9, vcc
	v_add_co_u32_e32 v64, vcc, s93, v8
	v_readlane_b32 s79, v251, 32
	s_nop 0
	v_addc_co_u32_e32 v65, vcc, 0, v9, vcc
	v_add_co_u32_e32 v66, vcc, s94, v8
	v_readlane_b32 s80, v251, 33
	s_nop 0
	v_addc_co_u32_e32 v67, vcc, 0, v9, vcc
	v_add_co_u32_e32 v68, vcc, s95, v8
	v_readlane_b32 s81, v251, 34
	s_nop 0
	v_addc_co_u32_e32 v69, vcc, 0, v9, vcc
	global_load_dword v4, v[62:63], off offset:1536 nt
	global_load_dword v7, v[64:65], off offset:64 nt
	global_load_dword v70, v[66:67], off offset:2688 nt
	global_load_dword v71, v[68:69], off offset:1216 nt
	v_add_co_u32_e32 v62, vcc, s96, v8
	v_readlane_b32 s84, v251, 37
	s_nop 0
	v_addc_co_u32_e32 v63, vcc, 0, v9, vcc
	v_add_co_u32_e32 v64, vcc, s97, v8
	v_readlane_b32 s85, v251, 38
	s_nop 0
	v_addc_co_u32_e32 v65, vcc, 0, v9, vcc
	v_add_co_u32_e32 v66, vcc, s15, v8
	v_readlane_b32 s86, v251, 39
	s_nop 0
	v_addc_co_u32_e32 v67, vcc, 0, v9, vcc
	v_add_co_u32_e32 v68, vcc, s16, v8
	v_readlane_b32 s87, v251, 40
	s_nop 0
	v_addc_co_u32_e32 v69, vcc, 0, v9, vcc
	global_load_dword v62, v[62:63], off offset:3840 nt
	s_nop 0
	global_load_dword v63, v[64:65], off offset:2368 nt
	s_nop 0
	global_load_dword v64, v[66:67], off offset:896 nt
	global_load_dword v65, v[68:69], off offset:3520 nt
	s_nop 0
	global_load_dword v36, v[36:37], off offset:1024 nt
	s_nop 0
	global_load_dword v37, v[48:49], off offset:3648 nt
	s_nop 0
	global_load_dword v48, v[50:51], off offset:2176 nt
	global_load_dword v49, v[52:53], off offset:704 nt
	s_nop 0
	global_load_dword v50, v[54:55], off offset:3328 nt
	global_load_dword v51, v[56:57], off offset:1856 nt
	global_load_dword v52, v[58:59], off offset:384 nt
	global_load_dword v53, v[60:61], off offset:3008 nt
	s_nop 0
	global_load_dword v54, v[20:21], off offset:512 nt
	global_load_dword v55, v[22:23], off offset:3136 nt
	s_nop 0
	global_load_dword v24, v[24:25], off offset:1664 nt
	s_nop 0
	global_load_dword v25, v[26:27], off offset:192 nt
	s_nop 0
	global_load_dword v26, v[28:29], off offset:2816 nt
	global_load_dword v27, v[30:31], off offset:1344 nt
	s_nop 0
	global_load_dword v28, v[32:33], off offset:3968 nt
	global_load_dword v29, v[34:35], off offset:2496 nt
	v_add_co_u32_e32 v20, vcc, s20, v8
	s_nop 1
	v_addc_co_u32_e32 v21, vcc, 0, v9, vcc
	v_add_co_u32_e32 v22, vcc, s6, v8
	s_add_u32 s6, s1, s5
	s_nop 0
	v_addc_co_u32_e32 v23, vcc, 0, v9, vcc
	global_load_dword v22, v[22:23], off offset:1984 nt
	s_nop 0
	global_load_dword v20, v[20:21], off offset:3456 nt
	s_nop 0
	global_load_dword v18, v[18:19], off offset:832 nt
	s_nop 0
	global_load_dword v16, v[16:17], off offset:2304 nt
	s_nop 0
	global_load_dword v14, v[14:15], off offset:3776 nt
	s_nop 0
	global_load_dword v12, v[12:13], off offset:1152 nt
	s_nop 0
	global_load_dword v10, v[10:11], off offset:2624 nt
	s_nop 0
	global_load_dword v8, v[8:9], off nt
	v_cmp_lt_i32_e32 vcc, -1, v6
	s_addc_u32 s7, s0, 0
	s_waitcnt vmcnt(31)
; #define LAS __attribute__((address_space(3)))
; __device__ __forceinline__ unsigned pk2(float lo, float hi) { return f2bf(lo) | (f2bf(hi) << 16); }
; __device__ __forceinline__ void transpose_item(const float* __restrict__ W, int K, int N, bf16_t* __restrict__ WT, int id, const float* __restrict__ gk, LAS float* scr, int item, int nblk, int lane) {
;     ...
;     if (sc < 0) {
; #pragma unroll
;         for (int i = 0; i < 32; ++i) v[i] = 0.f;
;     }
;     if (gk) {
; #pragma unroll
;         for (int i = 0; i < 32; ++i) v[i] *= gk[k0 + 2 * i + (lane >> 5)];
;     }
; #pragma unroll
;     for (int i = 0; i < 32; ++i) scr[(2 * i + (lane >> 5)) * 33 + (lane & 31)] = v[i];
;     asm volatile("s_waitcnt lgkmcnt(0)" ::: "memory");
;     const int c = lane & 7;
; #pragma unroll
;     for (int j = 0; j < 4; ++j) { const int n = (lane >> 3) + 8 * j; const LAS float* s = scr + (8 * c) * 33 + n;
;         u32x4 o; o.x = pk2(s[0 * 33], s[1 * 33]); o.y = pk2(s[2 * 33], s[3 * 33]); o.z = pk2(s[4 * 33], s[5 * 33]); o.w = pk2(s[6 * 33], s[7 * 33]);
	v_cndmask_b32_e32 v4, 0, v4, vcc
	s_waitcnt vmcnt(30)
	v_cndmask_b32_e32 v7, 0, v7, vcc
	s_waitcnt vmcnt(29)
	v_cndmask_b32_e32 v17, 0, v70, vcc
	s_waitcnt vmcnt(28)
	v_cndmask_b32_e32 v15, 0, v71, vcc
	s_waitcnt vmcnt(27)
	v_cndmask_b32_e32 v13, 0, v62, vcc
	s_waitcnt vmcnt(26)
	v_cndmask_b32_e32 v11, 0, v63, vcc
	s_waitcnt vmcnt(25)
	v_cndmask_b32_e32 v9, 0, v64, vcc
	s_waitcnt vmcnt(24)
	v_cndmask_b32_e32 v6, 0, v65, vcc
	s_waitcnt vmcnt(23)
	v_cndmask_b32_e32 v34, 0, v36, vcc
	s_waitcnt vmcnt(22)
	v_cndmask_b32_e32 v33, 0, v37, vcc
	s_waitcnt vmcnt(21)
	v_cndmask_b32_e32 v32, 0, v48, vcc
	s_waitcnt vmcnt(20)
	v_cndmask_b32_e32 v31, 0, v49, vcc
	s_waitcnt vmcnt(19)
	v_cndmask_b32_e32 v30, 0, v50, vcc
	s_waitcnt vmcnt(18)
	v_cndmask_b32_e32 v23, 0, v51, vcc
	s_waitcnt vmcnt(17)
	v_cndmask_b32_e32 v21, 0, v52, vcc
	s_waitcnt vmcnt(16)
	v_cndmask_b32_e32 v19, 0, v53, vcc
	s_waitcnt vmcnt(15)
	v_cndmask_b32_e32 v36, 0, v54, vcc
	s_waitcnt vmcnt(14)
	v_cndmask_b32_e32 v35, 0, v55, vcc
	s_waitcnt vmcnt(13)
	v_cndmask_b32_e32 v24, 0, v24, vcc
	s_waitcnt vmcnt(12)
	v_cndmask_b32_e32 v25, 0, v25, vcc
	s_waitcnt vmcnt(11)
	v_cndmask_b32_e32 v26, 0, v26, vcc
	s_waitcnt vmcnt(10)
	v_cndmask_b32_e32 v27, 0, v27, vcc
	s_waitcnt vmcnt(9)
	v_cndmask_b32_e32 v28, 0, v28, vcc
	s_waitcnt vmcnt(8)
	v_cndmask_b32_e32 v29, 0, v29, vcc
	s_waitcnt vmcnt(7)
	v_cndmask_b32_e32 v22, 0, v22, vcc
	s_waitcnt vmcnt(6)
	v_cndmask_b32_e32 v20, 0, v20, vcc
	s_waitcnt vmcnt(5)
	v_cndmask_b32_e32 v18, 0, v18, vcc
	s_waitcnt vmcnt(4)
	v_cndmask_b32_e32 v16, 0, v16, vcc
	s_waitcnt vmcnt(3)
	v_cndmask_b32_e32 v14, 0, v14, vcc
	s_waitcnt vmcnt(2)
	v_cndmask_b32_e32 v12, 0, v12, vcc
	s_waitcnt vmcnt(1)
	v_cndmask_b32_e32 v10, 0, v10, vcc
	s_waitcnt vmcnt(0)
	v_cndmask_b32_e32 v8, 0, v8, vcc
	ds_write2_b32 v39, v8, v10 offset1:66
	ds_write2_b32 v39, v12, v14 offset0:132 offset1:198
	v_add_u32_e32 v8, 0x400, v39
	ds_write2_b32 v8, v16, v18 offset0:8 offset1:74
	ds_write2_b32 v8, v20, v22 offset0:140 offset1:206
	v_add_u32_e32 v8, 0x800, v39
	ds_write2_b32 v8, v36, v35 offset0:16 offset1:82
	ds_write2_b32 v8, v24, v25 offset0:148 offset1:214
	v_add_u32_e32 v8, 0xc00, v39
	ds_write2_b32 v8, v26, v27 offset0:24 offset1:90
	ds_write2_b32 v8, v28, v29 offset0:156 offset1:222
	v_add_u32_e32 v8, 0x1000, v39
	ds_write2_b32 v8, v34, v33 offset0:32 offset1:98
	ds_write2_b32 v8, v32, v31 offset0:164 offset1:230
	v_add_u32_e32 v8, 0x1400, v39
	ds_write2_b32 v8, v30, v23 offset0:40 offset1:106
	ds_write2_b32 v8, v21, v19 offset0:172 offset1:238
	v_add_u32_e32 v8, 0x1800, v39
	ds_write2_b32 v8, v4, v7 offset0:48 offset1:114
	ds_write2_b32 v8, v17, v15 offset0:180 offset1:246
	v_add_u32_e32 v4, 0x1c00, v39
	ds_write2_b32 v4, v13, v11 offset0:56 offset1:122
	ds_write2_b32 v4, v9, v6 offset0:188 offset1:254
	s_waitcnt lgkmcnt(0)
	ds_read2_b32 v[10:11], v41 offset1:8
	ds_read2_b32 v[14:15], v41 offset0:33 offset1:41
	ds_read2_b32 v[16:17], v41 offset0:66 offset1:74
	v_lshlrev_b32_e32 v4, 1, v2
	ds_read2_b32 v[18:19], v41 offset0:99 offset1:107
	v_lshl_add_u64 v[12:13], s[6:7], 0, v[4:5]
	s_waitcnt lgkmcnt(3)
	v_bfe_u32 v4, v10, 16, 1
	v_add3_u32 v4, v10, v4, s70
	s_waitcnt lgkmcnt(2)
	v_bfe_u32 v6, v14, 16, 1
	ds_read2_b32 v[20:21], v41 offset0:132 offset1:140
	v_lshrrev_b32_e32 v4, 16, v4
	v_add3_u32 v6, v14, v6, s70
	ds_read2_b32 v[22:23], v41 offset0:165 offset1:173
	v_and_or_b32 v6, v6, s71, v4
	s_waitcnt lgkmcnt(3)
	v_bfe_u32 v4, v16, 16, 1
	v_add3_u32 v4, v16, v4, s70
	s_waitcnt lgkmcnt(2)
	v_bfe_u32 v7, v18, 16, 1
	ds_read2_b32 v[24:25], v41 offset0:198 offset1:206
	v_lshrrev_b32_e32 v4, 16, v4
	v_add3_u32 v7, v18, v7, s70
	ds_read2_b32 v[26:27], v41 offset0:231 offset1:239
	v_and_or_b32 v7, v7, s71, v4
	s_waitcnt lgkmcnt(3)
; #define LAS __attribute__((address_space(3)))
; __device__ __forceinline__ unsigned pk2(float lo, float hi) { return f2bf(lo) | (f2bf(hi) << 16); }
; __device__ __forceinline__ void transpose_item(const float* __restrict__ W, int K, int N, bf16_t* __restrict__ WT, int id, const float* __restrict__ gk, LAS float* scr, int item, int nblk, int lane) {
;     ...
;     for (int j = 0; j < 4; ++j) { const int n = (lane >> 3) + 8 * j; const LAS float* s = scr + (8 * c) * 33 + n;
;         u32x4 o; o.x = pk2(s[0 * 33], s[1 * 33]); o.y = pk2(s[2 * 33], s[3 * 33]); o.z = pk2(s[4 * 33], s[5 * 33]); o.w = pk2(s[6 * 33], s[7 * 33]);
;         *(u32x4*)(WT + (size_t)(n0 + n) * K + k0 + 8 * c) = o; }
;     asm volatile("s_waitcnt lgkmcnt(0)" ::: "memory");
	v_bfe_u32 v4, v20, 16, 1
	v_add3_u32 v4, v20, v4, s70
	s_waitcnt lgkmcnt(2)
	v_bfe_u32 v8, v22, 16, 1
	v_lshrrev_b32_e32 v4, 16, v4
	v_add3_u32 v8, v22, v8, s70
	v_and_or_b32 v8, v8, s71, v4
	s_waitcnt lgkmcnt(1)
	v_bfe_u32 v4, v24, 16, 1
	v_add3_u32 v4, v24, v4, s70
	s_waitcnt lgkmcnt(0)
	v_bfe_u32 v9, v26, 16, 1
	v_lshrrev_b32_e32 v4, 16, v4
	v_add3_u32 v9, v26, v9, s70
	v_and_or_b32 v9, v9, s71, v4
	v_or_b32_e32 v4, s4, v40
	v_lshlrev_b32_e32 v4, 12, v4
	v_lshl_add_u64 v[28:29], v[12:13], 0, v[4:5]
	v_bfe_u32 v4, v11, 16, 1
	global_store_dwordx4 v[28:29], v[6:9], off
	v_add3_u32 v4, v11, v4, s70
	v_lshrrev_b32_e32 v4, 16, v4
	v_bfe_u32 v6, v15, 16, 1
	v_add3_u32 v6, v15, v6, s70
	v_and_or_b32 v6, v6, s71, v4
	v_bfe_u32 v4, v17, 16, 1
	v_add3_u32 v4, v17, v4, s70
	v_bfe_u32 v7, v19, 16, 1
	v_lshrrev_b32_e32 v4, 16, v4
	v_add3_u32 v7, v19, v7, s70
	v_and_or_b32 v7, v7, s71, v4
	v_bfe_u32 v4, v21, 16, 1
	v_add3_u32 v4, v21, v4, s70
	v_bfe_u32 v8, v23, 16, 1
	v_lshrrev_b32_e32 v4, 16, v4
	v_add3_u32 v8, v23, v8, s70
	v_and_or_b32 v8, v8, s71, v4
	v_bfe_u32 v4, v25, 16, 1
	v_add3_u32 v4, v25, v4, s70
	v_bfe_u32 v9, v27, 16, 1
	v_lshrrev_b32_e32 v4, 16, v4
	v_add3_u32 v9, v27, v9, s70
	v_and_or_b32 v9, v9, s71, v4
	v_or_b32_e32 v4, s4, v42
	v_lshlrev_b32_e32 v4, 12, v4
	ds_read2_b32 v[10:11], v41 offset0:16 offset1:24
	v_lshl_add_u64 v[14:15], v[12:13], 0, v[4:5]
	global_store_dwordx4 v[14:15], v[6:9], off
	ds_read2_b32 v[14:15], v41 offset0:49 offset1:57
	ds_read2_b32 v[16:17], v41 offset0:82 offset1:90
	ds_read2_b32 v[18:19], v41 offset0:115 offset1:123
	s_waitcnt lgkmcnt(3)
	v_bfe_u32 v4, v10, 16, 1
	v_add3_u32 v4, v10, v4, s70
	s_waitcnt lgkmcnt(2)
	v_bfe_u32 v6, v14, 16, 1
	ds_read2_b32 v[20:21], v41 offset0:148 offset1:156
	v_lshrrev_b32_e32 v4, 16, v4
	v_add3_u32 v6, v14, v6, s70
	ds_read2_b32 v[22:23], v41 offset0:181 offset1:189
	v_and_or_b32 v6, v6, s71, v4
	s_waitcnt lgkmcnt(3)
	v_bfe_u32 v4, v16, 16, 1
	v_add3_u32 v4, v16, v4, s70
	s_waitcnt lgkmcnt(2)
	v_bfe_u32 v7, v18, 16, 1
	ds_read2_b32 v[24:25], v41 offset0:214 offset1:222
	v_lshrrev_b32_e32 v4, 16, v4
	v_add3_u32 v7, v18, v7, s70
	ds_read2_b32 v[26:27], v41 offset0:247 offset1:255
	v_and_or_b32 v7, v7, s71, v4
	s_waitcnt lgkmcnt(3)
	v_bfe_u32 v4, v20, 16, 1
	v_add3_u32 v4, v20, v4, s70
	s_waitcnt lgkmcnt(2)
	v_bfe_u32 v8, v22, 16, 1
	v_lshrrev_b32_e32 v4, 16, v4
	v_add3_u32 v8, v22, v8, s70
	v_and_or_b32 v8, v8, s71, v4
	s_waitcnt lgkmcnt(1)
	v_bfe_u32 v4, v24, 16, 1
	v_add3_u32 v4, v24, v4, s70
	s_waitcnt lgkmcnt(0)
	v_bfe_u32 v9, v26, 16, 1
	v_lshrrev_b32_e32 v4, 16, v4
	v_add3_u32 v9, v26, v9, s70
	v_and_or_b32 v9, v9, s71, v4
	v_or_b32_e32 v4, s4, v43
	v_lshlrev_b32_e32 v4, 12, v4
	v_lshl_add_u64 v[28:29], v[12:13], 0, v[4:5]
	v_bfe_u32 v4, v11, 16, 1
	global_store_dwordx4 v[28:29], v[6:9], off
	v_add3_u32 v4, v11, v4, s70
	v_lshrrev_b32_e32 v4, 16, v4
	v_bfe_u32 v6, v15, 16, 1
	v_add3_u32 v6, v15, v6, s70
	v_and_or_b32 v6, v6, s71, v4
	v_bfe_u32 v4, v17, 16, 1
	v_add3_u32 v4, v17, v4, s70
	v_bfe_u32 v7, v19, 16, 1
	v_lshrrev_b32_e32 v4, 16, v4
	v_add3_u32 v7, v19, v7, s70
	v_and_or_b32 v7, v7, s71, v4
	v_bfe_u32 v4, v21, 16, 1
	v_add3_u32 v4, v21, v4, s70
	v_bfe_u32 v8, v23, 16, 1
	v_lshrrev_b32_e32 v4, 16, v4
	v_add3_u32 v8, v23, v8, s70
	v_and_or_b32 v8, v8, s71, v4
	v_bfe_u32 v4, v25, 16, 1
	v_add3_u32 v4, v25, v4, s70
	v_bfe_u32 v9, v27, 16, 1
	v_lshrrev_b32_e32 v4, 16, v4
	v_add3_u32 v9, v27, v9, s70
	v_and_or_b32 v9, v9, s71, v4
	v_or_b32_e32 v4, s4, v44
	v_lshlrev_b32_e32 v4, 12, v4
	v_lshl_add_u64 v[10:11], v[12:13], 0, v[4:5]
	global_store_dwordx4 v[10:11], v[6:9], off
	s_waitcnt lgkmcnt(0)

; __device__ __forceinline__ void transpose_item(const float* __restrict__ W, int K, int N, bf16_t* __restrict__ WT, int id, const float* __restrict__ gk, LAS float* scr, int item, int nblk, int lane) {
;     const int kb = item / nblk, nb = item % nblk, k0 = 64 * kb, n0 = 32 * nb;
;     const int sc = srccol(id, n0 + (lane & 31));
;     const float* src = W + (size_t)(k0 + (lane >> 5)) * N + (sc < 0 ? 0 : sc);
;     float v[32];
; #pragma unroll
;     for (int i = 0; i < 32; ++i) v[i] = src[(size_t)(2 * i) * N];
;     if (sc < 0) {
; #pragma unroll
;         for (int i = 0; i < 32; ++i) v[i] = 0.f;
;     }
;     if (gk) {
; #pragma unroll
;         for (int i = 0; i < 32; ++i) v[i] *= gk[k0 + 2 * i + (lane >> 5)];
;     }
; #pragma unroll
;     for (int i = 0; i < 32; ++i) scr[(2 * i + (lane >> 5)) * 33 + (lane & 31)] = v[i];
; __device__ __forceinline__ void prologue_phase(const Args& A, LAS unsigned char* lds, int G, const int wv) {
;     ...
;         if (r < I_2) { transpose_item(A.w_ff2 + (size_t)l * DFF * DM, DFF, DM, (bf16_t*)(ws + WS_W2) + (size_t)l * DM * DFF, 5, nullptr, scr, r, 64, lane); continue; } r -= I_2;
.LBB0_92:
	s_andn2_b64 vcc, exec, s[0:1]
	s_cbranch_vccnz .LBB0_94
	s_ashr_i32 s11, s10, 31
	v_readlane_b32 s72, v251, 5
	s_lshl_b64 s[0:1], s[10:11], 26
	v_readlane_b32 s86, v251, 19
	v_readlane_b32 s87, v251, 20
	s_add_u32 s6, s86, s0
	s_addc_u32 s7, s87, s1
	s_lshl_b64 s[0:1], s[10:11], 25
	s_add_u32 s4, s28, s0
	s_addc_u32 s1, s29, s1
	s_add_i32 s0, s17, 0xe000
	s_and_b32 s5, s0, 0xffc0
	s_and_b32 s0, s33, 0x7e0
	v_or_b32_e32 v4, s5, v3
	v_or_b32_e32 v8, s0, v38
	v_lshlrev_b32_e32 v4, 13, v4
	v_lshl_add_u64 v[6:7], s[6:7], 0, v[4:5]
	v_lshlrev_b32_e32 v4, 2, v8
	v_lshl_add_u64 v[6:7], v[6:7], 0, v[4:5]
	v_add_co_u32_e32 v8, vcc, s39, v6
	s_lshl_b32 s5, s5, 1
	s_nop 0
	v_addc_co_u32_e32 v9, vcc, 0, v7, vcc
	v_add_co_u32_e32 v10, vcc, s40, v6
	s_add_u32 s4, s4, s5
	s_nop 0
	v_addc_co_u32_e32 v11, vcc, 0, v7, vcc
	v_add_co_u32_e32 v12, vcc, s41, v6
	s_addc_u32 s5, s1, 0
	s_nop 0
	v_addc_co_u32_e32 v13, vcc, 0, v7, vcc
	v_add_co_u32_e32 v14, vcc, s42, v6
	v_readlane_b32 s73, v251, 6
	s_nop 0
	v_addc_co_u32_e32 v15, vcc, 0, v7, vcc
	v_add_co_u32_e32 v16, vcc, s43, v6
	v_readlane_b32 s74, v251, 7
	s_nop 0
	v_addc_co_u32_e32 v17, vcc, 0, v7, vcc
	v_add_co_u32_e32 v18, vcc, s44, v6
	v_readlane_b32 s75, v251, 8
	s_nop 0
	v_addc_co_u32_e32 v19, vcc, 0, v7, vcc
	v_add_co_u32_e32 v20, vcc, s45, v6
	v_readlane_b32 s76, v251, 9
	s_nop 0
	v_addc_co_u32_e32 v21, vcc, 0, v7, vcc
	global_load_dword v4, v[6:7], off nt
	global_load_dword v24, v[8:9], off nt
	global_load_dword v25, v[10:11], off nt
	global_load_dword v26, v[12:13], off nt
	global_load_dword v27, v[14:15], off nt
	global_load_dword v28, v[16:17], off nt
	global_load_dword v29, v[18:19], off nt
	global_load_dword v30, v[20:21], off nt
	v_add_co_u32_e32 v8, vcc, s46, v6
	v_readlane_b32 s77, v251, 10
	s_nop 0
	v_addc_co_u32_e32 v9, vcc, 0, v7, vcc
	v_add_co_u32_e32 v10, vcc, s47, v6
	v_readlane_b32 s78, v251, 11
	s_nop 0
	v_addc_co_u32_e32 v11, vcc, 0, v7, vcc
	v_add_co_u32_e32 v12, vcc, s48, v6
	v_readlane_b32 s79, v251, 12
	s_nop 0
	v_addc_co_u32_e32 v13, vcc, 0, v7, vcc
	v_add_co_u32_e32 v14, vcc, s49, v6
	v_readlane_b32 s80, v251, 13
	s_nop 0
	v_addc_co_u32_e32 v15, vcc, 0, v7, vcc
	v_add_co_u32_e32 v16, vcc, s50, v6
	v_readlane_b32 s81, v251, 14
	s_nop 0
	v_addc_co_u32_e32 v17, vcc, 0, v7, vcc
	v_add_co_u32_e32 v18, vcc, s51, v6
	v_readlane_b32 s82, v251, 15
	s_nop 0
	v_addc_co_u32_e32 v19, vcc, 0, v7, vcc
	v_add_co_u32_e32 v20, vcc, s52, v6
	v_readlane_b32 s83, v251, 16
	s_nop 0
	v_addc_co_u32_e32 v21, vcc, 0, v7, vcc
	v_add_co_u32_e32 v22, vcc, s53, v6
	v_readlane_b32 s84, v251, 17
	s_nop 0
	v_addc_co_u32_e32 v23, vcc, 0, v7, vcc
	global_load_dword v31, v[8:9], off nt
	global_load_dword v32, v[10:11], off nt
	global_load_dword v33, v[12:13], off nt
	global_load_dword v34, v[14:15], off nt
	global_load_dword v35, v[16:17], off nt
	global_load_dword v36, v[18:19], off nt
	global_load_dword v37, v[20:21], off nt
	global_load_dword v48, v[22:23], off nt
	v_add_co_u32_e32 v8, vcc, s54, v6
	v_readlane_b32 s85, v251, 18
	s_nop 0
	v_addc_co_u32_e32 v9, vcc, 0, v7, vcc
	v_add_co_u32_e32 v10, vcc, s55, v6
	s_nop 1
	v_addc_co_u32_e32 v11, vcc, 0, v7, vcc
	v_add_co_u32_e32 v12, vcc, s56, v6
	s_nop 1
	v_addc_co_u32_e32 v13, vcc, 0, v7, vcc
	v_add_co_u32_e32 v14, vcc, s57, v6
	s_nop 1
	v_addc_co_u32_e32 v15, vcc, 0, v7, vcc
	v_add_co_u32_e32 v16, vcc, s58, v6
	s_nop 1
	v_addc_co_u32_e32 v17, vcc, 0, v7, vcc
	v_add_co_u32_e32 v18, vcc, s59, v6
	s_nop 1
	v_addc_co_u32_e32 v19, vcc, 0, v7, vcc
	v_add_co_u32_e32 v20, vcc, s60, v6
	s_nop 1
	v_addc_co_u32_e32 v21, vcc, 0, v7, vcc
	v_add_co_u32_e32 v22, vcc, s61, v6
	s_nop 1
	v_addc_co_u32_e32 v23, vcc, 0, v7, vcc
	global_load_dword v49, v[8:9], off nt
	global_load_dword v50, v[10:11], off nt
	global_load_dword v51, v[12:13], off nt
	global_load_dword v52, v[14:15], off nt
	global_load_dword v53, v[16:17], off nt
	global_load_dword v54, v[18:19], off nt
	global_load_dword v55, v[20:21], off nt
	s_nop 0
	global_load_dword v22, v[22:23], off nt
	v_add_co_u32_e32 v8, vcc, s62, v6
	s_nop 1
	v_addc_co_u32_e32 v9, vcc, 0, v7, vcc
	v_add_co_u32_e32 v10, vcc, s63, v6
	s_nop 1
	v_addc_co_u32_e32 v11, vcc, 0, v7, vcc
	v_add_co_u32_e32 v12, vcc, s64, v6
	s_nop 1
	v_addc_co_u32_e32 v13, vcc, 0, v7, vcc
	v_add_co_u32_e32 v14, vcc, s65, v6
	s_nop 1
	v_addc_co_u32_e32 v15, vcc, 0, v7, vcc
	v_add_co_u32_e32 v16, vcc, s66, v6
	s_nop 1
	v_addc_co_u32_e32 v17, vcc, 0, v7, vcc
	v_add_co_u32_e32 v18, vcc, s67, v6
	s_nop 1
	v_addc_co_u32_e32 v19, vcc, 0, v7, vcc
	v_add_co_u32_e32 v20, vcc, s68, v6
	s_nop 1
	v_addc_co_u32_e32 v21, vcc, 0, v7, vcc
	v_add_co_u32_e32 v6, vcc, s69, v6
	s_nop 1
	v_addc_co_u32_e32 v7, vcc, 0, v7, vcc
	global_load_dword v8, v[8:9], off nt
	s_nop 0
	global_load_dword v9, v[10:11], off nt
	s_nop 0
	global_load_dword v10, v[12:13], off nt
	global_load_dword v11, v[14:15], off nt
	s_nop 0
	global_load_dword v12, v[16:17], off nt
	global_load_dword v13, v[18:19], off nt
	global_load_dword v14, v[20:21], off nt
	s_nop 0
	global_load_dword v6, v[6:7], off nt
	s_waitcnt vmcnt(30)
	ds_write2_b32 v39, v4, v24 offset1:66
	s_waitcnt vmcnt(28)
	ds_write2_b32 v39, v25, v26 offset0:132 offset1:198
	v_add_u32_e32 v4, 0x400, v39
	s_waitcnt vmcnt(26)
	ds_write2_b32 v4, v27, v28 offset0:8 offset1:74
	s_waitcnt vmcnt(24)
	ds_write2_b32 v4, v29, v30 offset0:140 offset1:206
	v_add_u32_e32 v4, 0x800, v39
	s_waitcnt vmcnt(22)
	ds_write2_b32 v4, v31, v32 offset0:16 offset1:82
	s_waitcnt vmcnt(20)
; #define LAS __attribute__((address_space(3)))
; __device__ __forceinline__ unsigned pk2(float lo, float hi) { return f2bf(lo) | (f2bf(hi) << 16); }
; __device__ __forceinline__ void transpose_item(const float* __restrict__ W, int K, int N, bf16_t* __restrict__ WT, int id, const float* __restrict__ gk, LAS float* scr, int item, int nblk, int lane) {
;     ...
;     for (int i = 0; i < 32; ++i) scr[(2 * i + (lane >> 5)) * 33 + (lane & 31)] = v[i];
;     asm volatile("s_waitcnt lgkmcnt(0)" ::: "memory");
;     const int c = lane & 7;
; #pragma unroll
;     for (int j = 0; j < 4; ++j) { const int n = (lane >> 3) + 8 * j; const LAS float* s = scr + (8 * c) * 33 + n;
;         u32x4 o; o.x = pk2(s[0 * 33], s[1 * 33]); o.y = pk2(s[2 * 33], s[3 * 33]); o.z = pk2(s[4 * 33], s[5 * 33]); o.w = pk2(s[6 * 33], s[7 * 33]);
;         *(u32x4*)(WT + (size_t)(n0 + n) * K + k0 + 8 * c) = o; }
;     asm volatile("s_waitcnt lgkmcnt(0)" ::: "memory");
	ds_write2_b32 v4, v33, v34 offset0:148 offset1:214
	v_add_u32_e32 v4, 0xc00, v39
	s_waitcnt vmcnt(18)
	ds_write2_b32 v4, v35, v36 offset0:24 offset1:90
	s_waitcnt vmcnt(16)
	ds_write2_b32 v4, v37, v48 offset0:156 offset1:222
	v_add_u32_e32 v4, 0x1000, v39
	s_waitcnt vmcnt(14)
	ds_write2_b32 v4, v49, v50 offset0:32 offset1:98
	s_waitcnt vmcnt(12)
	ds_write2_b32 v4, v51, v52 offset0:164 offset1:230
	v_add_u32_e32 v4, 0x1400, v39
	s_waitcnt vmcnt(10)
	ds_write2_b32 v4, v53, v54 offset0:40 offset1:106
	s_waitcnt vmcnt(8)
	ds_write2_b32 v4, v55, v22 offset0:172 offset1:238
	v_add_u32_e32 v4, 0x1800, v39
	s_waitcnt vmcnt(6)
	ds_write2_b32 v4, v8, v9 offset0:48 offset1:114
	s_waitcnt vmcnt(4)
	ds_write2_b32 v4, v10, v11 offset0:180 offset1:246
	v_add_u32_e32 v4, 0x1c00, v39
	s_waitcnt vmcnt(2)
	ds_write2_b32 v4, v12, v13 offset0:56 offset1:122
	s_waitcnt vmcnt(0)
	ds_write2_b32 v4, v14, v6 offset0:188 offset1:254
	s_waitcnt lgkmcnt(0)
	ds_read2_b32 v[10:11], v41 offset1:8
	ds_read2_b32 v[14:15], v41 offset0:33 offset1:41
	ds_read2_b32 v[16:17], v41 offset0:66 offset1:74
	v_lshlrev_b32_e32 v4, 1, v2
	ds_read2_b32 v[18:19], v41 offset0:99 offset1:107
	v_lshl_add_u64 v[12:13], s[4:5], 0, v[4:5]
	s_waitcnt lgkmcnt(3)
	v_bfe_u32 v4, v10, 16, 1
	v_add3_u32 v4, v10, v4, s70
	s_waitcnt lgkmcnt(2)
	v_bfe_u32 v6, v14, 16, 1
	ds_read2_b32 v[20:21], v41 offset0:132 offset1:140
	v_lshrrev_b32_e32 v4, 16, v4
	v_add3_u32 v6, v14, v6, s70
	ds_read2_b32 v[22:23], v41 offset0:165 offset1:173
	v_and_or_b32 v6, v6, s71, v4
	s_waitcnt lgkmcnt(3)
	v_bfe_u32 v4, v16, 16, 1
	v_add3_u32 v4, v16, v4, s70
	s_waitcnt lgkmcnt(2)
	v_bfe_u32 v7, v18, 16, 1
	ds_read2_b32 v[24:25], v41 offset0:198 offset1:206
	v_lshrrev_b32_e32 v4, 16, v4
	v_add3_u32 v7, v18, v7, s70
	ds_read2_b32 v[26:27], v41 offset0:231 offset1:239
	v_and_or_b32 v7, v7, s71, v4
	s_waitcnt lgkmcnt(3)
	v_bfe_u32 v4, v20, 16, 1
	v_add3_u32 v4, v20, v4, s70
	s_waitcnt lgkmcnt(2)
	v_bfe_u32 v8, v22, 16, 1
	v_lshrrev_b32_e32 v4, 16, v4
	v_add3_u32 v8, v22, v8, s70
	v_and_or_b32 v8, v8, s71, v4
	s_waitcnt lgkmcnt(1)
	v_bfe_u32 v4, v24, 16, 1
	v_add3_u32 v4, v24, v4, s70
	s_waitcnt lgkmcnt(0)
	v_bfe_u32 v9, v26, 16, 1
	v_lshrrev_b32_e32 v4, 16, v4
	v_add3_u32 v9, v26, v9, s70
	v_and_or_b32 v9, v9, s71, v4
	v_or_b32_e32 v4, s0, v40
	v_lshlrev_b32_e32 v4, 14, v4
	v_lshl_add_u64 v[28:29], v[12:13], 0, v[4:5]
	v_bfe_u32 v4, v11, 16, 1
	global_store_dwordx4 v[28:29], v[6:9], off
	v_add3_u32 v4, v11, v4, s70
	v_lshrrev_b32_e32 v4, 16, v4
	v_bfe_u32 v6, v15, 16, 1
	v_add3_u32 v6, v15, v6, s70
	v_and_or_b32 v6, v6, s71, v4
	v_bfe_u32 v4, v17, 16, 1
	v_add3_u32 v4, v17, v4, s70
	v_bfe_u32 v7, v19, 16, 1
	v_lshrrev_b32_e32 v4, 16, v4
	v_add3_u32 v7, v19, v7, s70
	v_and_or_b32 v7, v7, s71, v4
	v_bfe_u32 v4, v21, 16, 1
	v_add3_u32 v4, v21, v4, s70
	v_bfe_u32 v8, v23, 16, 1
	v_lshrrev_b32_e32 v4, 16, v4
	v_add3_u32 v8, v23, v8, s70
	v_and_or_b32 v8, v8, s71, v4
	v_bfe_u32 v4, v25, 16, 1
	v_add3_u32 v4, v25, v4, s70
	v_bfe_u32 v9, v27, 16, 1
	v_lshrrev_b32_e32 v4, 16, v4
	v_add3_u32 v9, v27, v9, s70
	v_and_or_b32 v9, v9, s71, v4
	v_or_b32_e32 v4, s0, v42
	v_lshlrev_b32_e32 v4, 14, v4
	ds_read2_b32 v[10:11], v41 offset0:16 offset1:24
	v_lshl_add_u64 v[14:15], v[12:13], 0, v[4:5]
	global_store_dwordx4 v[14:15], v[6:9], off
	ds_read2_b32 v[14:15], v41 offset0:49 offset1:57
	ds_read2_b32 v[16:17], v41 offset0:82 offset1:90
	ds_read2_b32 v[18:19], v41 offset0:115 offset1:123
	s_waitcnt lgkmcnt(3)
	v_bfe_u32 v4, v10, 16, 1
	v_add3_u32 v4, v10, v4, s70
	s_waitcnt lgkmcnt(2)
	v_bfe_u32 v6, v14, 16, 1
	ds_read2_b32 v[20:21], v41 offset0:148 offset1:156
	v_lshrrev_b32_e32 v4, 16, v4
	v_add3_u32 v6, v14, v6, s70
	ds_read2_b32 v[22:23], v41 offset0:181 offset1:189
	v_and_or_b32 v6, v6, s71, v4
	s_waitcnt lgkmcnt(3)
	v_bfe_u32 v4, v16, 16, 1
	v_add3_u32 v4, v16, v4, s70
	s_waitcnt lgkmcnt(2)
	v_bfe_u32 v7, v18, 16, 1
	ds_read2_b32 v[24:25], v41 offset0:214 offset1:222
	v_lshrrev_b32_e32 v4, 16, v4
	v_add3_u32 v7, v18, v7, s70
	ds_read2_b32 v[26:27], v41 offset0:247 offset1:255
	v_and_or_b32 v7, v7, s71, v4
	s_waitcnt lgkmcnt(3)
	v_bfe_u32 v4, v20, 16, 1
	v_add3_u32 v4, v20, v4, s70
	s_waitcnt lgkmcnt(2)
	v_bfe_u32 v8, v22, 16, 1
	v_lshrrev_b32_e32 v4, 16, v4
	v_add3_u32 v8, v22, v8, s70
	v_and_or_b32 v8, v8, s71, v4
	s_waitcnt lgkmcnt(1)
	v_bfe_u32 v4, v24, 16, 1
	v_add3_u32 v4, v24, v4, s70
	s_waitcnt lgkmcnt(0)
	v_bfe_u32 v9, v26, 16, 1
	v_lshrrev_b32_e32 v4, 16, v4
	v_add3_u32 v9, v26, v9, s70
	v_and_or_b32 v9, v9, s71, v4
	v_or_b32_e32 v4, s0, v43
	v_lshlrev_b32_e32 v4, 14, v4
	v_lshl_add_u64 v[28:29], v[12:13], 0, v[4:5]
	v_bfe_u32 v4, v11, 16, 1
	global_store_dwordx4 v[28:29], v[6:9], off
	v_add3_u32 v4, v11, v4, s70
	v_lshrrev_b32_e32 v4, 16, v4
	v_bfe_u32 v6, v15, 16, 1
	v_add3_u32 v6, v15, v6, s70
	v_and_or_b32 v6, v6, s71, v4
	v_bfe_u32 v4, v17, 16, 1
	v_add3_u32 v4, v17, v4, s70
	v_bfe_u32 v7, v19, 16, 1
	v_lshrrev_b32_e32 v4, 16, v4
	v_add3_u32 v7, v19, v7, s70
	v_and_or_b32 v7, v7, s71, v4
	v_bfe_u32 v4, v21, 16, 1
	v_add3_u32 v4, v21, v4, s70
	v_bfe_u32 v8, v23, 16, 1
	v_lshrrev_b32_e32 v4, 16, v4
	v_add3_u32 v8, v23, v8, s70
	v_and_or_b32 v8, v8, s71, v4
	v_bfe_u32 v4, v25, 16, 1
	v_add3_u32 v4, v25, v4, s70
	v_bfe_u32 v9, v27, 16, 1
	v_lshrrev_b32_e32 v4, 16, v4
	v_add3_u32 v9, v27, v9, s70
	v_and_or_b32 v9, v9, s71, v4
	v_or_b32_e32 v4, s0, v44
	v_lshlrev_b32_e32 v4, 14, v4
	v_lshl_add_u64 v[10:11], v[12:13], 0, v[4:5]
	global_store_dwordx4 v[10:11], v[6:9], off
	s_waitcnt lgkmcnt(0)

; __device__ __forceinline__ void transpose_item(const float* __restrict__ W, int K, int N, bf16_t* __restrict__ WT, int id, const float* __restrict__ gk, LAS float* scr, int item, int nblk, int lane) {
;     const int kb = item / nblk, nb = item % nblk, k0 = 64 * kb, n0 = 32 * nb;
;     const int sc = srccol(id, n0 + (lane & 31));
;     const float* src = W + (size_t)(k0 + (lane >> 5)) * N + (sc < 0 ? 0 : sc);
;     float v[32];
; #pragma unroll
;     for (int i = 0; i < 32; ++i) v[i] = src[(size_t)(2 * i) * N];
; __device__ __forceinline__ void prologue_phase(const Args& A, LAS unsigned char* lds, int G, const int wv) {
;     ...
;         if (r < I_1) { transpose_item(A.w_ff1 + (size_t)l * DM * DFF, DM, DFF, (bf16_t*)(ws + WS_W1) + (size_t)l * DFF * DM, 5, nullptr, scr, r, 256, lane); continue; } r -= I_1;
.LBB0_95:
	s_andn2_b64 vcc, exec, s[0:1]
	s_cbranch_vccnz .LBB0_39
	s_ashr_i32 s11, s10, 31
	v_readlane_b32 s72, v251, 5
	s_lshl_b64 s[0:1], s[10:11], 26
	v_readlane_b32 s84, v251, 17
	v_readlane_b32 s85, v251, 18
	s_add_u32 s12, s84, s0
	s_addc_u32 s13, s85, s1
	s_lshl_b64 s[0:1], s[10:11], 25
	s_add_u32 s6, s30, s0
	s_addc_u32 s5, s31, s1
	s_bfe_u32 s0, s17, 0x80017
	s_add_i32 s0, s17, s0
	s_sext_i32_i16 s1, s0
	s_and_b32 s0, s0, 0xff00
	s_ashr_i32 s4, s1, 8
	s_sub_i32 s0, s17, s0
	s_sext_i32_i16 s1, s0
	s_lshl_b32 s0, s4, 6
	s_lshl_b32 s4, s1, 5
	v_or_b32_e32 v6, s0, v3
	v_or_b32_e32 v4, s4, v38
	v_ashrrev_i32_e32 v7, 31, v6
	v_lshlrev_b64 v[6:7], 15, v[6:7]
	v_max_i32_e32 v4, 0, v4
	v_lshl_add_u64 v[6:7], s[12:13], 0, v[6:7]
	v_lshlrev_b32_e32 v4, 2, v4
	v_lshl_add_u64 v[6:7], v[6:7], 0, v[4:5]
	v_add_co_u32_e32 v8, vcc, s42, v6
	s_mov_b32 s7, 0x80000
	s_nop 0
	v_addc_co_u32_e32 v9, vcc, 0, v7, vcc
	v_add_co_u32_e32 v10, vcc, s46, v6
	s_cmp_gt_i32 s1, -1
	s_nop 0
	v_addc_co_u32_e32 v11, vcc, 0, v7, vcc
	v_add_co_u32_e32 v12, vcc, s50, v6
	v_readlane_b32 s73, v251, 6
	s_nop 0
	v_addc_co_u32_e32 v13, vcc, 0, v7, vcc
	v_add_co_u32_e32 v14, vcc, s54, v6
	v_readlane_b32 s74, v251, 7
	s_nop 0
	v_addc_co_u32_e32 v15, vcc, 0, v7, vcc
	v_add_co_u32_e32 v16, vcc, s58, v6
	v_readlane_b32 s75, v251, 8
	s_nop 0
	v_addc_co_u32_e32 v17, vcc, 0, v7, vcc
	v_add_co_u32_e32 v18, vcc, s7, v6
	s_mov_b32 s7, 0x90000
	s_nop 0
	v_addc_co_u32_e32 v19, vcc, 0, v7, vcc
	v_add_co_u32_e32 v20, vcc, s7, v6
	s_mov_b32 s7, 0xb0000
	s_nop 0
	v_addc_co_u32_e32 v21, vcc, 0, v7, vcc
	v_add_co_u32_e32 v22, vcc, s89, v6
	v_readlane_b32 s76, v251, 9
	s_nop 0
	v_addc_co_u32_e32 v23, vcc, 0, v7, vcc
	v_add_co_u32_e32 v24, vcc, s7, v6
	s_mov_b32 s7, 0xc0000
	s_nop 0
	v_addc_co_u32_e32 v25, vcc, 0, v7, vcc
	v_add_co_u32_e32 v26, vcc, s7, v6
	s_mov_b32 s7, 0xd0000
	s_nop 0
	v_addc_co_u32_e32 v27, vcc, 0, v7, vcc
	v_add_co_u32_e32 v28, vcc, s7, v6
	s_mov_b32 s7, 0xe0000
	s_nop 0
	v_addc_co_u32_e32 v29, vcc, 0, v7, vcc
	v_add_co_u32_e32 v30, vcc, s7, v6
	s_mov_b32 s7, 0xf0000
	s_nop 0
	v_addc_co_u32_e32 v31, vcc, 0, v7, vcc
	v_add_co_u32_e32 v32, vcc, s7, v6
	s_mov_b32 s7, 0x100000
	s_nop 0
	v_addc_co_u32_e32 v33, vcc, 0, v7, vcc
	v_add_co_u32_e32 v34, vcc, s7, v6
	s_mov_b32 s7, 0x110000
	s_nop 0
	v_addc_co_u32_e32 v35, vcc, 0, v7, vcc
	v_add_co_u32_e32 v36, vcc, s7, v6
	s_mov_b32 s7, 0x120000
	s_nop 0
	v_addc_co_u32_e32 v37, vcc, 0, v7, vcc
	v_add_co_u32_e32 v48, vcc, s7, v6
	s_mov_b32 s7, 0x130000
	s_nop 0
	v_addc_co_u32_e32 v49, vcc, 0, v7, vcc
	v_add_co_u32_e32 v50, vcc, s7, v6
	s_mov_b32 s7, 0x140000
	s_nop 0
	v_addc_co_u32_e32 v51, vcc, 0, v7, vcc
	v_add_co_u32_e32 v52, vcc, s7, v6
	s_mov_b32 s7, 0x150000
	s_nop 0
	v_addc_co_u32_e32 v53, vcc, 0, v7, vcc
	v_add_co_u32_e32 v54, vcc, s7, v6
	s_mov_b32 s7, 0x160000
	s_nop 0
	v_addc_co_u32_e32 v55, vcc, 0, v7, vcc
	v_add_co_u32_e32 v56, vcc, s7, v6
	s_mov_b32 s7, 0x170000
	s_nop 0
	v_addc_co_u32_e32 v57, vcc, 0, v7, vcc
	v_add_co_u32_e32 v58, vcc, s7, v6
	s_mov_b32 s7, 0x180000
	s_nop 0
	v_addc_co_u32_e32 v59, vcc, 0, v7, vcc
	v_add_co_u32_e32 v60, vcc, s7, v6
	s_mov_b32 s7, 0x190000
	s_nop 0
	v_addc_co_u32_e32 v61, vcc, 0, v7, vcc
	v_add_co_u32_e32 v62, vcc, s7, v6
	s_mov_b32 s7, 0x1a0000
	s_nop 0
	v_addc_co_u32_e32 v63, vcc, 0, v7, vcc
	v_add_co_u32_e32 v64, vcc, s7, v6
	s_mov_b32 s7, 0x1b0000
	s_nop 0
	v_addc_co_u32_e32 v65, vcc, 0, v7, vcc
	v_add_co_u32_e32 v66, vcc, s7, v6
	s_mov_b32 s7, 0x1c0000
	s_nop 0
	v_addc_co_u32_e32 v67, vcc, 0, v7, vcc
	global_load_dword v4, v[60:61], off nt
	global_load_dword v68, v[62:63], off nt
	global_load_dword v69, v[64:65], off nt
	global_load_dword v70, v[66:67], off nt
	v_add_co_u32_e32 v60, vcc, s7, v6
	s_mov_b32 s7, 0x1d0000
	s_nop 0
	v_addc_co_u32_e32 v61, vcc, 0, v7, vcc
	v_add_co_u32_e32 v62, vcc, s7, v6
	s_mov_b32 s7, 0x1e0000
	s_nop 0
	v_addc_co_u32_e32 v63, vcc, 0, v7, vcc
	v_add_co_u32_e32 v64, vcc, s7, v6
	s_mov_b32 s7, 0x1f0000
	s_nop 0
	v_addc_co_u32_e32 v65, vcc, 0, v7, vcc
	v_add_co_u32_e32 v66, vcc, s7, v6
	v_readlane_b32 s77, v251, 10
	s_nop 0
	v_addc_co_u32_e32 v67, vcc, 0, v7, vcc
	global_load_dword v60, v[60:61], off nt
	s_nop 0
	global_load_dword v61, v[62:63], off nt
	s_nop 0
	global_load_dword v62, v[64:65], off nt
	global_load_dword v63, v[66:67], off nt
	s_nop 0
	global_load_dword v34, v[34:35], off nt
	s_nop 0
	global_load_dword v35, v[36:37], off nt
	s_nop 0
	global_load_dword v36, v[48:49], off nt
	global_load_dword v37, v[50:51], off nt
	s_nop 0
	global_load_dword v48, v[52:53], off nt
	global_load_dword v49, v[54:55], off nt
	global_load_dword v50, v[56:57], off nt
	global_load_dword v51, v[58:59], off nt
	s_nop 0
	global_load_dword v52, v[18:19], off nt
	global_load_dword v53, v[20:21], off nt
	s_nop 0
	global_load_dword v22, v[22:23], off nt
	s_nop 0
	global_load_dword v23, v[24:25], off nt
	s_nop 0
	global_load_dword v24, v[26:27], off nt
	global_load_dword v25, v[28:29], off nt
	s_nop 0
	global_load_dword v26, v[30:31], off nt
	global_load_dword v27, v[32:33], off nt
	v_add_co_u32_e32 v18, vcc, s62, v6
	v_readlane_b32 s78, v251, 11
	s_nop 0
	v_addc_co_u32_e32 v19, vcc, 0, v7, vcc
	v_add_co_u32_e32 v20, vcc, s66, v6
	v_readlane_b32 s79, v251, 12
	s_nop 0
	v_addc_co_u32_e32 v21, vcc, 0, v7, vcc
	global_load_dword v20, v[20:21], off nt
	s_nop 0
	global_load_dword v18, v[18:19], off nt
	s_nop 0
	global_load_dword v16, v[16:17], off nt
	s_nop 0
	global_load_dword v14, v[14:15], off nt
	s_nop 0
	global_load_dword v12, v[12:13], off nt
	s_nop 0
	global_load_dword v10, v[10:11], off nt
	s_nop 0
	global_load_dword v8, v[8:9], off nt
	s_nop 0
	global_load_dword v6, v[6:7], off nt
	s_cselect_b64 vcc, -1, 0
	s_ashr_i32 s1, s0, 31
	s_lshl_b64 s[0:1], s[0:1], 1
	s_add_u32 s0, s6, s0
	s_addc_u32 s1, s5, s1
	v_readlane_b32 s80, v251, 13
	v_readlane_b32 s81, v251, 14
	v_readlane_b32 s82, v251, 15
	v_readlane_b32 s83, v251, 16
	v_readlane_b32 s86, v251, 19
	v_readlane_b32 s87, v251, 20
	s_waitcnt vmcnt(31)
; #define LAS __attribute__((address_space(3)))
; __device__ __forceinline__ unsigned pk2(float lo, float hi) { return f2bf(lo) | (f2bf(hi) << 16); }
; __device__ __forceinline__ void transpose_item(const float* __restrict__ W, int K, int N, bf16_t* __restrict__ WT, int id, const float* __restrict__ gk, LAS float* scr, int item, int nblk, int lane) {
;     ...
;     if (sc < 0) {
; #pragma unroll
;         for (int i = 0; i < 32; ++i) v[i] = 0.f;
;     }
;     if (gk) {
; #pragma unroll
;         for (int i = 0; i < 32; ++i) v[i] *= gk[k0 + 2 * i + (lane >> 5)];
;     }
; #pragma unroll
;     for (int i = 0; i < 32; ++i) scr[(2 * i + (lane >> 5)) * 33 + (lane & 31)] = v[i];
;     asm volatile("s_waitcnt lgkmcnt(0)" ::: "memory");
;     const int c = lane & 7;
; #pragma unroll
;     for (int j = 0; j < 4; ++j) { const int n = (lane >> 3) + 8 * j; const LAS float* s = scr + (8 * c) * 33 + n;
;         u32x4 o; o.x = pk2(s[0 * 33], s[1 * 33]); o.y = pk2(s[2 * 33], s[3 * 33]); o.z = pk2(s[4 * 33], s[5 * 33]); o.w = pk2(s[6 * 33], s[7 * 33]);
	v_cndmask_b32_e32 v4, 0, v4, vcc
	s_waitcnt vmcnt(30)
	v_cndmask_b32_e32 v19, 0, v68, vcc
	s_waitcnt vmcnt(29)
	v_cndmask_b32_e32 v17, 0, v69, vcc
	s_waitcnt vmcnt(28)
	v_cndmask_b32_e32 v15, 0, v70, vcc
	s_waitcnt vmcnt(27)
	v_cndmask_b32_e32 v13, 0, v60, vcc
	s_waitcnt vmcnt(26)
	v_cndmask_b32_e32 v11, 0, v61, vcc
	s_waitcnt vmcnt(25)
	v_cndmask_b32_e32 v9, 0, v62, vcc
	s_waitcnt vmcnt(24)
	v_cndmask_b32_e32 v7, 0, v63, vcc
	s_waitcnt vmcnt(23)
	v_cndmask_b32_e32 v34, 0, v34, vcc
	s_waitcnt vmcnt(22)
	v_cndmask_b32_e32 v33, 0, v35, vcc
	s_waitcnt vmcnt(21)
	v_cndmask_b32_e32 v32, 0, v36, vcc
	s_waitcnt vmcnt(20)
	v_cndmask_b32_e32 v31, 0, v37, vcc
	s_waitcnt vmcnt(19)
	v_cndmask_b32_e32 v30, 0, v48, vcc
	s_waitcnt vmcnt(18)
	v_cndmask_b32_e32 v29, 0, v49, vcc
	s_waitcnt vmcnt(17)
	v_cndmask_b32_e32 v28, 0, v50, vcc
	s_waitcnt vmcnt(16)
	v_cndmask_b32_e32 v21, 0, v51, vcc
	s_waitcnt vmcnt(15)
	v_cndmask_b32_e32 v36, 0, v52, vcc
	s_waitcnt vmcnt(14)
	v_cndmask_b32_e32 v35, 0, v53, vcc
	s_waitcnt vmcnt(13)
	v_cndmask_b32_e32 v22, 0, v22, vcc
	s_waitcnt vmcnt(12)
	v_cndmask_b32_e32 v23, 0, v23, vcc
	s_waitcnt vmcnt(11)
	v_cndmask_b32_e32 v24, 0, v24, vcc
	s_waitcnt vmcnt(10)
	v_cndmask_b32_e32 v25, 0, v25, vcc
	s_waitcnt vmcnt(9)
	v_cndmask_b32_e32 v26, 0, v26, vcc
	s_waitcnt vmcnt(8)
	v_cndmask_b32_e32 v27, 0, v27, vcc
	s_waitcnt vmcnt(7)
	v_cndmask_b32_e32 v20, 0, v20, vcc
	s_waitcnt vmcnt(6)
	v_cndmask_b32_e32 v18, 0, v18, vcc
	s_waitcnt vmcnt(5)
	v_cndmask_b32_e32 v16, 0, v16, vcc
	s_waitcnt vmcnt(4)
	v_cndmask_b32_e32 v14, 0, v14, vcc
	s_waitcnt vmcnt(3)
	v_cndmask_b32_e32 v12, 0, v12, vcc
	s_waitcnt vmcnt(2)
	v_cndmask_b32_e32 v10, 0, v10, vcc
	s_waitcnt vmcnt(1)
	v_cndmask_b32_e32 v8, 0, v8, vcc
	s_waitcnt vmcnt(0)
	v_cndmask_b32_e32 v6, 0, v6, vcc
	ds_write2_b32 v39, v6, v8 offset1:66
	ds_write2_b32 v39, v10, v12 offset0:132 offset1:198
	v_add_u32_e32 v6, 0x400, v39
	ds_write2_b32 v6, v14, v16 offset0:8 offset1:74
	ds_write2_b32 v6, v18, v20 offset0:140 offset1:206
	v_add_u32_e32 v6, 0x800, v39
	ds_write2_b32 v6, v36, v35 offset0:16 offset1:82
	ds_write2_b32 v6, v22, v23 offset0:148 offset1:214
	v_add_u32_e32 v6, 0xc00, v39
	ds_write2_b32 v6, v24, v25 offset0:24 offset1:90
	ds_write2_b32 v6, v26, v27 offset0:156 offset1:222
	v_add_u32_e32 v6, 0x1000, v39
	ds_write2_b32 v6, v34, v33 offset0:32 offset1:98
	ds_write2_b32 v6, v32, v31 offset0:164 offset1:230
	v_add_u32_e32 v6, 0x1400, v39
	ds_write2_b32 v6, v30, v29 offset0:40 offset1:106
	ds_write2_b32 v6, v28, v21 offset0:172 offset1:238
	v_add_u32_e32 v6, 0x1800, v39
	ds_write2_b32 v6, v4, v19 offset0:48 offset1:114
	ds_write2_b32 v6, v17, v15 offset0:180 offset1:246
	v_add_u32_e32 v4, 0x1c00, v39
	ds_write2_b32 v4, v13, v11 offset0:56 offset1:122
	ds_write2_b32 v4, v9, v7 offset0:188 offset1:254
	s_waitcnt lgkmcnt(0)
	ds_read2_b32 v[10:11], v41 offset1:8
	ds_read2_b32 v[14:15], v41 offset0:33 offset1:41
	ds_read2_b32 v[16:17], v41 offset0:66 offset1:74
	v_lshlrev_b32_e32 v4, 1, v2
	ds_read2_b32 v[18:19], v41 offset0:99 offset1:107
	v_lshl_add_u64 v[12:13], s[0:1], 0, v[4:5]
	s_waitcnt lgkmcnt(3)
	v_bfe_u32 v4, v10, 16, 1
	v_add3_u32 v4, v10, v4, s70
	s_waitcnt lgkmcnt(2)
	v_bfe_u32 v6, v14, 16, 1
	ds_read2_b32 v[20:21], v41 offset0:132 offset1:140
	v_lshrrev_b32_e32 v4, 16, v4
	v_add3_u32 v6, v14, v6, s70
	ds_read2_b32 v[22:23], v41 offset0:165 offset1:173
	v_and_or_b32 v6, v6, s71, v4
	s_waitcnt lgkmcnt(3)
	v_bfe_u32 v4, v16, 16, 1
	v_add3_u32 v4, v16, v4, s70
	s_waitcnt lgkmcnt(2)
	v_bfe_u32 v7, v18, 16, 1
	ds_read2_b32 v[24:25], v41 offset0:198 offset1:206
	v_lshrrev_b32_e32 v4, 16, v4
	v_add3_u32 v7, v18, v7, s70
	ds_read2_b32 v[26:27], v41 offset0:231 offset1:239
	v_and_or_b32 v7, v7, s71, v4
	s_waitcnt lgkmcnt(3)
	v_bfe_u32 v4, v20, 16, 1
	v_add3_u32 v4, v20, v4, s70
	s_waitcnt lgkmcnt(2)
; #define LAS __attribute__((address_space(3)))
; __device__ __forceinline__ unsigned pk2(float lo, float hi) { return f2bf(lo) | (f2bf(hi) << 16); }
; __device__ __forceinline__ void transpose_item(const float* __restrict__ W, int K, int N, bf16_t* __restrict__ WT, int id, const float* __restrict__ gk, LAS float* scr, int item, int nblk, int lane) {
;     ...
;     for (int j = 0; j < 4; ++j) { const int n = (lane >> 3) + 8 * j; const LAS float* s = scr + (8 * c) * 33 + n;
;         u32x4 o; o.x = pk2(s[0 * 33], s[1 * 33]); o.y = pk2(s[2 * 33], s[3 * 33]); o.z = pk2(s[4 * 33], s[5 * 33]); o.w = pk2(s[6 * 33], s[7 * 33]);
;         *(u32x4*)(WT + (size_t)(n0 + n) * K + k0 + 8 * c) = o; }
;     asm volatile("s_waitcnt lgkmcnt(0)" ::: "memory");
; }
; __device__ __forceinline__ void prologue_phase(const Args& A, LAS unsigned char* lds, int G, const int wv) {
;     ...
;     for (int it = gw; it < 2 * PER_L; it += NGW) {
	v_bfe_u32 v8, v22, 16, 1
	v_lshrrev_b32_e32 v4, 16, v4
	v_add3_u32 v8, v22, v8, s70
	v_and_or_b32 v8, v8, s71, v4
	s_waitcnt lgkmcnt(1)
	v_bfe_u32 v4, v24, 16, 1
	v_or_b32_e32 v28, s4, v40
	v_add3_u32 v4, v24, v4, s70
	s_waitcnt lgkmcnt(0)
	v_bfe_u32 v9, v26, 16, 1
	v_ashrrev_i32_e32 v29, 31, v28
	v_lshrrev_b32_e32 v4, 16, v4
	v_add3_u32 v9, v26, v9, s70
	v_lshlrev_b64 v[28:29], 12, v[28:29]
	v_and_or_b32 v9, v9, s71, v4
	v_lshl_add_u64 v[28:29], v[12:13], 0, v[28:29]
	v_bfe_u32 v4, v11, 16, 1
	global_store_dwordx4 v[28:29], v[6:9], off
	v_add3_u32 v4, v11, v4, s70
	v_lshrrev_b32_e32 v4, 16, v4
	v_bfe_u32 v6, v15, 16, 1
	v_add3_u32 v6, v15, v6, s70
	v_and_or_b32 v6, v6, s71, v4
	v_bfe_u32 v4, v17, 16, 1
	v_add3_u32 v4, v17, v4, s70
	v_bfe_u32 v7, v19, 16, 1
	v_lshrrev_b32_e32 v4, 16, v4
	v_add3_u32 v7, v19, v7, s70
	v_and_or_b32 v7, v7, s71, v4
	v_bfe_u32 v4, v21, 16, 1
	v_add3_u32 v4, v21, v4, s70
	v_bfe_u32 v8, v23, 16, 1
	v_lshrrev_b32_e32 v4, 16, v4
	v_add3_u32 v8, v23, v8, s70
	v_and_or_b32 v8, v8, s71, v4
	v_bfe_u32 v4, v25, 16, 1
	v_or_b32_e32 v10, s4, v42
	v_add3_u32 v4, v25, v4, s70
	v_bfe_u32 v9, v27, 16, 1
	v_ashrrev_i32_e32 v11, 31, v10
	v_lshrrev_b32_e32 v4, 16, v4
	v_add3_u32 v9, v27, v9, s70
	v_lshlrev_b64 v[10:11], 12, v[10:11]
	v_and_or_b32 v9, v9, s71, v4
	ds_read2_b32 v[14:15], v41 offset0:16 offset1:24
	v_lshl_add_u64 v[10:11], v[12:13], 0, v[10:11]
	global_store_dwordx4 v[10:11], v[6:9], off
	ds_read2_b32 v[10:11], v41 offset0:49 offset1:57
	ds_read2_b32 v[16:17], v41 offset0:82 offset1:90
	ds_read2_b32 v[18:19], v41 offset0:115 offset1:123
	s_waitcnt lgkmcnt(3)
	v_bfe_u32 v4, v14, 16, 1
	v_add3_u32 v4, v14, v4, s70
	s_waitcnt lgkmcnt(2)
	v_bfe_u32 v6, v10, 16, 1
	ds_read2_b32 v[20:21], v41 offset0:148 offset1:156
	v_lshrrev_b32_e32 v4, 16, v4
	v_add3_u32 v6, v10, v6, s70
	ds_read2_b32 v[22:23], v41 offset0:181 offset1:189
	v_and_or_b32 v6, v6, s71, v4
	s_waitcnt lgkmcnt(3)
	v_bfe_u32 v4, v16, 16, 1
	v_add3_u32 v4, v16, v4, s70
	s_waitcnt lgkmcnt(2)
	v_bfe_u32 v7, v18, 16, 1
	ds_read2_b32 v[24:25], v41 offset0:214 offset1:222
	v_lshrrev_b32_e32 v4, 16, v4
	v_add3_u32 v7, v18, v7, s70
	ds_read2_b32 v[26:27], v41 offset0:247 offset1:255
	v_and_or_b32 v7, v7, s71, v4
	s_waitcnt lgkmcnt(3)
	v_bfe_u32 v4, v20, 16, 1
	v_add3_u32 v4, v20, v4, s70
	s_waitcnt lgkmcnt(2)
	v_bfe_u32 v8, v22, 16, 1
	v_lshrrev_b32_e32 v4, 16, v4
	v_add3_u32 v8, v22, v8, s70
	v_and_or_b32 v8, v8, s71, v4
	s_waitcnt lgkmcnt(1)
	v_bfe_u32 v4, v24, 16, 1
	v_or_b32_e32 v28, s4, v43
	v_add3_u32 v4, v24, v4, s70
	s_waitcnt lgkmcnt(0)
	v_bfe_u32 v9, v26, 16, 1
	v_ashrrev_i32_e32 v29, 31, v28
	v_lshrrev_b32_e32 v4, 16, v4
	v_add3_u32 v9, v26, v9, s70
	v_lshlrev_b64 v[28:29], 12, v[28:29]
	v_and_or_b32 v9, v9, s71, v4
	v_lshl_add_u64 v[28:29], v[12:13], 0, v[28:29]
	v_bfe_u32 v4, v15, 16, 1
	global_store_dwordx4 v[28:29], v[6:9], off
	v_add3_u32 v4, v15, v4, s70
	v_lshrrev_b32_e32 v4, 16, v4
	v_bfe_u32 v6, v11, 16, 1
	v_add3_u32 v6, v11, v6, s70
	v_and_or_b32 v6, v6, s71, v4
	v_bfe_u32 v4, v17, 16, 1
	v_add3_u32 v4, v17, v4, s70
	v_bfe_u32 v7, v19, 16, 1
	v_lshrrev_b32_e32 v4, 16, v4
	v_add3_u32 v7, v19, v7, s70
	v_and_or_b32 v7, v7, s71, v4
	v_bfe_u32 v4, v21, 16, 1
	v_add3_u32 v4, v21, v4, s70
	v_bfe_u32 v8, v23, 16, 1
	v_lshrrev_b32_e32 v4, 16, v4
	v_add3_u32 v8, v23, v8, s70
	v_and_or_b32 v8, v8, s71, v4
	v_bfe_u32 v4, v25, 16, 1
	v_or_b32_e32 v10, s4, v44
	v_add3_u32 v4, v25, v4, s70
	v_bfe_u32 v9, v27, 16, 1
	v_ashrrev_i32_e32 v11, 31, v10
	v_lshrrev_b32_e32 v4, 16, v4
	v_add3_u32 v9, v27, v9, s70
	v_lshlrev_b64 v[10:11], 12, v[10:11]
	v_and_or_b32 v9, v9, s71, v4
	v_lshl_add_u64 v[10:11], v[12:13], 0, v[10:11]
	global_store_dwordx4 v[10:11], v[6:9], off
	s_waitcnt lgkmcnt(0)
	s_branch .LBB0_39

; #define LAS __attribute__((address_space(3)))
; __device__ __forceinline__ int opaque_tid(int wv) { unsigned z = 0u; asm volatile("" : "+v"(z)); return (wv << 6) | (int)__builtin_amdgcn_mbcnt_hi(~0u, __builtin_amdgcn_mbcnt_lo(~0u, z)); }
; __device__ __forceinline__ unsigned xb_add(unsigned* p, unsigned v) { return __hip_atomic_fetch_add(p, v, __ATOMIC_RELAXED, __HIP_MEMORY_SCOPE_AGENT); }
; __device__ __forceinline__ unsigned xb_xcc_id() { return (unsigned)__builtin_amdgcn_s_getreg((3 << 11) | 20) & 0xFu; }
; __global__ void __launch_bounds__(512) fwd_megakernel(Args A) {
;     ...
;     cg::grid_group grid = cg::this_grid();
;     unsigned* xbar = (unsigned*)(ws + WS_CTL) + 1024;
;     volatile LAS unsigned* xst = (volatile LAS unsigned*)(lds + MISC_OFF + 64);
;     { const int t0_ = opaque_tid(wv); if (t0_ == 0) { xst[0] = 0u; xst[1] = 0u; (void)xb_add(&xbar[XB_XCNT(xb_xcc_id())], 1u); } }
.LBB0_181:
.LBB0_182:
	s_mov_b64 s[2:3], exec
	s_mov_b64 exec, 1
	s_and_b32 s4, s86, 7
	s_lshl_b32 s4, s4, 8
	s_add_u32 s4, s4, 0x6000
	s_add_u32 s4, s60, s4
	s_addc_u32 s5, s61, 0
	v_mov_b32_e32 v2, 0
	global_load_dword v3, v2, s[4:5] sc1
	s_waitcnt vmcnt(0)
	v_readfirstlane_b32 s6, v3
	s_mov_b64 exec, s[2:3]
	s_bcnt1_i32_b32 s6, s6
	v_readlane_b32 s7, v251, 2
	s_mov_b32 s100, 0
	s_mov_b32 s101, 0
	s_cmpk_lg_i32 s7, 0x100
	s_cbranch_scc1 .Lmode_done
	s_mov_b32 s100, 1
	s_cmp_lg_u32 s6, 1
	s_cbranch_scc1 .Lmode_done
	s_mov_b32 s100, 2

; __device__ __forceinline__ unsigned xb_ld(unsigned* p)              { return __hip_atomic_load(p, __ATOMIC_RELAXED, __HIP_MEMORY_SCOPE_AGENT); }
; __device__ __forceinline__ unsigned xb_add(unsigned* p, unsigned v) { return __hip_atomic_fetch_add(p, v, __ATOMIC_RELAXED, __HIP_MEMORY_SCOPE_AGENT); }
; #define XB_SPIN(cond, bar) do { unsigned _sp = 0; while (cond) { __builtin_amdgcn_s_sleep(1); \
;     if ((++_sp & 255u) == 0u) { if (xb_ld(&(bar)[XB_TMO])) break; if (_sp > XB_SPIN_CAP) { atomicAdd(&(bar)[XB_TMO], 1u); break; } } } } while (0)
; __device__ __forceinline__ void xcd_barrier(unsigned* bar, volatile LAS unsigned* st, bool is0) {
;     ...
;             __builtin_amdgcn_fence(__ATOMIC_ACQUIRE, "agent");
;             xb_add(&bar[XB_XGEN(x)], 1u);
;             asm volatile("s_waitcnt vmcnt(0)" ::: "memory");
;         } else {
;             XB_SPIN(xb_ld(&bar[XB_XGEN(x)]) == gen, bar);
;             __builtin_amdgcn_fence(__ATOMIC_ACQUIRE, "agent");
;             asm volatile("s_waitcnt vmcnt(0)" ::: "memory");
.LBB0_312:
	s_or_b64 exec, exec, s[8:9]
	s_waitcnt vmcnt(0)
	s_waitcnt vmcnt(0)

; #define LAS __attribute__((address_space(3)))
; __device__ __forceinline__ unsigned xb_ld(unsigned* p)              { return __hip_atomic_load(p, __ATOMIC_RELAXED, __HIP_MEMORY_SCOPE_AGENT); }
; __device__ __forceinline__ unsigned xb_add(unsigned* p, unsigned v) { return __hip_atomic_fetch_add(p, v, __ATOMIC_RELAXED, __HIP_MEMORY_SCOPE_AGENT); }
; __device__ __forceinline__ unsigned xb_xcc_id() { return (unsigned)__builtin_amdgcn_s_getreg((3 << 11) | 20) & 0xFu; }
; #define XB_SPIN(cond, bar) do { unsigned _sp = 0; while (cond) { __builtin_amdgcn_s_sleep(1); \
;     if ((++_sp & 255u) == 0u) { if (xb_ld(&(bar)[XB_TMO])) break; if (_sp > XB_SPIN_CAP) { atomicAdd(&(bar)[XB_TMO], 1u); break; } } } } while (0)
; __device__ __forceinline__ void xcd_barrier(unsigned* bar, volatile LAS unsigned* st, bool is0) {
;     asm volatile("s_waitcnt vmcnt(0)" ::: "memory");
;     __syncthreads();
;     if (is0) {
;         __builtin_amdgcn_s_waitcnt(0);
;         const unsigned x = xb_xcc_id();
;         unsigned nloc = st[0], nx = st[1];
;         if (nloc == 0u) { xcd_barrier_complete(bar, x, nloc, nx); st[0] = nloc; st[1] = nx; }
;         const unsigned old = xb_add(&bar[XB_XSUB(x)], 1u);
;         const unsigned gen = old / nloc;
;         if (old + 1u == (gen + 1u) * nloc) {
;             __builtin_amdgcn_fence(__ATOMIC_RELEASE, "agent");
;             asm volatile("s_waitcnt vmcnt(0)" ::: "memory");
;             const unsigned og = xb_add(&bar[XB_TOP], 1u);
;             const unsigned tg = og / nx;
;             if (og + 1u == (tg + 1u) * nx) xb_add(&bar[XB_TOPGEN], 1u);
;             else XB_SPIN(xb_ld(&bar[XB_TOPGEN]) == tg, bar);
;             __builtin_amdgcn_fence(__ATOMIC_ACQUIRE, "agent");
;             xb_add(&bar[XB_XGEN(x)], 1u);
;             asm volatile("s_waitcnt vmcnt(0)" ::: "memory");
;         } else {
;             XB_SPIN(xb_ld(&bar[XB_XGEN(x)]) == gen, bar);
;             __builtin_amdgcn_fence(__ATOMIC_ACQUIRE, "agent");
;             asm volatile("s_waitcnt vmcnt(0)" ::: "memory");
;         }
;     }
;     __syncthreads();
; }
.LBB0_816:
	v_readlane_b32 s0, v254, 45
	v_readlane_b32 s8, v251, 41
	s_or_b32 s0, s0, 6
	v_readlane_b32 s15, v251, 48
	v_readlane_b32 s14, v251, 47
	s_cmp_ge_i32 s0, s15
	v_readlane_b32 s1, v254, 46
	v_readlane_b32 s9, v251, 42
	v_readlane_b32 s10, v251, 43
	v_readlane_b32 s11, v251, 44
	v_readlane_b32 s12, v251, 45
	v_readlane_b32 s13, v251, 46
	s_cbranch_scc1 .LBB0_884
	v_readlane_b32 s0, v252, 13
	v_readlane_b32 s1, v252, 14
	s_mov_b64 s[2:3], -1
	s_and_b64 vcc, exec, s[0:1]
	s_cbranch_vccz .LBB0_871
	s_cmp_eq_u32 s100, 0
	s_cbranch_scc1 .Lgb_orig_3
	s_waitcnt vmcnt(0) lgkmcnt(0)
	s_barrier
	s_cmp_lg_u32 s94, 0
	s_cbranch_scc1 .Lgb_join_3
	s_mov_b64 exec, 1
	v_readlane_b32 s8, v251, 45
	v_readlane_b32 s9, v251, 46
	v_readlane_b32 s6, v251, 50
	v_mov_b32_e32 v4, 1
	v_mov_b32_e32 v8, 0
	s_and_b32 s6, s6, 7
	s_lshl_b32 s6, s6, 8
	s_add_u32 s6, s6, 0x5000
	s_add_u32 s8, s8, s6
	s_addc_u32 s9, s9, 0
	s_add_u32 s12, s101, 1
	s_lshl_b32 s13, s12, 5
	s_cmp_eq_u32 s100, 2
	s_cbranch_scc1 .Lgb_arr_3
	buffer_wbl2 sc1
	s_waitcnt vmcnt(0)
.Lgb_arr_3:
	global_atomic_add v6, v8, v4, s[8:9] sc0
	s_waitcnt vmcnt(0)
	v_readfirstlane_b32 s15, v6
	s_nop 1
	s_add_u32 s15, s15, 1
	s_cmp_eq_u32 s15, s13
	s_cbranch_scc0 .Lgb_wait_3
	global_atomic_add v8, v4, s[8:9] offset:2048
	s_branch .Lgb_acq_3
.Lgb_wait_3:
	s_mov_b32 s16, 0
.Lgb_w_3:
	s_sleep 1
	global_load_dword v6, v8, s[8:9] offset:2048 sc1
	s_add_u32 s16, s16, 1
	s_waitcnt vmcnt(0)
	v_readfirstlane_b32 s15, v6
	s_cmp_lg_u32 s15, s101
	s_cbranch_scc1 .Lgb_acq_3
	s_cmp_lt_u32 s16, 0x400000
	s_cbranch_scc1 .Lgb_w_3
.Lgb_acq_3:
	s_cmp_eq_u32 s100, 2
	s_cbranch_scc1 .Lgb_noinv_3
	buffer_inv sc1
	s_waitcnt vmcnt(0)
.Lgb_noinv_3:
	s_mov_b64 exec, -1
.Lgb_join_3:
	s_add_u32 s101, s101, 1
	s_mov_b64 s[2:3], 0
	s_barrier
	s_branch .Lgb_after_3
.Lgb_orig_3:
	v_mov_b32_e32 v0, v1
	s_waitcnt vmcnt(0)
	s_waitcnt vmcnt(0) lgkmcnt(0)
	v_mbcnt_lo_u32_b32 v0, -1, v0
	v_mbcnt_hi_u32_b32 v0, -1, v0
	v_or_b32_e32 v0, s94, v0
	v_cmp_eq_u32_e32 vcc, 0, v0
	s_barrier
	s_and_saveexec_b64 s[2:3], vcc
	s_cbranch_execz .LBB0_870
	v_readlane_b32 s1, v254, 35
	s_waitcnt vmcnt(0) expcnt(0) lgkmcnt(0)
	s_getreg_b32 s0, hwreg(HW_REG_XCC_ID, 0, 4)
	v_mov_b32_e32 v0, s1
	ds_read_b32 v3, v0
	v_readlane_b32 s1, v254, 36
	s_and_b32 s0, s0, 15
	s_waitcnt lgkmcnt(0)
	v_cmp_ne_u32_e32 vcc, 0, v3
	v_mov_b32_e32 v0, s1
	ds_read_b32 v2, v0
	s_cbranch_vccnz .LBB0_834
	s_mov_b32 s1, 1
	s_branch .LBB0_822

.Lgb_after_3:
.LBB0_871:
	s_and_b64 vcc, exec, s[2:3]
	s_cbranch_vccz .LBB0_883
	s_waitcnt vmcnt(0) lgkmcnt(0)
	s_barrier
	s_mov_b64 s[2:3], exec
	v_readlane_b32 s0, v254, 37
	v_readlane_b32 s1, v254, 38
	s_and_b64 s[0:1], s[2:3], s[0:1]
	s_mov_b64 exec, s[0:1]
	s_cbranch_execz .LBB0_882
	v_readlane_b32 s0, v251, 0
	v_readlane_b32 s1, v251, 1
	buffer_wbl2 sc1
	s_load_dwordx2 s[6:7], s[0:1], 0x58
	s_mov_b64 s[8:9], exec
	v_mbcnt_lo_u32_b32 v2, s8, 0
	v_mbcnt_hi_u32_b32 v2, s9, v2
	v_cmp_eq_u32_e32 vcc, 0, v2
	s_waitcnt lgkmcnt(0)
	global_load_dword v0, v1, s[6:7] offset:40
	s_and_saveexec_b64 s[10:11], vcc
	s_cbranch_execz .LBB0_875
	s_bcnt1_i32_b64 s0, s[8:9]
	v_mov_b32_e32 v3, s0
	global_atomic_add v3, v1, v3, s[6:7] offset:32 sc0

; #define LAS __attribute__((address_space(3)))
; __device__ __forceinline__ unsigned xb_ld(unsigned* p)              { return __hip_atomic_load(p, __ATOMIC_RELAXED, __HIP_MEMORY_SCOPE_AGENT); }
; __device__ __forceinline__ unsigned xb_add(unsigned* p, unsigned v) { return __hip_atomic_fetch_add(p, v, __ATOMIC_RELAXED, __HIP_MEMORY_SCOPE_AGENT); }
; __device__ __forceinline__ unsigned xb_xcc_id() { return (unsigned)__builtin_amdgcn_s_getreg((3 << 11) | 20) & 0xFu; }
; #define XB_SPIN(cond, bar) do { unsigned _sp = 0; while (cond) { __builtin_amdgcn_s_sleep(1); \
;     if ((++_sp & 255u) == 0u) { if (xb_ld(&(bar)[XB_TMO])) break; if (_sp > XB_SPIN_CAP) { atomicAdd(&(bar)[XB_TMO], 1u); break; } } } } while (0)
; __device__ __forceinline__ void xcd_barrier(unsigned* bar, volatile LAS unsigned* st, bool is0) {
;     asm volatile("s_waitcnt vmcnt(0)" ::: "memory");
;     __syncthreads();
;     if (is0) {
;         __builtin_amdgcn_s_waitcnt(0);
;         const unsigned x = xb_xcc_id();
;         unsigned nloc = st[0], nx = st[1];
;         if (nloc == 0u) { xcd_barrier_complete(bar, x, nloc, nx); st[0] = nloc; st[1] = nx; }
;         const unsigned old = xb_add(&bar[XB_XSUB(x)], 1u);
;         const unsigned gen = old / nloc;
;         if (old + 1u == (gen + 1u) * nloc) {
;             __builtin_amdgcn_fence(__ATOMIC_RELEASE, "agent");
;             asm volatile("s_waitcnt vmcnt(0)" ::: "memory");
;             const unsigned og = xb_add(&bar[XB_TOP], 1u);
;             const unsigned tg = og / nx;
;             if (og + 1u == (tg + 1u) * nx) xb_add(&bar[XB_TOPGEN], 1u);
;             else XB_SPIN(xb_ld(&bar[XB_TOPGEN]) == tg, bar);
.LBB0_909:
	v_readlane_b32 s0, v254, 45
	v_readlane_b32 s8, v251, 41
	s_add_i32 s0, s0, 8
	v_readlane_b32 s15, v251, 48
	s_cmp_ge_i32 s0, s15
	v_readlane_b32 s1, v254, 46
	v_readlane_b32 s9, v251, 42
	v_readlane_b32 s10, v251, 43
	v_readlane_b32 s11, v251, 44
	v_readlane_b32 s12, v251, 45
	v_readlane_b32 s13, v251, 46
	v_readlane_b32 s14, v251, 47
	s_cbranch_scc1 .LBB0_976
	v_readlane_b32 s6, v252, 13
	v_readlane_b32 s7, v252, 14
	s_mov_b64 s[2:3], -1
	s_and_b64 vcc, exec, s[6:7]
	s_cbranch_vccz .LBB0_964
	s_cmp_eq_u32 s100, 0
	s_cbranch_scc1 .Lgb_orig_4
	s_waitcnt vmcnt(0) lgkmcnt(0)
	s_barrier
	s_cmp_lg_u32 s94, 0
	s_cbranch_scc1 .Lgb_join_4
	s_mov_b64 exec, 1
	v_readlane_b32 s8, v251, 45
	v_readlane_b32 s9, v251, 46
	v_readlane_b32 s6, v251, 50
	v_mov_b32_e32 v4, 1
	v_mov_b32_e32 v8, 0
	s_and_b32 s6, s6, 7
	s_lshl_b32 s6, s6, 8
	s_add_u32 s6, s6, 0x5000
	s_add_u32 s8, s8, s6
	s_addc_u32 s9, s9, 0
	s_add_u32 s12, s101, 1
	s_lshl_b32 s13, s12, 5
	s_cmp_eq_u32 s100, 2
	s_cbranch_scc1 .Lgb_arr_4
	buffer_wbl2 sc1
	s_waitcnt vmcnt(0)

; #define LAS __attribute__((address_space(3)))
; __device__ __forceinline__ unsigned xb_add(unsigned* p, unsigned v) { return __hip_atomic_fetch_add(p, v, __ATOMIC_RELAXED, __HIP_MEMORY_SCOPE_AGENT); }
; __device__ __forceinline__ unsigned xb_xcc_id() { return (unsigned)__builtin_amdgcn_s_getreg((3 << 11) | 20) & 0xFu; }
; __device__ __forceinline__ void xcd_barrier(unsigned* bar, volatile LAS unsigned* st, bool is0) {
;     asm volatile("s_waitcnt vmcnt(0)" ::: "memory");
;     __syncthreads();
;     if (is0) {
;         __builtin_amdgcn_s_waitcnt(0);
;         const unsigned x = xb_xcc_id();
;         unsigned nloc = st[0], nx = st[1];
;         if (nloc == 0u) { xcd_barrier_complete(bar, x, nloc, nx); st[0] = nloc; st[1] = nx; }
;         const unsigned old = xb_add(&bar[XB_XSUB(x)], 1u);
.Lgb_orig_4:
	v_mov_b32_e32 v0, v1
	s_waitcnt vmcnt(0)
	s_waitcnt vmcnt(0) lgkmcnt(0)
	v_mbcnt_lo_u32_b32 v0, -1, v0
	v_mbcnt_hi_u32_b32 v0, -1, v0
	v_or_b32_e32 v0, s94, v0
	v_cmp_eq_u32_e32 vcc, 0, v0
	s_barrier
	s_and_saveexec_b64 s[2:3], vcc
	s_cbranch_execz .LBB0_963
	v_readlane_b32 s6, v254, 35
	s_waitcnt vmcnt(0) expcnt(0) lgkmcnt(0)
	s_getreg_b32 s1, hwreg(HW_REG_XCC_ID, 0, 4)
	v_mov_b32_e32 v0, s6
	ds_read_b32 v3, v0
	v_readlane_b32 s6, v254, 36
	s_and_b32 s1, s1, 15
	s_waitcnt lgkmcnt(0)
	v_cmp_ne_u32_e32 vcc, 0, v3
	v_mov_b32_e32 v0, s6
	ds_read_b32 v2, v0
	s_cbranch_vccnz .LBB0_927
	s_mov_b32 s12, 1
	s_branch .LBB0_915

.Lgb_after_4:
.LBB0_964:
	s_and_b64 vcc, exec, s[2:3]
	s_cbranch_vccz .LBB0_976
	s_waitcnt vmcnt(0) lgkmcnt(0)
	s_barrier
	s_mov_b64 s[2:3], exec
	v_readlane_b32 s6, v254, 37
	v_readlane_b32 s7, v254, 38
	s_and_b64 s[6:7], s[2:3], s[6:7]
	s_mov_b64 exec, s[6:7]
	s_cbranch_execz .LBB0_975
	v_readlane_b32 s6, v251, 0
	v_readlane_b32 s7, v251, 1
	buffer_wbl2 sc1
	s_load_dwordx2 s[6:7], s[6:7], 0x58
	s_mov_b64 s[8:9], exec
	v_mbcnt_lo_u32_b32 v2, s8, 0
	v_mbcnt_hi_u32_b32 v2, s9, v2
	v_cmp_eq_u32_e32 vcc, 0, v2
	s_waitcnt lgkmcnt(0)
	global_load_dword v0, v1, s[6:7] offset:40
	s_and_saveexec_b64 s[10:11], vcc
	s_cbranch_execz .LBB0_968
	s_bcnt1_i32_b64 s1, s[8:9]
	v_mov_b32_e32 v3, s1
	global_atomic_add v3, v1, v3, s[6:7] offset:32 sc0

; #define LAS __attribute__((address_space(3)))
; __device__ __forceinline__ unsigned xb_ld(unsigned* p)              { return __hip_atomic_load(p, __ATOMIC_RELAXED, __HIP_MEMORY_SCOPE_AGENT); }
; __device__ __forceinline__ unsigned xb_add(unsigned* p, unsigned v) { return __hip_atomic_fetch_add(p, v, __ATOMIC_RELAXED, __HIP_MEMORY_SCOPE_AGENT); }
; __device__ __forceinline__ unsigned xb_xcc_id() { return (unsigned)__builtin_amdgcn_s_getreg((3 << 11) | 20) & 0xFu; }
; #define XB_SPIN(cond, bar) do { unsigned _sp = 0; while (cond) { __builtin_amdgcn_s_sleep(1); \
;     if ((++_sp & 255u) == 0u) { if (xb_ld(&(bar)[XB_TMO])) break; if (_sp > XB_SPIN_CAP) { atomicAdd(&(bar)[XB_TMO], 1u); break; } } } } while (0)
; __device__ __forceinline__ void xcd_barrier(unsigned* bar, volatile LAS unsigned* st, bool is0) {
;     asm volatile("s_waitcnt vmcnt(0)" ::: "memory");
;     __syncthreads();
;     if (is0) {
;         __builtin_amdgcn_s_waitcnt(0);
;         const unsigned x = xb_xcc_id();
;         unsigned nloc = st[0], nx = st[1];
;         if (nloc == 0u) { xcd_barrier_complete(bar, x, nloc, nx); st[0] = nloc; st[1] = nx; }
;         const unsigned old = xb_add(&bar[XB_XSUB(x)], 1u);
;         const unsigned gen = old / nloc;
;         if (old + 1u == (gen + 1u) * nloc) {
;             __builtin_amdgcn_fence(__ATOMIC_RELEASE, "agent");
;             asm volatile("s_waitcnt vmcnt(0)" ::: "memory");
;             const unsigned og = xb_add(&bar[XB_TOP], 1u);
;             const unsigned tg = og / nx;
;             if (og + 1u == (tg + 1u) * nx) xb_add(&bar[XB_TOPGEN], 1u);
;             else XB_SPIN(xb_ld(&bar[XB_TOPGEN]) == tg, bar);
.LBB0_1242:
	v_readlane_b32 s0, v252, 13
	v_readlane_b32 s1, v252, 14
	s_mov_b64 s[2:3], -1
	s_and_b64 vcc, exec, s[0:1]
	s_cbranch_vccz .LBB0_1296
	s_cmp_eq_u32 s100, 0
	s_cbranch_scc1 .Lgb_orig_5
	s_waitcnt vmcnt(0) lgkmcnt(0)
	s_barrier
	s_cmp_lg_u32 s94, 0
	s_cbranch_scc1 .Lgb_join_5
	s_mov_b64 exec, 1
	v_readlane_b32 s8, v251, 45
	v_readlane_b32 s9, v251, 46
	v_readlane_b32 s6, v251, 50
	v_mov_b32_e32 v4, 1
	v_mov_b32_e32 v8, 0
	s_and_b32 s6, s6, 7
	s_lshl_b32 s6, s6, 8
	s_add_u32 s6, s6, 0x5000
	s_add_u32 s8, s8, s6
	s_addc_u32 s9, s9, 0
	s_add_u32 s12, s101, 1
	s_lshl_b32 s13, s12, 5
	s_cmp_eq_u32 s100, 2
	s_cbranch_scc1 .Lgb_arr_5
	buffer_wbl2 sc1
	s_waitcnt vmcnt(0)

; __device__ __forceinline__ unsigned xb_ld(unsigned* p)              { return __hip_atomic_load(p, __ATOMIC_RELAXED, __HIP_MEMORY_SCOPE_AGENT); }
; __device__ __forceinline__ unsigned xb_add(unsigned* p, unsigned v) { return __hip_atomic_fetch_add(p, v, __ATOMIC_RELAXED, __HIP_MEMORY_SCOPE_AGENT); }
; #define XB_SPIN(cond, bar) do { unsigned _sp = 0; while (cond) { __builtin_amdgcn_s_sleep(1); \
;     if ((++_sp & 255u) == 0u) { if (xb_ld(&(bar)[XB_TMO])) break; if (_sp > XB_SPIN_CAP) { atomicAdd(&(bar)[XB_TMO], 1u); break; } } } } while (0)
; __device__ __forceinline__ void xcd_barrier(unsigned* bar, volatile LAS unsigned* st, bool is0) {
;     ...
;             __builtin_amdgcn_fence(__ATOMIC_ACQUIRE, "agent");
;             xb_add(&bar[XB_XGEN(x)], 1u);
;             asm volatile("s_waitcnt vmcnt(0)" ::: "memory");
;         } else {
;             XB_SPIN(xb_ld(&bar[XB_XGEN(x)]) == gen, bar);
;             __builtin_amdgcn_fence(__ATOMIC_ACQUIRE, "agent");
.Lgb_acq_5:
	buffer_inv sc1
	s_waitcnt vmcnt(0)
	s_mov_b64 exec, -1

.Lgb_after_5:
.LBB0_1296:
	s_and_b64 vcc, exec, s[2:3]
	s_cbranch_vccnz .LBB0_1297
	s_getpc_b64 s[98:99]

; #define LAS __attribute__((address_space(3)))
; __global__ void __launch_bounds__(512) fwd_megakernel(Args A) {
;     extern __shared__ __attribute__((aligned(16))) unsigned char lds_raw[];
;     LAS unsigned char* lds = (LAS unsigned char*)lds_raw;
;     const int G = gridDim.x, bx = blockIdx.x;
;     const int wv = __builtin_amdgcn_readfirstlane((int)threadIdx.x >> 6);
;     unsigned char* ws = A.ws;
;     const int lo = A.ph_lo, hi = A.ph_hi;
	.amdhsa_kernel _Z14fwd_megakernel4Args
		.amdhsa_group_segment_fixed_size 0
		.amdhsa_private_segment_fixed_size 0
		.amdhsa_kernarg_size 416
		.amdhsa_user_sgpr_count 2
		.amdhsa_user_sgpr_dispatch_ptr 0
		.amdhsa_user_sgpr_queue_ptr 0
		.amdhsa_user_sgpr_kernarg_segment_ptr 1
		.amdhsa_user_sgpr_dispatch_id 0
		.amdhsa_user_sgpr_kernarg_preload_length 0
		.amdhsa_user_sgpr_kernarg_preload_offset 0
		.amdhsa_user_sgpr_private_segment_size 0
		.amdhsa_uses_dynamic_stack 0
		.amdhsa_enable_private_segment 0
		.amdhsa_system_sgpr_workgroup_id_x 1
		.amdhsa_system_sgpr_workgroup_id_y 0
		.amdhsa_system_sgpr_workgroup_id_z 0
		.amdhsa_system_sgpr_workgroup_info 0
		.amdhsa_system_vgpr_workitem_id 2
		.amdhsa_next_free_vgpr 256
		.amdhsa_next_free_sgpr 102
		.amdhsa_accum_offset 256
		.amdhsa_reserve_vcc 1
		.amdhsa_float_round_mode_32 0
		.amdhsa_float_round_mode_16_64 0
		.amdhsa_float_denorm_mode_32 3
		.amdhsa_float_denorm_mode_16_64 3
		.amdhsa_dx10_clamp 1
		.amdhsa_ieee_mode 1
		.amdhsa_fp16_overflow 0
		.amdhsa_tg_split 0
		.amdhsa_exception_fp_ieee_invalid_op 0
		.amdhsa_exception_fp_denorm_src 0
		.amdhsa_exception_fp_ieee_div_zero 0
		.amdhsa_exception_fp_ieee_overflow 0
		.amdhsa_exception_fp_ieee_underflow 0
		.amdhsa_exception_fp_ieee_inexact 0
		.amdhsa_exception_int_div_zero 0
	.end_amdhsa_kernel

; __global__ void __launch_bounds__(512) fwd_megakernel(Args A) {
;     extern __shared__ __attribute__((aligned(16))) unsigned char lds_raw[];
amdhsa.kernels:
  - .agpr_count:     0
    .args:
      - .offset:         0
        .size:           160
        .value_kind:     by_value
      - .offset:         160
        .size:           4
        .value_kind:     hidden_block_count_x
      - .offset:         164
        .size:           4
        .value_kind:     hidden_block_count_y
      - .offset:         168
        .size:           4
        .value_kind:     hidden_block_count_z
      - .offset:         172
        .size:           2
        .value_kind:     hidden_group_size_x
      - .offset:         174
        .size:           2
        .value_kind:     hidden_group_size_y
      - .offset:         176
        .size:           2
        .value_kind:     hidden_group_size_z
      - .offset:         178
        .size:           2
        .value_kind:     hidden_remainder_x
      - .offset:         180
        .size:           2
        .value_kind:     hidden_remainder_y
      - .offset:         182
        .size:           2
        .value_kind:     hidden_remainder_z
      - .offset:         200
        .size:           8
        .value_kind:     hidden_global_offset_x
      - .offset:         208
        .size:           8
        .value_kind:     hidden_global_offset_y
      - .offset:         216
        .size:           8
        .value_kind:     hidden_global_offset_z
      - .offset:         224
        .size:           2
        .value_kind:     hidden_grid_dims
      - .offset:         248
        .size:           8
        .value_kind:     hidden_multigrid_sync_arg
      - .offset:         280
        .size:           4
        .value_kind:     hidden_dynamic_lds_size
    .group_segment_fixed_size: 0
    .kernarg_segment_align: 8
    .kernarg_segment_size: 416
    .language:       OpenCL C
    .language_version:
      - 2
      - 0
    .max_flat_workgroup_size: 512
    .name:           _Z14fwd_megakernel4Args
    .private_segment_fixed_size: 0
    .sgpr_count:     108
    .sgpr_spill_count: 285
    .symbol:         _Z14fwd_megakernel4Args.kd
    .uniform_work_group_size: 1
    .uses_dynamic_stack: false
    .vgpr_count:     256
    .vgpr_spill_count: 0
    .wavefront_size: 64
